# v34rot
# baseline (speedup 1.0000x reference)
; template <class Epi, class Sched>
; __device__ __forceinline__ void gemm_simple(PG8_LAS unsigned char* lds, const Gemm g, const Sched& S, const Epi& E, int wave_s) {
;     ...
;         for (; t < nt; t += 2) {
;             const bool last = (t == nt - 2);
;             PG8_TILE(0, cA + (size_t)(t + 1) * kstep, cB + (size_t)(t + 1) * kstep, true);
;             const char* a2 = last ? nA : cA + (size_t)(t + 2) * kstep; const char* b2 = last ? nB : cB + (size_t)(t + 2) * kstep;
.LBB0_62:
	s_add_i32 s53, s10, -2
	s_lshl_b32 s54, s10, 7
	s_add_u32 s55, s16, 0x100
	s_addc_u32 s56, s17, 0
	s_add_u32 s57, s18, 0x100
	s_addc_u32 s58, s19, 0
	s_add_u32 s59, s18, 0x160080
	s_addc_u32 s60, s19, 0
	s_add_u32 s61, s16, 0x160080
	s_addc_u32 s62, s17, 0
	s_add_u32 s18, s18, 0x80
	s_addc_u32 s19, s19, 0
	s_add_u32 s63, s16, 0x80
	s_addc_u32 s64, s17, 0
	s_mov_b64 s[10:11], 0x2b00
	s_branch .Lrt_top_63
.Lrt_63:
	v_mfma_f32_16x16x32_bf16 v[56:59], v[206:209], v[174:177], v[56:59]
	v_mfma_f32_16x16x32_bf16 v[52:55], v[214:217], v[174:177], v[52:55]
	v_mfma_f32_16x16x32_bf16 v[40:43], v[206:209], v[182:185], v[40:43]
	v_mfma_f32_16x16x32_bf16 v[36:39], v[214:217], v[182:185], v[36:39]
	v_mfma_f32_16x16x32_bf16 v[24:27], v[206:209], v[190:193], v[24:27]
	v_mfma_f32_16x16x32_bf16 v[20:23], v[214:217], v[190:193], v[20:23]
	v_mfma_f32_16x16x32_bf16 v[8:11], v[206:209], v[198:201], v[8:11]
	v_mfma_f32_16x16x32_bf16 v[4:7], v[214:217], v[198:201], v[4:7]
.Lrt_top_63:
.LBB0_63:
	s_waitcnt vmcnt(2) lgkmcnt(0)
	s_barrier
	ds_read_b128 v[142:145], v132
	ds_read_b128 v[170:173], v154
	ds_read_b128 v[156:159], v132 offset:2048
	ds_read_b128 v[178:181], v154 offset:2048
	ds_read_b128 v[186:189], v154 offset:4096
	s_add_u32 s16, s63, s54
	s_addc_u32 s17, s64, 0
	s_mov_b32 m0, s39
	s_nop 0
	global_load_lds_dwordx4 v139, s[16:17]
	s_mov_b32 m0, s43
	s_nop 0
	global_load_lds_dwordx4 v152, s[16:17]
	s_waitcnt lgkmcnt(3)
	v_mfma_f32_16x16x32_bf16 v[128:131], v[142:145], v[170:173], v[128:131]
	s_waitcnt lgkmcnt(2)
	v_mfma_f32_16x16x32_bf16 v[124:127], v[156:159], v[170:173], v[124:127]
	ds_read_b128 v[194:197], v154 offset:6144
	s_waitcnt lgkmcnt(2)
	v_mfma_f32_16x16x32_bf16 v[112:115], v[142:145], v[178:181], v[112:115]
	v_mfma_f32_16x16x32_bf16 v[108:111], v[156:159], v[178:181], v[108:111]
	ds_read_b128 v[146:149], v132 offset:1024
	ds_read_b128 v[174:177], v154 offset:1024
	s_waitcnt lgkmcnt(3)
	v_mfma_f32_16x16x32_bf16 v[96:99], v[142:145], v[186:189], v[96:99]
	ds_read_b128 v[160:163], v132 offset:3072
	v_mfma_f32_16x16x32_bf16 v[92:95], v[156:159], v[186:189], v[92:95]
	ds_read_b128 v[182:185], v154 offset:3072
	s_waitcnt lgkmcnt(4)
	v_mfma_f32_16x16x32_bf16 v[80:83], v[142:145], v[194:197], v[80:83]
	v_mfma_f32_16x16x32_bf16 v[76:79], v[156:159], v[194:197], v[76:79]
	ds_read_b128 v[190:193], v154 offset:5120
	s_waitcnt lgkmcnt(3)
	v_mfma_f32_16x16x32_bf16 v[128:131], v[146:149], v[174:177], v[128:131]
	s_waitcnt lgkmcnt(2)
	v_mfma_f32_16x16x32_bf16 v[124:127], v[160:163], v[174:177], v[124:127]
	ds_read_b128 v[198:201], v154 offset:7168
	s_waitcnt lgkmcnt(2)
	v_mfma_f32_16x16x32_bf16 v[112:115], v[146:149], v[182:185], v[112:115]
	v_mfma_f32_16x16x32_bf16 v[108:111], v[160:163], v[182:185], v[108:111]
	ds_read_b128 v[202:205], v133
	s_waitcnt lgkmcnt(2)
	v_mfma_f32_16x16x32_bf16 v[96:99], v[146:149], v[190:193], v[96:99]
	ds_read_b128 v[210:213], v133 offset:2048
	v_mfma_f32_16x16x32_bf16 v[92:95], v[160:163], v[190:193], v[92:95]
	s_waitcnt lgkmcnt(2)
	v_mfma_f32_16x16x32_bf16 v[80:83], v[146:149], v[198:201], v[80:83]
	v_mfma_f32_16x16x32_bf16 v[76:79], v[160:163], v[198:201], v[76:79]
	s_add_u32 s16, s18, s54
	s_addc_u32 s17, s19, 0
	s_mov_b32 m0, s40
	s_nop 0
	global_load_lds_dwordx4 v138, s[16:17]
	s_mov_b32 m0, s44
	s_nop 0
	global_load_lds_dwordx4 v140, s[16:17]
	s_waitcnt lgkmcnt(1)
	v_mfma_f32_16x16x32_bf16 v[120:123], v[202:205], v[170:173], v[120:123]
	s_waitcnt lgkmcnt(0)
	v_mfma_f32_16x16x32_bf16 v[116:119], v[210:213], v[170:173], v[116:119]
	v_mfma_f32_16x16x32_bf16 v[104:107], v[202:205], v[178:181], v[104:107]
	v_mfma_f32_16x16x32_bf16 v[100:103], v[210:213], v[178:181], v[100:103]
	ds_read_b128 v[206:209], v133 offset:1024
	v_mfma_f32_16x16x32_bf16 v[88:91], v[202:205], v[186:189], v[88:91]
	ds_read_b128 v[214:217], v133 offset:3072
	v_mfma_f32_16x16x32_bf16 v[84:87], v[210:213], v[186:189], v[84:87]
	v_mfma_f32_16x16x32_bf16 v[72:75], v[202:205], v[194:197], v[72:75]
	v_mfma_f32_16x16x32_bf16 v[68:71], v[210:213], v[194:197], v[68:71]
	s_waitcnt lgkmcnt(1)
	v_mfma_f32_16x16x32_bf16 v[120:123], v[206:209], v[174:177], v[120:123]
	s_waitcnt lgkmcnt(0)
	v_mfma_f32_16x16x32_bf16 v[116:119], v[214:217], v[174:177], v[116:119]
	v_mfma_f32_16x16x32_bf16 v[104:107], v[206:209], v[182:185], v[104:107]
	v_mfma_f32_16x16x32_bf16 v[100:103], v[214:217], v[182:185], v[100:103]
	v_mfma_f32_16x16x32_bf16 v[88:91], v[206:209], v[190:193], v[88:91]
	v_mfma_f32_16x16x32_bf16 v[84:87], v[214:217], v[190:193], v[84:87]
	v_mfma_f32_16x16x32_bf16 v[72:75], v[206:209], v[198:201], v[72:75]
	v_mfma_f32_16x16x32_bf16 v[68:71], v[214:217], v[198:201], v[68:71]
	s_waitcnt vmcnt(4) lgkmcnt(0)
	s_barrier
; template <class Epi, class Sched>
; __device__ __forceinline__ void gemm_simple(PG8_LAS unsigned char* lds, const Gemm g, const Sched& S, const Epi& E, int wave_s) {
;     ...
;             const char* a2 = last ? nA : cA + (size_t)(t + 2) * kstep; const char* b2 = last ? nB : cB + (size_t)(t + 2) * kstep;
;             PG8_TILE(1, a2, b2, (!last || has_next));
	ds_read_b128 v[170:173], v154 offset:16384
	ds_read_b128 v[178:181], v154 offset:18432
	ds_read_b128 v[186:189], v154 offset:20480
	s_add_u32 s16, s61, s54
	s_addc_u32 s17, s62, 0
	s_mov_b32 m0, s41
	s_nop 0
	global_load_lds_dwordx4 v139, s[16:17]
	s_mov_b32 m0, s45
	s_nop 0
	global_load_lds_dwordx4 v152, s[16:17]
	s_waitcnt lgkmcnt(2)
	v_mfma_f32_16x16x32_bf16 v[64:67], v[142:145], v[170:173], v[64:67]
	v_mfma_f32_16x16x32_bf16 v[60:63], v[156:159], v[170:173], v[60:63]
	ds_read_b128 v[194:197], v154 offset:22528
	s_waitcnt lgkmcnt(2)
	v_mfma_f32_16x16x32_bf16 v[48:51], v[142:145], v[178:181], v[48:51]
	v_mfma_f32_16x16x32_bf16 v[44:47], v[156:159], v[178:181], v[44:47]
	ds_read_b128 v[174:177], v154 offset:17408
	s_waitcnt lgkmcnt(2)
	v_mfma_f32_16x16x32_bf16 v[32:35], v[142:145], v[186:189], v[32:35]
	v_mfma_f32_16x16x32_bf16 v[28:31], v[156:159], v[186:189], v[28:31]
	ds_read_b128 v[182:185], v154 offset:19456
	s_waitcnt lgkmcnt(2)
	v_mfma_f32_16x16x32_bf16 v[16:19], v[142:145], v[194:197], v[16:19]
	v_mfma_f32_16x16x32_bf16 v[12:15], v[156:159], v[194:197], v[12:15]
	ds_read_b128 v[190:193], v154 offset:21504
	s_waitcnt lgkmcnt(2)
	v_mfma_f32_16x16x32_bf16 v[64:67], v[146:149], v[174:177], v[64:67]
	v_mfma_f32_16x16x32_bf16 v[60:63], v[160:163], v[174:177], v[60:63]
	ds_read_b128 v[198:201], v154 offset:23552
	s_waitcnt lgkmcnt(2)
	v_mfma_f32_16x16x32_bf16 v[48:51], v[146:149], v[182:185], v[48:51]
	v_mfma_f32_16x16x32_bf16 v[44:47], v[160:163], v[182:185], v[44:47]
	s_waitcnt lgkmcnt(1)
	v_mfma_f32_16x16x32_bf16 v[32:35], v[146:149], v[190:193], v[32:35]
	v_mfma_f32_16x16x32_bf16 v[28:31], v[160:163], v[190:193], v[28:31]
	s_waitcnt lgkmcnt(0)
	v_mfma_f32_16x16x32_bf16 v[16:19], v[146:149], v[198:201], v[16:19]
	v_mfma_f32_16x16x32_bf16 v[12:15], v[160:163], v[198:201], v[12:15]
	s_add_u32 s16, s59, s54
	s_addc_u32 s17, s60, 0
	s_mov_b32 m0, s42
	s_nop 0
	global_load_lds_dwordx4 v138, s[16:17]
	s_mov_b32 m0, s46
	s_nop 0
	global_load_lds_dwordx4 v140, s[16:17]
	v_mfma_f32_16x16x32_bf16 v[56:59], v[202:205], v[170:173], v[56:59]
	s_add_u32 s16, s57, s54
	s_addc_u32 s17, s58, 0
	s_add_u32 s65, s55, s54
	v_mfma_f32_16x16x32_bf16 v[52:55], v[210:213], v[170:173], v[52:55]
	s_addc_u32 s66, s56, 0
	v_mfma_f32_16x16x32_bf16 v[40:43], v[202:205], v[178:181], v[40:43]
	v_mfma_f32_16x16x32_bf16 v[36:39], v[210:213], v[178:181], v[36:39]
	v_mfma_f32_16x16x32_bf16 v[24:27], v[202:205], v[186:189], v[24:27]
	v_mfma_f32_16x16x32_bf16 v[20:23], v[210:213], v[186:189], v[20:23]
	v_mfma_f32_16x16x32_bf16 v[8:11], v[202:205], v[194:197], v[8:11]
	v_mfma_f32_16x16x32_bf16 v[4:7], v[210:213], v[194:197], v[4:7]
	v_mfma_f32_16x16x32_bf16 v[56:59], v[206:209], v[174:177], v[56:59]
	v_mfma_f32_16x16x32_bf16 v[52:55], v[214:217], v[174:177], v[52:55]
	v_mfma_f32_16x16x32_bf16 v[40:43], v[206:209], v[182:185], v[40:43]
	v_mfma_f32_16x16x32_bf16 v[36:39], v[214:217], v[182:185], v[36:39]
	v_mfma_f32_16x16x32_bf16 v[24:27], v[206:209], v[190:193], v[24:27]
	v_mfma_f32_16x16x32_bf16 v[20:23], v[214:217], v[190:193], v[20:23]
	v_mfma_f32_16x16x32_bf16 v[8:11], v[206:209], v[198:201], v[8:11]
	v_mfma_f32_16x16x32_bf16 v[4:7], v[214:217], v[198:201], v[4:7]
	s_waitcnt vmcnt(2) lgkmcnt(0)
	s_barrier
	ds_read_b128 v[142:145], v134
	ds_read_b128 v[170:173], v154 offset:32768
	ds_read_b128 v[156:159], v134 offset:2048
	ds_read_b128 v[178:181], v154 offset:34816
	ds_read_b128 v[186:189], v154 offset:36864
	s_cmp_eq_u32 s54, s10
	s_cselect_b32 s17, s5, s17
	s_cselect_b32 s16, s4, s16
	s_cselect_b32 s67, s9, s66
	s_cselect_b32 s66, s8, s65
	s_mov_b32 m0, s26
	s_nop 0
	global_load_lds_dwordx4 v139, s[66:67]
	s_mov_b32 m0, s27
	s_nop 0
	global_load_lds_dwordx4 v152, s[66:67]
	s_waitcnt lgkmcnt(3)
	v_mfma_f32_16x16x32_bf16 v[128:131], v[142:145], v[170:173], v[128:131]
	s_waitcnt lgkmcnt(2)
	v_mfma_f32_16x16x32_bf16 v[124:127], v[156:159], v[170:173], v[124:127]
	ds_read_b128 v[194:197], v154 offset:38912
	s_waitcnt lgkmcnt(2)
	v_mfma_f32_16x16x32_bf16 v[112:115], v[142:145], v[178:181], v[112:115]
	v_mfma_f32_16x16x32_bf16 v[108:111], v[156:159], v[178:181], v[108:111]
	ds_read_b128 v[146:149], v134 offset:1024
	ds_read_b128 v[174:177], v154 offset:33792
	s_waitcnt lgkmcnt(3)
	v_mfma_f32_16x16x32_bf16 v[96:99], v[142:145], v[186:189], v[96:99]
	ds_read_b128 v[160:163], v134 offset:3072
	v_mfma_f32_16x16x32_bf16 v[92:95], v[156:159], v[186:189], v[92:95]
	ds_read_b128 v[182:185], v154 offset:35840
	s_waitcnt lgkmcnt(4)
	v_mfma_f32_16x16x32_bf16 v[80:83], v[142:145], v[194:197], v[80:83]
	v_mfma_f32_16x16x32_bf16 v[76:79], v[156:159], v[194:197], v[76:79]
	ds_read_b128 v[190:193], v154 offset:37888
	s_waitcnt lgkmcnt(3)
	v_mfma_f32_16x16x32_bf16 v[128:131], v[146:149], v[174:177], v[128:131]
	s_waitcnt lgkmcnt(2)
	v_mfma_f32_16x16x32_bf16 v[124:127], v[160:163], v[174:177], v[124:127]
	ds_read_b128 v[198:201], v154 offset:39936
	s_waitcnt lgkmcnt(2)
	v_mfma_f32_16x16x32_bf16 v[112:115], v[146:149], v[182:185], v[112:115]
	v_mfma_f32_16x16x32_bf16 v[108:111], v[160:163], v[182:185], v[108:111]
	ds_read_b128 v[202:205], v135
	s_waitcnt lgkmcnt(2)
	v_mfma_f32_16x16x32_bf16 v[96:99], v[146:149], v[190:193], v[96:99]
	ds_read_b128 v[210:213], v135 offset:2048
	v_mfma_f32_16x16x32_bf16 v[92:95], v[160:163], v[190:193], v[92:95]
	s_waitcnt lgkmcnt(2)
	v_mfma_f32_16x16x32_bf16 v[80:83], v[146:149], v[198:201], v[80:83]
	v_mfma_f32_16x16x32_bf16 v[76:79], v[160:163], v[198:201], v[76:79]
	s_mov_b32 m0, s25
	s_nop 0
	global_load_lds_dwordx4 v138, s[16:17]
	s_mov_b32 m0, s28
	s_nop 0
	global_load_lds_dwordx4 v140, s[16:17]
	s_waitcnt lgkmcnt(1)
	v_mfma_f32_16x16x32_bf16 v[120:123], v[202:205], v[170:173], v[120:123]
	s_waitcnt lgkmcnt(0)
	v_mfma_f32_16x16x32_bf16 v[116:119], v[210:213], v[170:173], v[116:119]
	v_mfma_f32_16x16x32_bf16 v[104:107], v[202:205], v[178:181], v[104:107]
	v_mfma_f32_16x16x32_bf16 v[100:103], v[210:213], v[178:181], v[100:103]
	ds_read_b128 v[206:209], v135 offset:1024
	v_mfma_f32_16x16x32_bf16 v[88:91], v[202:205], v[186:189], v[88:91]
	ds_read_b128 v[214:217], v135 offset:3072
	v_mfma_f32_16x16x32_bf16 v[84:87], v[210:213], v[186:189], v[84:87]
	v_mfma_f32_16x16x32_bf16 v[72:75], v[202:205], v[194:197], v[72:75]
	v_mfma_f32_16x16x32_bf16 v[68:71], v[210:213], v[194:197], v[68:71]
	s_waitcnt lgkmcnt(1)
	v_mfma_f32_16x16x32_bf16 v[120:123], v[206:209], v[174:177], v[120:123]
	s_waitcnt lgkmcnt(0)
	v_mfma_f32_16x16x32_bf16 v[116:119], v[214:217], v[174:177], v[116:119]
	v_mfma_f32_16x16x32_bf16 v[104:107], v[206:209], v[182:185], v[104:107]
	v_mfma_f32_16x16x32_bf16 v[100:103], v[214:217], v[182:185], v[100:103]
	v_mfma_f32_16x16x32_bf16 v[88:91], v[206:209], v[190:193], v[88:91]
	v_mfma_f32_16x16x32_bf16 v[84:87], v[214:217], v[190:193], v[84:87]
	v_mfma_f32_16x16x32_bf16 v[72:75], v[206:209], v[198:201], v[72:75]
	v_mfma_f32_16x16x32_bf16 v[68:71], v[214:217], v[198:201], v[68:71]
	s_waitcnt vmcnt(4) lgkmcnt(0)
	s_barrier
	ds_read_b128 v[170:173], v154 offset:49152
	ds_read_b128 v[178:181], v154 offset:51200
	ds_read_b128 v[186:189], v154 offset:53248
	s_add_u32 s66, s66, 0x160000
	s_addc_u32 s67, s67, 0
	s_mov_b32 m0, s29
	s_nop 0
	global_load_lds_dwordx4 v139, s[66:67]
	s_mov_b32 m0, s36
	s_nop 0
	global_load_lds_dwordx4 v152, s[66:67]
	s_waitcnt lgkmcnt(2)
	v_mfma_f32_16x16x32_bf16 v[64:67], v[142:145], v[170:173], v[64:67]
	v_mfma_f32_16x16x32_bf16 v[60:63], v[156:159], v[170:173], v[60:63]
	ds_read_b128 v[194:197], v154 offset:55296
	s_waitcnt lgkmcnt(2)
	v_mfma_f32_16x16x32_bf16 v[48:51], v[142:145], v[178:181], v[48:51]
	v_mfma_f32_16x16x32_bf16 v[44:47], v[156:159], v[178:181], v[44:47]
	ds_read_b128 v[174:177], v154 offset:50176
	s_waitcnt lgkmcnt(2)
	v_mfma_f32_16x16x32_bf16 v[32:35], v[142:145], v[186:189], v[32:35]
	v_mfma_f32_16x16x32_bf16 v[28:31], v[156:159], v[186:189], v[28:31]
	ds_read_b128 v[182:185], v154 offset:52224
	s_waitcnt lgkmcnt(2)
	v_mfma_f32_16x16x32_bf16 v[16:19], v[142:145], v[194:197], v[16:19]
	v_mfma_f32_16x16x32_bf16 v[12:15], v[156:159], v[194:197], v[12:15]
	ds_read_b128 v[190:193], v154 offset:54272
	s_waitcnt lgkmcnt(2)
	v_mfma_f32_16x16x32_bf16 v[64:67], v[146:149], v[174:177], v[64:67]
	v_mfma_f32_16x16x32_bf16 v[60:63], v[160:163], v[174:177], v[60:63]
	ds_read_b128 v[198:201], v154 offset:56320
	s_waitcnt lgkmcnt(2)
	v_mfma_f32_16x16x32_bf16 v[48:51], v[146:149], v[182:185], v[48:51]
	v_mfma_f32_16x16x32_bf16 v[44:47], v[160:163], v[182:185], v[44:47]
	s_waitcnt lgkmcnt(1)
	v_mfma_f32_16x16x32_bf16 v[32:35], v[146:149], v[190:193], v[32:35]
	v_mfma_f32_16x16x32_bf16 v[28:31], v[160:163], v[190:193], v[28:31]
	s_waitcnt lgkmcnt(0)
	v_mfma_f32_16x16x32_bf16 v[16:19], v[146:149], v[198:201], v[16:19]
	v_mfma_f32_16x16x32_bf16 v[12:15], v[160:163], v[198:201], v[12:15]
	s_add_u32 s16, s16, 0x160000
	s_addc_u32 s17, s17, 0
	s_mov_b32 m0, s37
	s_nop 0
	global_load_lds_dwordx4 v138, s[16:17]
	s_mov_b32 m0, s38
	s_nop 0
	global_load_lds_dwordx4 v140, s[16:17]
	s_add_i32 s53, s53, 2
	s_add_u32 s10, s10, 0xffffff00
	s_addc_u32 s11, s11, -1
	s_add_u32 s55, s55, 0x100
	s_addc_u32 s56, s56, 0
	s_add_u32 s57, s57, 0x100
	s_addc_u32 s58, s58, 0
	s_add_u32 s59, s59, 0x100
	v_mfma_f32_16x16x32_bf16 v[56:59], v[202:205], v[170:173], v[56:59]
	s_addc_u32 s60, s60, 0
	s_add_u32 s61, s61, 0x100
	s_addc_u32 s62, s62, 0
	v_mfma_f32_16x16x32_bf16 v[52:55], v[210:213], v[170:173], v[52:55]
	s_add_u32 s18, s18, 0x100
	s_addc_u32 s19, s19, 0
	s_add_u32 s63, s63, 0x100
	v_mfma_f32_16x16x32_bf16 v[40:43], v[202:205], v[178:181], v[40:43]
	s_addc_u32 s64, s64, 0
	s_cmpk_lt_u32 s53, 0x56
	v_mfma_f32_16x16x32_bf16 v[36:39], v[210:213], v[178:181], v[36:39]
	v_mfma_f32_16x16x32_bf16 v[24:27], v[202:205], v[186:189], v[24:27]
	v_mfma_f32_16x16x32_bf16 v[20:23], v[210:213], v[186:189], v[20:23]
	v_mfma_f32_16x16x32_bf16 v[8:11], v[202:205], v[194:197], v[8:11]
	v_mfma_f32_16x16x32_bf16 v[4:7], v[210:213], v[194:197], v[4:7]
	s_cbranch_scc1 .Lrt_63
; __device__ __forceinline__ unsigned cvt_pk_bf16(float lo, float hi) { unsigned r; asm volatile("v_cvt_pk_bf16_f32 %0, %1, %2" : "=v"(r) : "v"(lo), "v"(hi)); return r; }
; #define LAS __attribute__((address_space(3)))
; __device__ __forceinline__ float bflo(unsigned w) { return __uint_as_float(w << 16); }
; __device__ __forceinline__ float bfhi(unsigned w) { return __uint_as_float(w & 0xffff0000u); }
;     __device__ __forceinline__ void operator()(const f32x4 (&acc)[2][2][4][2], const Unit& u, int wr, int wc, int fr, int fq, const LAS float* rt) const {
;         const int row0 = u.pm * 256 + wr * 64 + fr, col0 = u.pn * 256 + wc * 32 + 8 * fq, lane = fq * 16 + fr;
; #pragma unroll
;         for (int ai = 0; ai < 2; ++ai)
; #pragma unroll
;             for (int m = 0; m < 4; ++m) { const size_t row = (size_t)(row0 + ai * 128 + m * 16); const float rs = (MODE == 1) ? rt[ai * 128 + wr * 64 + m * 16 + fr] : 1.0f; float ss = 0.f;
; #pragma unroll
;                 for (int bj = 0; bj < 2; ++bj) { const size_t o = row * DM + col0 + bj * 128; const u32x4 xv = *(const u32x4*)(xin + o);
;                     f32x4 v0 = acc[ai][bj][m][0], v1 = acc[ai][bj][m][1];
;                     if (MODE == 1) { const u32x4 p = *(const u32x4*)(pe + o);
;                         v0[0] = sigmoidf_(v0[0] * rs) * bflo(p.x); v0[1] = sigmoidf_(v0[1] * rs) * bfhi(p.x); v0[2] = sigmoidf_(v0[2] * rs) * bflo(p.y); v0[3] = sigmoidf_(v0[3] * rs) * bfhi(p.y);
;                         v1[0] = sigmoidf_(v1[0] * rs) * bflo(p.z); v1[1] = sigmoidf_(v1[1] * rs) * bfhi(p.z); v1[2] = sigmoidf_(v1[2] * rs) * bflo(p.w); v1[3] = sigmoidf_(v1[3] * rs) * bfhi(p.w); }
;                     v0[0] += bflo(xv.x); v0[1] += bfhi(xv.x); v0[2] += bflo(xv.y); v0[3] += bfhi(xv.y); v1[0] += bflo(xv.z); v1[1] += bfhi(xv.z); v1[2] += bflo(xv.w); v1[3] += bfhi(xv.w);
;                     ss += (v0[0] * v0[0] + v0[1] * v0[1]) + (v0[2] * v0[2] + v0[3] * v0[3]) + (v1[0] * v1[0] + v1[1] * v1[1]) + (v1[2] * v1[2] + v1[3] * v1[3]);
;                     u32x4 w; w.x = cvt_pk_bf16(v0[0], v0[1]); w.y = cvt_pk_bf16(v0[2], v0[3]); w.z = cvt_pk_bf16(v1[0], v1[1]); w.w = cvt_pk_bf16(v1[2], v1[3]);
;                     __builtin_nontemporal_store(w, (u32x4*)(xout + o)); }
;                 ss += shx(ss, 16, lane); ss += shx(ss, 32, lane);
;                 if (fq == 0) ssq_out[row * 32 + u.pn * 4 + wc] = ss; }
	v_mfma_f32_16x16x32_bf16 v[56:59], v[206:209], v[174:177], v[56:59]
	v_mfma_f32_16x16x32_bf16 v[52:55], v[214:217], v[174:177], v[52:55]
	v_mfma_f32_16x16x32_bf16 v[40:43], v[206:209], v[182:185], v[40:43]
	v_mfma_f32_16x16x32_bf16 v[36:39], v[214:217], v[182:185], v[36:39]
	v_mfma_f32_16x16x32_bf16 v[24:27], v[206:209], v[190:193], v[24:27]
	v_mfma_f32_16x16x32_bf16 v[20:23], v[214:217], v[190:193], v[20:23]
	v_mfma_f32_16x16x32_bf16 v[8:11], v[206:209], v[198:201], v[8:11]
	v_mfma_f32_16x16x32_bf16 v[4:7], v[214:217], v[198:201], v[4:7]
	v_mov_b32_e32 v132, v141
	s_lshl_b32 s10, s52, 8
	v_mbcnt_lo_u32_b32 v132, -1, v132
	v_mbcnt_hi_u32_b32 v135, -1, v132
	v_and_b32_e32 v136, 15, v135
	s_add_i32 s10, s10, s23
	v_or_b32_e32 v134, s10, v136
	s_lshl_b32 s10, s35, 8
	v_ashrrev_i32_e32 v137, 4, v135
	s_or_b32 s10, s10, s24
	v_lshl_add_u32 v132, v137, 3, s10
	v_lshlrev_b32_e32 v137, 6, v137
	v_lshlrev_b32_e32 v136, 2, v136
	s_movk_i32 s10, 0x80
	v_cmp_gt_u32_e32 vcc, 16, v135
	v_ashrrev_i32_e32 v135, 31, v134
	v_bitop3_b32 v156, v137, 64, v136 bitop3:0x36
	v_bitop3_b32 v155, v137, s10, v136 bitop3:0x36
	v_lshlrev_b64 v[136:137], 12, v[134:135]
	v_ashrrev_i32_e32 v133, 31, v132
	v_lshl_add_u64 v[136:137], s[94:95], 0, v[136:137]
	v_lshl_add_u64 v[136:137], v[132:133], 1, v[136:137]
	v_lshlrev_b32_e32 v236, 12, v134
	v_lshl_add_u32 v236, v132, 1, v236
	global_load_dwordx4 v[172:175], v236, s[94:95]
	global_load_dwordx4 v[176:179], v236, s[94:95] offset:256
	v_add_u32_e32 v237, 0x10000, v236
	global_load_dwordx4 v[180:183], v237, s[94:95]
	global_load_dwordx4 v[184:187], v237, s[94:95] offset:256
	v_add_u32_e32 v237, 0x20000, v236
	global_load_dwordx4 v[188:191], v237, s[94:95]
	global_load_dwordx4 v[192:195], v237, s[94:95] offset:256
	v_add_u32_e32 v237, 0x30000, v236
	global_load_dwordx4 v[196:199], v237, s[94:95]
	global_load_dwordx4 v[200:203], v237, s[94:95] offset:256
	v_add_u32_e32 v237, 0x80000, v236
	global_load_dwordx4 v[204:207], v237, s[94:95]
	global_load_dwordx4 v[208:211], v237, s[94:95] offset:256
	v_add_u32_e32 v237, 0x90000, v236
	global_load_dwordx4 v[212:215], v237, s[94:95]
	global_load_dwordx4 v[216:219], v237, s[94:95] offset:256
	v_add_u32_e32 v237, 0xa0000, v236
	global_load_dwordx4 v[220:223], v237, s[94:95]
	global_load_dwordx4 v[224:227], v237, s[94:95] offset:256
	v_add_u32_e32 v237, 0xb0000, v236
	global_load_dwordx4 v[228:231], v237, s[94:95]
	global_load_dwordx4 v[232:235], v237, s[94:95] offset:256
	s_lshl_b32 s10, s35, 2
	s_ashr_i32 s11, s10, 31
	s_waitcnt vmcnt(15)
	s_nop 1
	v_mov_b64_e32 v[142:143], v[172:173]
	v_mov_b64_e32 v[144:145], v[174:175]
	v_lshlrev_b32_e32 v146, 16, v142
	v_and_b32_e32 v142, 0xffff0000, v142
	v_add_f32_e32 v129, v129, v142
	v_lshlrev_b32_e32 v142, 16, v143
	v_add_f32_e32 v130, v130, v142
	v_and_b32_e32 v142, 0xffff0000, v143
	v_add_f32_e32 v131, v131, v142
	v_lshlrev_b32_e32 v142, 16, v144
	v_add_f32_e32 v142, v124, v142
	v_and_b32_e32 v124, 0xffff0000, v144
	v_add_f32_e32 v143, v125, v124
	v_lshlrev_b32_e32 v124, 16, v145
	v_add_f32_e32 v144, v126, v124
	v_and_b32_e32 v124, 0xffff0000, v145
	v_add_f32_e32 v128, v128, v146
	v_add_f32_e32 v127, v127, v124
	v_mul_f32_e32 v124, v129, v129
	v_mul_f32_e32 v125, v131, v131
	v_fmac_f32_e32 v124, v128, v128
	v_fmac_f32_e32 v125, v130, v130
	v_add_f32_e32 v124, v124, v125
	v_mul_f32_e32 v125, v143, v143
	v_fmac_f32_e32 v125, v142, v142
	v_add_f32_e32 v124, v125, v124
	v_mul_f32_e32 v125, v127, v127
	v_fmac_f32_e32 v125, v144, v144
	v_add_f32_e32 v145, v125, v124
	v_cvt_pk_bf16_f32 v124, v128, v129
	v_cvt_pk_bf16_f32 v125, v130, v131
	v_cvt_pk_bf16_f32 v126, v142, v143
	v_cvt_pk_bf16_f32 v127, v144, v127
	global_store_dwordx4 v[136:137], v[124:127], off nt
	s_waitcnt vmcnt(15)
	s_nop 1
	v_mov_b64_e32 v[124:125], v[176:177]
	v_mov_b64_e32 v[126:127], v[178:179]
	v_lshlrev_b32_e32 v128, 16, v124
	v_and_b32_e32 v124, 0xffff0000, v124
	v_add_f32_e32 v121, v121, v124
	v_lshlrev_b32_e32 v124, 16, v125
	v_add_f32_e32 v122, v122, v124
	v_and_b32_e32 v124, 0xffff0000, v125
	v_add_f32_e32 v123, v123, v124
	v_lshlrev_b32_e32 v124, 16, v126
	v_add_f32_e32 v124, v116, v124
	v_and_b32_e32 v116, 0xffff0000, v126
	v_add_f32_e32 v125, v117, v116
	v_lshlrev_b32_e32 v116, 16, v127
	v_add_f32_e32 v126, v118, v116
	v_and_b32_e32 v116, 0xffff0000, v127
	v_add_f32_e32 v120, v120, v128
	v_add_f32_e32 v119, v119, v116
	v_mul_f32_e32 v116, v121, v121
	v_mul_f32_e32 v117, v123, v123
	v_fmac_f32_e32 v116, v120, v120
	v_fmac_f32_e32 v117, v122, v122
	v_add_f32_e32 v116, v116, v117
	v_mul_f32_e32 v117, v125, v125
	v_fmac_f32_e32 v117, v124, v124
	v_add_f32_e32 v116, v117, v116
	v_mul_f32_e32 v117, v119, v119
	v_fmac_f32_e32 v117, v126, v126
	v_add_f32_e32 v116, v117, v116
	v_add_f32_e32 v127, v145, v116
	v_cvt_pk_bf16_f32 v116, v120, v121
	v_cvt_pk_bf16_f32 v117, v122, v123
	v_cvt_pk_bf16_f32 v118, v124, v125
	v_cvt_pk_bf16_f32 v119, v126, v119
	global_store_dwordx4 v[136:137], v[116:119], off offset:256 nt
	ds_bpermute_b32 v116, v156, v127
	s_waitcnt lgkmcnt(0)
	v_add_f32_e32 v116, v127, v116
	ds_bpermute_b32 v117, v155, v116
	s_and_saveexec_b64 s[16:17], vcc
	s_cbranch_execz .LBB0_66
	v_readlane_b32 s18, v255, 2
	v_lshlrev_b64 v[118:119], 7, v[134:135]
	v_readlane_b32 s19, v255, 3
	s_lshl_b32 s84, s22, 2
	s_mov_b32 s69, 0xf800000
	v_lshl_add_u64 v[118:119], s[18:19], 0, v[118:119]
	v_lshl_add_u64 v[118:119], s[10:11], 2, v[118:119]
	v_lshl_add_u64 v[118:119], v[118:119], 0, s[84:85]
	s_waitcnt lgkmcnt(0)
	v_add_f32_e32 v116, v116, v117
	global_store_dword v[118:119], v116, off

; template <class Epi, class Sched>
; __device__ __forceinline__ void gemm_simple(PG8_LAS unsigned char* lds, const Gemm g, const Sched& S, const Epi& E, int wave_s) {
;     ...
;         const bool has_next = S.next(ui + 1, nxt);
;         const char* nA = has_next ? (const char*)g.A + (size_t)nxt.pm * tstep : cA; const char* nB = has_next ? (const char*)g.Bt + (size_t)nxt.pn * tstep : cB;
.LBB0_94:
	s_ashr_i32 s17, s16, 31
	s_lshl_b64 s[18:19], s[16:17], 20
	s_add_u32 s18, s94, s18
	s_addc_u32 s19, s95, s19
	s_and_b64 s[20:21], exec, s[8:9]
	s_cselect_b32 s17, s25, s19
	s_cselect_b32 s60, s24, s18
	s_ashr_i32 s5, s4, 31
	s_lshl_b64 s[20:21], s[4:5], 20
	s_add_u32 s20, s36, s20
	s_addc_u32 s21, s37, s21
	s_and_b64 s[28:29], exec, s[8:9]
	s_cselect_b32 s5, s11, s21
	s_cselect_b32 s61, s10, s20
	s_add_i32 s62, s26, -2
	s_lshl_b32 s63, s26, 7
	s_mov_b64 s[26:27], 0xf00
	s_branch .Lrt_top_95
.Lrt_95:
	v_mfma_f32_16x16x32_bf16 v[64:67], v[210:213], v[178:181], v[64:67]
	v_mfma_f32_16x16x32_bf16 v[56:59], v[218:221], v[178:181], v[56:59]
	v_mfma_f32_16x16x32_bf16 v[48:51], v[210:213], v[186:189], v[48:51]
	v_mfma_f32_16x16x32_bf16 v[40:43], v[218:221], v[186:189], v[40:43]
	v_mfma_f32_16x16x32_bf16 v[32:35], v[210:213], v[194:197], v[32:35]
	v_mfma_f32_16x16x32_bf16 v[24:27], v[218:221], v[194:197], v[24:27]
	v_mfma_f32_16x16x32_bf16 v[16:19], v[210:213], v[202:205], v[16:19]
	v_mfma_f32_16x16x32_bf16 v[12:15], v[218:221], v[202:205], v[12:15]
.Lrt_top_95:
.LBB0_95:
	s_waitcnt vmcnt(2) lgkmcnt(0)
	s_barrier
	ds_read_b128 v[142:145], v132
	ds_read_b128 v[174:177], v156
	ds_read_b128 v[158:161], v132 offset:2048
	ds_read_b128 v[182:185], v156 offset:2048
	ds_read_b128 v[190:193], v156 offset:4096
	s_add_u32 s64, s10, s63
	s_addc_u32 s65, s11, 0
	s_add_u32 s28, s64, 0x80
	s_addc_u32 s29, s65, 0
	s_mov_b32 m0, s48
	s_nop 0
	global_load_lds_dwordx4 v140, s[28:29]
	s_mov_b32 m0, s52
	s_nop 0
	global_load_lds_dwordx4 v153, s[28:29]
	s_waitcnt lgkmcnt(3)
	v_mfma_f32_16x16x32_bf16 v[124:127], v[142:145], v[174:177], v[124:127]
	s_waitcnt lgkmcnt(2)
	v_mfma_f32_16x16x32_bf16 v[116:119], v[158:161], v[174:177], v[116:119]
	ds_read_b128 v[198:201], v156 offset:6144
	s_waitcnt lgkmcnt(2)
	v_mfma_f32_16x16x32_bf16 v[108:111], v[142:145], v[182:185], v[108:111]
	v_mfma_f32_16x16x32_bf16 v[100:103], v[158:161], v[182:185], v[100:103]
	ds_read_b128 v[146:149], v132 offset:1024
	ds_read_b128 v[178:181], v156 offset:1024
	s_waitcnt lgkmcnt(3)
	v_mfma_f32_16x16x32_bf16 v[92:95], v[142:145], v[190:193], v[92:95]
	ds_read_b128 v[170:173], v132 offset:3072
	v_mfma_f32_16x16x32_bf16 v[84:87], v[158:161], v[190:193], v[84:87]
	ds_read_b128 v[186:189], v156 offset:3072
	s_waitcnt lgkmcnt(4)
	v_mfma_f32_16x16x32_bf16 v[76:79], v[142:145], v[198:201], v[76:79]
	v_mfma_f32_16x16x32_bf16 v[68:71], v[158:161], v[198:201], v[68:71]
	ds_read_b128 v[194:197], v156 offset:5120
	s_waitcnt lgkmcnt(3)
	v_mfma_f32_16x16x32_bf16 v[124:127], v[146:149], v[178:181], v[124:127]
	s_waitcnt lgkmcnt(2)
	v_mfma_f32_16x16x32_bf16 v[116:119], v[170:173], v[178:181], v[116:119]
	ds_read_b128 v[202:205], v156 offset:7168
	s_waitcnt lgkmcnt(2)
	v_mfma_f32_16x16x32_bf16 v[108:111], v[146:149], v[186:189], v[108:111]
	v_mfma_f32_16x16x32_bf16 v[100:103], v[170:173], v[186:189], v[100:103]
	ds_read_b128 v[206:209], v133
	s_waitcnt lgkmcnt(2)
	v_mfma_f32_16x16x32_bf16 v[92:95], v[146:149], v[194:197], v[92:95]
	ds_read_b128 v[214:217], v133 offset:2048
	v_mfma_f32_16x16x32_bf16 v[84:87], v[170:173], v[194:197], v[84:87]
	s_waitcnt lgkmcnt(2)
	v_mfma_f32_16x16x32_bf16 v[76:79], v[146:149], v[202:205], v[76:79]
	v_mfma_f32_16x16x32_bf16 v[68:71], v[170:173], v[202:205], v[68:71]
	s_add_u32 s66, s24, s63
	s_addc_u32 s67, s25, 0
	s_add_u32 s28, s66, 0x80
	s_addc_u32 s29, s67, 0
	s_mov_b32 m0, s49
	s_nop 0
	global_load_lds_dwordx4 v139, s[28:29]
	s_mov_b32 m0, s53
	s_nop 0
	global_load_lds_dwordx4 v152, s[28:29]
	s_waitcnt lgkmcnt(1)
	v_mfma_f32_16x16x32_bf16 v[128:131], v[206:209], v[174:177], v[128:131]
	s_waitcnt lgkmcnt(0)
	v_mfma_f32_16x16x32_bf16 v[120:123], v[214:217], v[174:177], v[120:123]
	v_mfma_f32_16x16x32_bf16 v[112:115], v[206:209], v[182:185], v[112:115]
	v_mfma_f32_16x16x32_bf16 v[104:107], v[214:217], v[182:185], v[104:107]
	ds_read_b128 v[210:213], v133 offset:1024
	v_mfma_f32_16x16x32_bf16 v[96:99], v[206:209], v[190:193], v[96:99]
	ds_read_b128 v[218:221], v133 offset:3072
	v_mfma_f32_16x16x32_bf16 v[88:91], v[214:217], v[190:193], v[88:91]
	v_mfma_f32_16x16x32_bf16 v[80:83], v[206:209], v[198:201], v[80:83]
	v_mfma_f32_16x16x32_bf16 v[72:75], v[214:217], v[198:201], v[72:75]
	s_waitcnt lgkmcnt(1)
	v_mfma_f32_16x16x32_bf16 v[128:131], v[210:213], v[178:181], v[128:131]
	s_waitcnt lgkmcnt(0)
	v_mfma_f32_16x16x32_bf16 v[120:123], v[218:221], v[178:181], v[120:123]
	v_mfma_f32_16x16x32_bf16 v[112:115], v[210:213], v[186:189], v[112:115]
	v_mfma_f32_16x16x32_bf16 v[104:107], v[218:221], v[186:189], v[104:107]
	v_mfma_f32_16x16x32_bf16 v[96:99], v[210:213], v[194:197], v[96:99]
	v_mfma_f32_16x16x32_bf16 v[88:91], v[218:221], v[194:197], v[88:91]
	v_mfma_f32_16x16x32_bf16 v[80:83], v[210:213], v[202:205], v[80:83]
	v_mfma_f32_16x16x32_bf16 v[72:75], v[218:221], v[202:205], v[72:75]
	s_waitcnt vmcnt(4) lgkmcnt(0)
	s_barrier
; template <class Epi, class Sched>
; __device__ __forceinline__ void gemm_simple(PG8_LAS unsigned char* lds, const Gemm g, const Sched& S, const Epi& E, int wave_s) {
;     ...
;             const char* a2 = last ? nA : cA + (size_t)(t + 2) * kstep; const char* b2 = last ? nB : cB + (size_t)(t + 2) * kstep;
;             PG8_TILE(1, a2, b2, (!last || has_next));
	ds_read_b128 v[174:177], v156 offset:16384
	ds_read_b128 v[182:185], v156 offset:18432
	ds_read_b128 v[190:193], v156 offset:20480
	s_add_u32 s28, s64, 0x80080
	s_addc_u32 s29, s65, 0
	s_mov_b32 m0, s50
	s_nop 0
	global_load_lds_dwordx4 v140, s[28:29]
	s_mov_b32 m0, s54
	s_nop 0
	global_load_lds_dwordx4 v153, s[28:29]
	s_waitcnt lgkmcnt(2)
	v_mfma_f32_16x16x32_bf16 v[60:63], v[142:145], v[174:177], v[60:63]
	v_mfma_f32_16x16x32_bf16 v[52:55], v[158:161], v[174:177], v[52:55]
	ds_read_b128 v[198:201], v156 offset:22528
	s_waitcnt lgkmcnt(2)
	v_mfma_f32_16x16x32_bf16 v[44:47], v[142:145], v[182:185], v[44:47]
	v_mfma_f32_16x16x32_bf16 v[36:39], v[158:161], v[182:185], v[36:39]
	ds_read_b128 v[178:181], v156 offset:17408
	s_waitcnt lgkmcnt(2)
	v_mfma_f32_16x16x32_bf16 v[28:31], v[142:145], v[190:193], v[28:31]
	v_mfma_f32_16x16x32_bf16 v[20:23], v[158:161], v[190:193], v[20:23]
	ds_read_b128 v[186:189], v156 offset:19456
	s_waitcnt lgkmcnt(2)
	v_mfma_f32_16x16x32_bf16 v[8:11], v[142:145], v[198:201], v[8:11]
	v_mfma_f32_16x16x32_bf16 v[4:7], v[158:161], v[198:201], v[4:7]
	ds_read_b128 v[194:197], v156 offset:21504
	s_waitcnt lgkmcnt(2)
	v_mfma_f32_16x16x32_bf16 v[60:63], v[146:149], v[178:181], v[60:63]
	v_mfma_f32_16x16x32_bf16 v[52:55], v[170:173], v[178:181], v[52:55]
	ds_read_b128 v[202:205], v156 offset:23552
	s_waitcnt lgkmcnt(2)
	v_mfma_f32_16x16x32_bf16 v[44:47], v[146:149], v[186:189], v[44:47]
	v_mfma_f32_16x16x32_bf16 v[36:39], v[170:173], v[186:189], v[36:39]
	s_waitcnt lgkmcnt(1)
	v_mfma_f32_16x16x32_bf16 v[28:31], v[146:149], v[194:197], v[28:31]
	v_mfma_f32_16x16x32_bf16 v[20:23], v[170:173], v[194:197], v[20:23]
	s_waitcnt lgkmcnt(0)
	v_mfma_f32_16x16x32_bf16 v[8:11], v[146:149], v[202:205], v[8:11]
	v_mfma_f32_16x16x32_bf16 v[4:7], v[170:173], v[202:205], v[4:7]
	s_add_u32 s28, s66, 0x80080
	s_addc_u32 s29, s67, 0
	s_mov_b32 m0, s51
	s_nop 0
	global_load_lds_dwordx4 v139, s[28:29]
	s_mov_b32 m0, s55
	s_nop 0
	global_load_lds_dwordx4 v152, s[28:29]
	v_mfma_f32_16x16x32_bf16 v[64:67], v[206:209], v[174:177], v[64:67]
	s_add_u32 s28, s66, 0x100
	s_addc_u32 s29, s67, 0
	s_add_u32 s64, s64, 0x100
	v_mfma_f32_16x16x32_bf16 v[56:59], v[214:217], v[174:177], v[56:59]
	s_addc_u32 s65, s65, 0
	v_mfma_f32_16x16x32_bf16 v[48:51], v[206:209], v[182:185], v[48:51]
	v_mfma_f32_16x16x32_bf16 v[40:43], v[214:217], v[182:185], v[40:43]
	v_mfma_f32_16x16x32_bf16 v[32:35], v[206:209], v[190:193], v[32:35]
	v_mfma_f32_16x16x32_bf16 v[24:27], v[214:217], v[190:193], v[24:27]
	v_mfma_f32_16x16x32_bf16 v[16:19], v[206:209], v[198:201], v[16:19]
	v_mfma_f32_16x16x32_bf16 v[12:15], v[214:217], v[198:201], v[12:15]
	v_mfma_f32_16x16x32_bf16 v[64:67], v[210:213], v[178:181], v[64:67]
	v_mfma_f32_16x16x32_bf16 v[56:59], v[218:221], v[178:181], v[56:59]
	v_mfma_f32_16x16x32_bf16 v[48:51], v[210:213], v[186:189], v[48:51]
	v_mfma_f32_16x16x32_bf16 v[40:43], v[218:221], v[186:189], v[40:43]
	v_mfma_f32_16x16x32_bf16 v[32:35], v[210:213], v[194:197], v[32:35]
	v_mfma_f32_16x16x32_bf16 v[24:27], v[218:221], v[194:197], v[24:27]
	v_mfma_f32_16x16x32_bf16 v[16:19], v[210:213], v[202:205], v[16:19]
	v_mfma_f32_16x16x32_bf16 v[12:15], v[218:221], v[202:205], v[12:15]
	s_waitcnt vmcnt(2) lgkmcnt(0)
	s_barrier
	ds_read_b128 v[142:145], v134
	ds_read_b128 v[174:177], v156 offset:32768
	ds_read_b128 v[158:161], v134 offset:2048
	ds_read_b128 v[182:185], v156 offset:34816
	ds_read_b128 v[190:193], v156 offset:36864
	s_cmp_eq_u32 s63, s26
	s_cselect_b32 s29, s17, s29
	s_cselect_b32 s28, s60, s28
	s_cselect_b32 s65, s5, s65
	s_cselect_b32 s64, s61, s64
	s_mov_b32 m0, s35
	s_nop 0
	global_load_lds_dwordx4 v140, s[64:65]
	s_mov_b32 m0, s39
	s_nop 0
	global_load_lds_dwordx4 v153, s[64:65]
	s_waitcnt lgkmcnt(3)
	v_mfma_f32_16x16x32_bf16 v[124:127], v[142:145], v[174:177], v[124:127]
	s_waitcnt lgkmcnt(2)
	v_mfma_f32_16x16x32_bf16 v[116:119], v[158:161], v[174:177], v[116:119]
	ds_read_b128 v[198:201], v156 offset:38912
	s_waitcnt lgkmcnt(2)
	v_mfma_f32_16x16x32_bf16 v[108:111], v[142:145], v[182:185], v[108:111]
	v_mfma_f32_16x16x32_bf16 v[100:103], v[158:161], v[182:185], v[100:103]
	ds_read_b128 v[146:149], v134 offset:1024
	ds_read_b128 v[178:181], v156 offset:33792
	s_waitcnt lgkmcnt(3)
	v_mfma_f32_16x16x32_bf16 v[92:95], v[142:145], v[190:193], v[92:95]
	ds_read_b128 v[170:173], v134 offset:3072
	v_mfma_f32_16x16x32_bf16 v[84:87], v[158:161], v[190:193], v[84:87]
	ds_read_b128 v[186:189], v156 offset:35840
	s_waitcnt lgkmcnt(4)
	v_mfma_f32_16x16x32_bf16 v[76:79], v[142:145], v[198:201], v[76:79]
	v_mfma_f32_16x16x32_bf16 v[68:71], v[158:161], v[198:201], v[68:71]
	ds_read_b128 v[194:197], v156 offset:37888
	s_waitcnt lgkmcnt(3)
	v_mfma_f32_16x16x32_bf16 v[124:127], v[146:149], v[178:181], v[124:127]
	s_waitcnt lgkmcnt(2)
	v_mfma_f32_16x16x32_bf16 v[116:119], v[170:173], v[178:181], v[116:119]
	ds_read_b128 v[202:205], v156 offset:39936
	s_waitcnt lgkmcnt(2)
	v_mfma_f32_16x16x32_bf16 v[108:111], v[146:149], v[186:189], v[108:111]
	v_mfma_f32_16x16x32_bf16 v[100:103], v[170:173], v[186:189], v[100:103]
	ds_read_b128 v[206:209], v135
	s_waitcnt lgkmcnt(2)
	v_mfma_f32_16x16x32_bf16 v[92:95], v[146:149], v[194:197], v[92:95]
	ds_read_b128 v[214:217], v135 offset:2048
	v_mfma_f32_16x16x32_bf16 v[84:87], v[170:173], v[194:197], v[84:87]
	s_waitcnt lgkmcnt(2)
	v_mfma_f32_16x16x32_bf16 v[76:79], v[146:149], v[202:205], v[76:79]
	v_mfma_f32_16x16x32_bf16 v[68:71], v[170:173], v[202:205], v[68:71]
	s_mov_b32 m0, s23
	s_nop 0
	global_load_lds_dwordx4 v139, s[28:29]
	s_mov_b32 m0, s40
	s_nop 0
	global_load_lds_dwordx4 v152, s[28:29]
	s_waitcnt lgkmcnt(1)
	v_mfma_f32_16x16x32_bf16 v[128:131], v[206:209], v[174:177], v[128:131]
	s_waitcnt lgkmcnt(0)
	v_mfma_f32_16x16x32_bf16 v[120:123], v[214:217], v[174:177], v[120:123]
	v_mfma_f32_16x16x32_bf16 v[112:115], v[206:209], v[182:185], v[112:115]
	v_mfma_f32_16x16x32_bf16 v[104:107], v[214:217], v[182:185], v[104:107]
	ds_read_b128 v[210:213], v135 offset:1024
	v_mfma_f32_16x16x32_bf16 v[96:99], v[206:209], v[190:193], v[96:99]
	ds_read_b128 v[218:221], v135 offset:3072
	v_mfma_f32_16x16x32_bf16 v[88:91], v[214:217], v[190:193], v[88:91]
	v_mfma_f32_16x16x32_bf16 v[80:83], v[206:209], v[198:201], v[80:83]
	v_mfma_f32_16x16x32_bf16 v[72:75], v[214:217], v[198:201], v[72:75]
	s_waitcnt lgkmcnt(1)
	v_mfma_f32_16x16x32_bf16 v[128:131], v[210:213], v[178:181], v[128:131]
	s_waitcnt lgkmcnt(0)
	v_mfma_f32_16x16x32_bf16 v[120:123], v[218:221], v[178:181], v[120:123]
	v_mfma_f32_16x16x32_bf16 v[112:115], v[210:213], v[186:189], v[112:115]
	v_mfma_f32_16x16x32_bf16 v[104:107], v[218:221], v[186:189], v[104:107]
	v_mfma_f32_16x16x32_bf16 v[96:99], v[210:213], v[194:197], v[96:99]
	v_mfma_f32_16x16x32_bf16 v[88:91], v[218:221], v[194:197], v[88:91]
	v_mfma_f32_16x16x32_bf16 v[80:83], v[210:213], v[202:205], v[80:83]
	v_mfma_f32_16x16x32_bf16 v[72:75], v[218:221], v[202:205], v[72:75]
	s_waitcnt vmcnt(4) lgkmcnt(0)
	s_barrier
; #define LAS __attribute__((address_space(3)))
; __device__ __forceinline__ void rstd_table(const float* ssq, LAS unsigned char* lds, const Unit& u, int tid, int par) {
;     if (tid < 256) { const f32x4* p = (const f32x4*)(ssq + (size_t)(u.pm * 256 + tid) * 32); f32x4 a = p[0];
; #pragma unroll
;         for (int i = 1; i < 8; ++i) a += p[i];
;         ((LAS float*)(lds + 131072 + par * 1024))[tid] = 1.0f / sqrtf(((a[0] + a[1]) + (a[2] + a[3])) * (1.0f / DM) + 1e-6f); }
	ds_read_b128 v[174:177], v156 offset:49152
	ds_read_b128 v[182:185], v156 offset:51200
	ds_read_b128 v[190:193], v156 offset:53248
	s_add_u32 s64, s64, 0x80000
	s_addc_u32 s65, s65, 0
	s_mov_b32 m0, s41
	s_nop 0
	global_load_lds_dwordx4 v140, s[64:65]
	s_mov_b32 m0, s42
	s_nop 0
	global_load_lds_dwordx4 v153, s[64:65]
	s_waitcnt lgkmcnt(2)
	v_mfma_f32_16x16x32_bf16 v[60:63], v[142:145], v[174:177], v[60:63]
	v_mfma_f32_16x16x32_bf16 v[52:55], v[158:161], v[174:177], v[52:55]
	ds_read_b128 v[198:201], v156 offset:55296
	s_waitcnt lgkmcnt(2)
	v_mfma_f32_16x16x32_bf16 v[44:47], v[142:145], v[182:185], v[44:47]
	v_mfma_f32_16x16x32_bf16 v[36:39], v[158:161], v[182:185], v[36:39]
	ds_read_b128 v[178:181], v156 offset:50176
	s_waitcnt lgkmcnt(2)
	v_mfma_f32_16x16x32_bf16 v[28:31], v[142:145], v[190:193], v[28:31]
	v_mfma_f32_16x16x32_bf16 v[20:23], v[158:161], v[190:193], v[20:23]
	ds_read_b128 v[186:189], v156 offset:52224
	s_waitcnt lgkmcnt(2)
	v_mfma_f32_16x16x32_bf16 v[8:11], v[142:145], v[198:201], v[8:11]
	v_mfma_f32_16x16x32_bf16 v[4:7], v[158:161], v[198:201], v[4:7]
	ds_read_b128 v[194:197], v156 offset:54272
	s_waitcnt lgkmcnt(2)
	v_mfma_f32_16x16x32_bf16 v[60:63], v[146:149], v[178:181], v[60:63]
	v_mfma_f32_16x16x32_bf16 v[52:55], v[170:173], v[178:181], v[52:55]
	ds_read_b128 v[202:205], v156 offset:56320
	s_waitcnt lgkmcnt(2)
	v_mfma_f32_16x16x32_bf16 v[44:47], v[146:149], v[186:189], v[44:47]
	v_mfma_f32_16x16x32_bf16 v[36:39], v[170:173], v[186:189], v[36:39]
	s_waitcnt lgkmcnt(1)
	v_mfma_f32_16x16x32_bf16 v[28:31], v[146:149], v[194:197], v[28:31]
	v_mfma_f32_16x16x32_bf16 v[20:23], v[170:173], v[194:197], v[20:23]
	s_waitcnt lgkmcnt(0)
	v_mfma_f32_16x16x32_bf16 v[8:11], v[146:149], v[202:205], v[8:11]
	v_mfma_f32_16x16x32_bf16 v[4:7], v[170:173], v[202:205], v[4:7]
	s_add_u32 s28, s28, 0x80000
	s_addc_u32 s29, s29, 0
	s_mov_b32 m0, s43
	s_nop 0
	global_load_lds_dwordx4 v139, s[28:29]
	s_mov_b32 m0, s44
	s_nop 0
	global_load_lds_dwordx4 v152, s[28:29]
	v_mfma_f32_16x16x32_bf16 v[64:67], v[206:209], v[174:177], v[64:67]
	s_add_i32 s62, s62, 2
	s_add_u32 s26, s26, 0xffffff00
	s_addc_u32 s27, s27, -1
	v_mfma_f32_16x16x32_bf16 v[56:59], v[214:217], v[174:177], v[56:59]
	s_add_u32 s24, s24, 0x100
	s_addc_u32 s25, s25, 0
	s_add_u32 s10, s10, 0x100
	v_mfma_f32_16x16x32_bf16 v[48:51], v[206:209], v[182:185], v[48:51]
	s_addc_u32 s11, s11, 0
	s_cmp_lt_u32 s62, 30
	v_mfma_f32_16x16x32_bf16 v[40:43], v[214:217], v[182:185], v[40:43]
	v_mfma_f32_16x16x32_bf16 v[32:35], v[206:209], v[190:193], v[32:35]
	v_mfma_f32_16x16x32_bf16 v[24:27], v[214:217], v[190:193], v[24:27]
	v_mfma_f32_16x16x32_bf16 v[16:19], v[206:209], v[198:201], v[16:19]
	v_mfma_f32_16x16x32_bf16 v[12:15], v[214:217], v[198:201], v[12:15]
	s_cbranch_scc1 .Lrt_95
	v_mfma_f32_16x16x32_bf16 v[64:67], v[210:213], v[178:181], v[64:67]
	v_mfma_f32_16x16x32_bf16 v[56:59], v[218:221], v[178:181], v[56:59]
	v_mfma_f32_16x16x32_bf16 v[48:51], v[210:213], v[186:189], v[48:51]
	v_mfma_f32_16x16x32_bf16 v[40:43], v[218:221], v[186:189], v[40:43]
	v_mfma_f32_16x16x32_bf16 v[32:35], v[210:213], v[194:197], v[32:35]
	v_mfma_f32_16x16x32_bf16 v[24:27], v[218:221], v[194:197], v[24:27]
	v_mfma_f32_16x16x32_bf16 v[16:19], v[210:213], v[202:205], v[16:19]
	v_mfma_f32_16x16x32_bf16 v[12:15], v[218:221], v[202:205], v[12:15]
	s_nor_b64 s[10:11], s[6:7], s[8:9]
	s_and_saveexec_b64 s[24:25], s[10:11]
	s_cbranch_execz .LBB0_89
	v_lshl_add_u32 v132, s16, 8, v138
	v_ashrrev_i32_e32 v133, 31, v132
	v_lshlrev_b64 v[132:133], 7, v[132:133]
	v_lshl_add_u64 v[136:137], s[0:1], 0, v[132:133]
	global_load_dwordx4 v[132:135], v[136:137], off offset:48
	global_load_dwordx4 v[142:145], v[136:137], off offset:32
	global_load_dwordx4 v[146:149], v[136:137], off
	global_load_dwordx4 v[158:161], v[136:137], off offset:16
	s_lshl_b32 s5, s57, 10
	s_and_b32 s5, s5, 0x400
	s_waitcnt vmcnt(0)
	v_pk_add_f32 v[148:149], v[148:149], v[160:161]
	v_pk_add_f32 v[146:147], v[146:147], v[158:159]
	v_pk_add_f32 v[144:145], v[148:149], v[144:145]
	v_pk_add_f32 v[142:143], v[146:147], v[142:143]
	v_pk_add_f32 v[162:163], v[144:145], v[134:135]
	v_pk_add_f32 v[170:171], v[142:143], v[132:133]
	global_load_dwordx4 v[132:135], v[136:137], off offset:112
	global_load_dwordx4 v[142:145], v[136:137], off offset:96
	global_load_dwordx4 v[146:149], v[136:137], off offset:80
	global_load_dwordx4 v[158:161], v[136:137], off offset:64
	s_waitcnt vmcnt(0)
	v_pk_add_f32 v[136:137], v[162:163], v[160:161]
	v_pk_add_f32 v[158:159], v[170:171], v[158:159]
	v_pk_add_f32 v[136:137], v[136:137], v[148:149]
	v_pk_add_f32 v[146:147], v[158:159], v[146:147]
	v_pk_add_f32 v[136:137], v[136:137], v[144:145]
	v_pk_add_f32 v[142:143], v[146:147], v[142:143]
	v_pk_add_f32 v[134:135], v[136:137], v[134:135]
	v_pk_add_f32 v[132:133], v[142:143], v[132:133]
	s_nop 0
	v_pk_mov_b32 v[136:137], v[132:133], v[134:135] op_sel:[1,0]
	v_mov_b32_e32 v133, v135
	v_pk_add_f32 v[132:133], v[136:137], v[132:133]
	s_nop 0
	v_add_f32_e32 v132, v132, v133
	v_fmamk_f32 v132, v132, 0x3a000000, v164
	v_cmp_gt_f32_e32 vcc, s69, v132
	v_mul_f32_e32 v133, 0x4f800000, v132
	s_nop 0
	v_cndmask_b32_e32 v132, v132, v133, vcc
	v_sqrt_f32_e32 v133, v132
	s_nop 0
	v_add_u32_e32 v134, -1, v133
	v_fma_f32 v135, -v134, v133, v132
	v_cmp_ge_f32_e64 s[10:11], 0, v135
	v_add_u32_e32 v135, 1, v133
	s_nop 0
	v_cndmask_b32_e64 v134, v133, v134, s[10:11]
	v_fma_f32 v133, -v135, v133, v132
	v_cmp_lt_f32_e64 s[10:11], 0, v133
	s_nop 1
	v_cndmask_b32_e64 v133, v134, v135, s[10:11]
	v_mul_f32_e32 v134, 0x37800000, v133
	v_cndmask_b32_e32 v133, v133, v134, vcc
	v_cmp_class_f32_e32 vcc, v132, v165
	s_nop 1
	v_cndmask_b32_e32 v132, v133, v132, vcc
	v_div_scale_f32 v133, s[10:11], v132, v132, 1.0
	v_rcp_f32_e32 v134, v133
	s_nop 0
	v_fma_f32 v135, -v133, v134, 1.0
	v_fmac_f32_e32 v134, v135, v134
	v_div_scale_f32 v135, vcc, 1.0, v132, 1.0
	v_mul_f32_e32 v136, v135, v134
	v_fma_f32 v137, -v133, v136, v135
	v_fmac_f32_e32 v136, v137, v134
	v_fma_f32 v133, -v133, v136, v135
	v_div_fmas_f32 v133, v133, v134, v136
	v_div_fixup_f32 v132, v133, v132, 1.0
	v_add_u32_e32 v133, s5, v154
	ds_write_b32 v133, v132
	s_branch .LBB0_89

; template <class Epi, class Sched>
; __device__ __forceinline__ void gemm_simple(PG8_LAS unsigned char* lds, const Gemm g, const Sched& S, const Epi& E, int wave_s) {
;     ...
;         const bool has_next = S.next(ui + 1, nxt);
;         const char* nA = has_next ? (const char*)g.A + (size_t)nxt.pm * tstep : cA; const char* nB = has_next ? (const char*)g.Bt + (size_t)nxt.pn * tstep : cB;
.LBB0_118:
	s_ashr_i32 s11, s10, 31
	s_lshl_b64 s[16:17], s[10:11], 20
	s_add_u32 s16, s12, s16
	s_addc_u32 s17, s13, s17
	s_and_b64 s[18:19], vcc, exec
	s_cselect_b32 s11, s17, s27
	s_cselect_b32 s21, s16, s26
	s_ashr_i32 s5, s4, 31
	s_lshl_b64 s[18:19], s[4:5], 20
	s_add_u32 s18, s28, s18
	s_addc_u32 s19, s29, s19
	s_and_b64 s[60:61], vcc, exec
	s_cselect_b32 s5, s19, s25
	s_cselect_b32 s23, s18, s24
	s_add_i32 s35, s58, -2
	s_lshl_b32 s58, s58, 7
	s_add_u32 s59, s24, 0x100
	s_addc_u32 s60, s25, 0
	s_add_u32 s61, s26, 0x100
	s_addc_u32 s62, s27, 0
	s_add_u32 s63, s26, 0x80080
	s_addc_u32 s64, s27, 0
	s_add_u32 s65, s24, 0x80080
	s_addc_u32 s66, s25, 0
	s_add_u32 s67, s26, 0x80
	s_addc_u32 s68, s27, 0
	s_add_u32 s69, s24, 0x80
	s_addc_u32 s70, s25, 0
	s_mov_b64 s[24:25], 0xf00
	s_branch .Lrt_top_119
.Lrt_119:
	v_mfma_f32_16x16x32_bf16 v[56:59], v[210:213], v[178:181], v[56:59]
	v_mfma_f32_16x16x32_bf16 v[52:55], v[218:221], v[178:181], v[52:55]
	v_mfma_f32_16x16x32_bf16 v[40:43], v[210:213], v[186:189], v[40:43]
	v_mfma_f32_16x16x32_bf16 v[36:39], v[218:221], v[186:189], v[36:39]
	v_mfma_f32_16x16x32_bf16 v[24:27], v[210:213], v[194:197], v[24:27]
	v_mfma_f32_16x16x32_bf16 v[20:23], v[218:221], v[194:197], v[20:23]
	v_mfma_f32_16x16x32_bf16 v[8:11], v[210:213], v[202:205], v[8:11]
	v_mfma_f32_16x16x32_bf16 v[4:7], v[218:221], v[202:205], v[4:7]
.Lrt_top_119:
.LBB0_119:
	s_waitcnt vmcnt(2) lgkmcnt(0)
	s_barrier
	ds_read_b128 v[146:149], v132
	ds_read_b128 v[174:177], v154
	ds_read_b128 v[160:163], v132 offset:2048
	ds_read_b128 v[182:185], v154 offset:2048
	ds_read_b128 v[190:193], v154 offset:4096
	s_add_u32 s26, s69, s58
	s_addc_u32 s27, s70, 0
	s_mov_b32 m0, s47
	s_nop 0
	global_load_lds_dwordx4 v139, s[26:27]
	s_mov_b32 m0, s51
	s_nop 0
	global_load_lds_dwordx4 v152, s[26:27]
	s_waitcnt lgkmcnt(3)
	v_mfma_f32_16x16x32_bf16 v[128:131], v[146:149], v[174:177], v[128:131]
	s_waitcnt lgkmcnt(2)
	v_mfma_f32_16x16x32_bf16 v[124:127], v[160:163], v[174:177], v[124:127]
	ds_read_b128 v[198:201], v154 offset:6144
	s_waitcnt lgkmcnt(2)
	v_mfma_f32_16x16x32_bf16 v[112:115], v[146:149], v[182:185], v[112:115]
	v_mfma_f32_16x16x32_bf16 v[108:111], v[160:163], v[182:185], v[108:111]
	ds_read_b128 v[156:159], v132 offset:1024
	ds_read_b128 v[178:181], v154 offset:1024
	s_waitcnt lgkmcnt(3)
	v_mfma_f32_16x16x32_bf16 v[96:99], v[146:149], v[190:193], v[96:99]
	ds_read_b128 v[170:173], v132 offset:3072
	v_mfma_f32_16x16x32_bf16 v[92:95], v[160:163], v[190:193], v[92:95]
	ds_read_b128 v[186:189], v154 offset:3072
	s_waitcnt lgkmcnt(4)
	v_mfma_f32_16x16x32_bf16 v[80:83], v[146:149], v[198:201], v[80:83]
	v_mfma_f32_16x16x32_bf16 v[76:79], v[160:163], v[198:201], v[76:79]
	ds_read_b128 v[194:197], v154 offset:5120
	s_waitcnt lgkmcnt(3)
	v_mfma_f32_16x16x32_bf16 v[128:131], v[156:159], v[178:181], v[128:131]
	s_waitcnt lgkmcnt(2)
	v_mfma_f32_16x16x32_bf16 v[124:127], v[170:173], v[178:181], v[124:127]
	ds_read_b128 v[202:205], v154 offset:7168
	s_waitcnt lgkmcnt(2)
	v_mfma_f32_16x16x32_bf16 v[112:115], v[156:159], v[186:189], v[112:115]
	v_mfma_f32_16x16x32_bf16 v[108:111], v[170:173], v[186:189], v[108:111]
	ds_read_b128 v[206:209], v133
	s_waitcnt lgkmcnt(2)
	v_mfma_f32_16x16x32_bf16 v[96:99], v[156:159], v[194:197], v[96:99]
	ds_read_b128 v[214:217], v133 offset:2048
	v_mfma_f32_16x16x32_bf16 v[92:95], v[170:173], v[194:197], v[92:95]
	s_waitcnt lgkmcnt(2)
	v_mfma_f32_16x16x32_bf16 v[80:83], v[156:159], v[202:205], v[80:83]
	v_mfma_f32_16x16x32_bf16 v[76:79], v[170:173], v[202:205], v[76:79]
	s_add_u32 s26, s67, s58
	s_addc_u32 s27, s68, 0
	s_mov_b32 m0, s48
	s_nop 0
	global_load_lds_dwordx4 v138, s[26:27]
	s_mov_b32 m0, s52
	s_nop 0
	global_load_lds_dwordx4 v140, s[26:27]
	s_waitcnt lgkmcnt(1)
	v_mfma_f32_16x16x32_bf16 v[120:123], v[206:209], v[174:177], v[120:123]
	s_waitcnt lgkmcnt(0)
	v_mfma_f32_16x16x32_bf16 v[116:119], v[214:217], v[174:177], v[116:119]
	v_mfma_f32_16x16x32_bf16 v[104:107], v[206:209], v[182:185], v[104:107]
	v_mfma_f32_16x16x32_bf16 v[100:103], v[214:217], v[182:185], v[100:103]
	ds_read_b128 v[210:213], v133 offset:1024
	v_mfma_f32_16x16x32_bf16 v[88:91], v[206:209], v[190:193], v[88:91]
	ds_read_b128 v[218:221], v133 offset:3072
	v_mfma_f32_16x16x32_bf16 v[84:87], v[214:217], v[190:193], v[84:87]
	v_mfma_f32_16x16x32_bf16 v[72:75], v[206:209], v[198:201], v[72:75]
	v_mfma_f32_16x16x32_bf16 v[68:71], v[214:217], v[198:201], v[68:71]
	s_waitcnt lgkmcnt(1)
	v_mfma_f32_16x16x32_bf16 v[120:123], v[210:213], v[178:181], v[120:123]
	s_waitcnt lgkmcnt(0)
	v_mfma_f32_16x16x32_bf16 v[116:119], v[218:221], v[178:181], v[116:119]
	v_mfma_f32_16x16x32_bf16 v[104:107], v[210:213], v[186:189], v[104:107]
	v_mfma_f32_16x16x32_bf16 v[100:103], v[218:221], v[186:189], v[100:103]
	v_mfma_f32_16x16x32_bf16 v[88:91], v[210:213], v[194:197], v[88:91]
	v_mfma_f32_16x16x32_bf16 v[84:87], v[218:221], v[194:197], v[84:87]
	v_mfma_f32_16x16x32_bf16 v[72:75], v[210:213], v[202:205], v[72:75]
	v_mfma_f32_16x16x32_bf16 v[68:71], v[218:221], v[202:205], v[68:71]
	s_waitcnt vmcnt(4) lgkmcnt(0)
	s_barrier
; template <class Epi, class Sched>
; __device__ __forceinline__ void gemm_simple(PG8_LAS unsigned char* lds, const Gemm g, const Sched& S, const Epi& E, int wave_s) {
;     ...
;         for (; t < nt; t += 2) {
;             const bool last = (t == nt - 2);
;             PG8_TILE(0, cA + (size_t)(t + 1) * kstep, cB + (size_t)(t + 1) * kstep, true);
;             const char* a2 = last ? nA : cA + (size_t)(t + 2) * kstep; const char* b2 = last ? nB : cB + (size_t)(t + 2) * kstep;
;             PG8_TILE(1, a2, b2, (!last || has_next));
	ds_read_b128 v[174:177], v154 offset:16384
	ds_read_b128 v[182:185], v154 offset:18432
	ds_read_b128 v[190:193], v154 offset:20480
	s_add_u32 s26, s65, s58
	s_addc_u32 s27, s66, 0
	s_mov_b32 m0, s49
	s_nop 0
	global_load_lds_dwordx4 v139, s[26:27]
	s_mov_b32 m0, s53
	s_nop 0
	global_load_lds_dwordx4 v152, s[26:27]
	s_waitcnt lgkmcnt(2)
	v_mfma_f32_16x16x32_bf16 v[64:67], v[146:149], v[174:177], v[64:67]
	v_mfma_f32_16x16x32_bf16 v[60:63], v[160:163], v[174:177], v[60:63]
	ds_read_b128 v[198:201], v154 offset:22528
	s_waitcnt lgkmcnt(2)
	v_mfma_f32_16x16x32_bf16 v[48:51], v[146:149], v[182:185], v[48:51]
	v_mfma_f32_16x16x32_bf16 v[44:47], v[160:163], v[182:185], v[44:47]
	ds_read_b128 v[178:181], v154 offset:17408
	s_waitcnt lgkmcnt(2)
	v_mfma_f32_16x16x32_bf16 v[32:35], v[146:149], v[190:193], v[32:35]
	v_mfma_f32_16x16x32_bf16 v[28:31], v[160:163], v[190:193], v[28:31]
	ds_read_b128 v[186:189], v154 offset:19456
	s_waitcnt lgkmcnt(2)
	v_mfma_f32_16x16x32_bf16 v[16:19], v[146:149], v[198:201], v[16:19]
	v_mfma_f32_16x16x32_bf16 v[12:15], v[160:163], v[198:201], v[12:15]
	ds_read_b128 v[194:197], v154 offset:21504
	s_waitcnt lgkmcnt(2)
	v_mfma_f32_16x16x32_bf16 v[64:67], v[156:159], v[178:181], v[64:67]
	v_mfma_f32_16x16x32_bf16 v[60:63], v[170:173], v[178:181], v[60:63]
	ds_read_b128 v[202:205], v154 offset:23552
	s_waitcnt lgkmcnt(2)
	v_mfma_f32_16x16x32_bf16 v[48:51], v[156:159], v[186:189], v[48:51]
	v_mfma_f32_16x16x32_bf16 v[44:47], v[170:173], v[186:189], v[44:47]
	s_waitcnt lgkmcnt(1)
	v_mfma_f32_16x16x32_bf16 v[32:35], v[156:159], v[194:197], v[32:35]
	v_mfma_f32_16x16x32_bf16 v[28:31], v[170:173], v[194:197], v[28:31]
	s_waitcnt lgkmcnt(0)
	v_mfma_f32_16x16x32_bf16 v[16:19], v[156:159], v[202:205], v[16:19]
	v_mfma_f32_16x16x32_bf16 v[12:15], v[170:173], v[202:205], v[12:15]
	s_add_u32 s26, s63, s58
	s_addc_u32 s27, s64, 0
	s_mov_b32 m0, s50
	s_nop 0
	global_load_lds_dwordx4 v138, s[26:27]
	s_mov_b32 m0, s54
	s_nop 0
	global_load_lds_dwordx4 v140, s[26:27]
	v_mfma_f32_16x16x32_bf16 v[56:59], v[206:209], v[174:177], v[56:59]
	s_add_u32 s26, s61, s58
	s_addc_u32 s27, s62, 0
	s_add_u32 s71, s59, s58
	v_mfma_f32_16x16x32_bf16 v[52:55], v[214:217], v[174:177], v[52:55]
	s_addc_u32 s72, s60, 0
	v_mfma_f32_16x16x32_bf16 v[40:43], v[206:209], v[182:185], v[40:43]
	v_mfma_f32_16x16x32_bf16 v[36:39], v[214:217], v[182:185], v[36:39]
	v_mfma_f32_16x16x32_bf16 v[24:27], v[206:209], v[190:193], v[24:27]
	v_mfma_f32_16x16x32_bf16 v[20:23], v[214:217], v[190:193], v[20:23]
	v_mfma_f32_16x16x32_bf16 v[8:11], v[206:209], v[198:201], v[8:11]
	v_mfma_f32_16x16x32_bf16 v[4:7], v[214:217], v[198:201], v[4:7]
	v_mfma_f32_16x16x32_bf16 v[56:59], v[210:213], v[178:181], v[56:59]
	v_mfma_f32_16x16x32_bf16 v[52:55], v[218:221], v[178:181], v[52:55]
	v_mfma_f32_16x16x32_bf16 v[40:43], v[210:213], v[186:189], v[40:43]
	v_mfma_f32_16x16x32_bf16 v[36:39], v[218:221], v[186:189], v[36:39]
	v_mfma_f32_16x16x32_bf16 v[24:27], v[210:213], v[194:197], v[24:27]
	v_mfma_f32_16x16x32_bf16 v[20:23], v[218:221], v[194:197], v[20:23]
	v_mfma_f32_16x16x32_bf16 v[8:11], v[210:213], v[202:205], v[8:11]
	v_mfma_f32_16x16x32_bf16 v[4:7], v[218:221], v[202:205], v[4:7]
	s_waitcnt vmcnt(2) lgkmcnt(0)
	s_barrier
	ds_read_b128 v[146:149], v134
	ds_read_b128 v[174:177], v154 offset:32768
	ds_read_b128 v[160:163], v134 offset:2048
	ds_read_b128 v[182:185], v154 offset:34816
	ds_read_b128 v[190:193], v154 offset:36864
	s_cmp_eq_u32 s58, s24
	s_cselect_b32 s27, s11, s27
	s_cselect_b32 s26, s21, s26
	s_cselect_b32 s73, s5, s72
	s_cselect_b32 s72, s23, s71
	s_mov_b32 m0, s40
	s_nop 0
	global_load_lds_dwordx4 v139, s[72:73]
	s_mov_b32 m0, s41
	s_nop 0
	global_load_lds_dwordx4 v152, s[72:73]
	s_waitcnt lgkmcnt(3)
	v_mfma_f32_16x16x32_bf16 v[128:131], v[146:149], v[174:177], v[128:131]
	s_waitcnt lgkmcnt(2)
	v_mfma_f32_16x16x32_bf16 v[124:127], v[160:163], v[174:177], v[124:127]
	ds_read_b128 v[198:201], v154 offset:38912
	s_waitcnt lgkmcnt(2)
	v_mfma_f32_16x16x32_bf16 v[112:115], v[146:149], v[182:185], v[112:115]
	v_mfma_f32_16x16x32_bf16 v[108:111], v[160:163], v[182:185], v[108:111]
	ds_read_b128 v[156:159], v134 offset:1024
	ds_read_b128 v[178:181], v154 offset:33792
	s_waitcnt lgkmcnt(3)
	v_mfma_f32_16x16x32_bf16 v[96:99], v[146:149], v[190:193], v[96:99]
	ds_read_b128 v[170:173], v134 offset:3072
	v_mfma_f32_16x16x32_bf16 v[92:95], v[160:163], v[190:193], v[92:95]
	ds_read_b128 v[186:189], v154 offset:35840
	s_waitcnt lgkmcnt(4)
	v_mfma_f32_16x16x32_bf16 v[80:83], v[146:149], v[198:201], v[80:83]
	v_mfma_f32_16x16x32_bf16 v[76:79], v[160:163], v[198:201], v[76:79]
	ds_read_b128 v[194:197], v154 offset:37888
	s_waitcnt lgkmcnt(3)
	v_mfma_f32_16x16x32_bf16 v[128:131], v[156:159], v[178:181], v[128:131]
	s_waitcnt lgkmcnt(2)
	v_mfma_f32_16x16x32_bf16 v[124:127], v[170:173], v[178:181], v[124:127]
	ds_read_b128 v[202:205], v154 offset:39936
	s_waitcnt lgkmcnt(2)
	v_mfma_f32_16x16x32_bf16 v[112:115], v[156:159], v[186:189], v[112:115]
	v_mfma_f32_16x16x32_bf16 v[108:111], v[170:173], v[186:189], v[108:111]
	ds_read_b128 v[206:209], v135
	s_waitcnt lgkmcnt(2)
	v_mfma_f32_16x16x32_bf16 v[96:99], v[156:159], v[194:197], v[96:99]
	ds_read_b128 v[214:217], v135 offset:2048
	v_mfma_f32_16x16x32_bf16 v[92:95], v[170:173], v[194:197], v[92:95]
	s_waitcnt lgkmcnt(2)
	v_mfma_f32_16x16x32_bf16 v[80:83], v[156:159], v[202:205], v[80:83]
	v_mfma_f32_16x16x32_bf16 v[76:79], v[170:173], v[202:205], v[76:79]
	s_mov_b32 m0, s39
	s_nop 0
	global_load_lds_dwordx4 v138, s[26:27]
	s_mov_b32 m0, s42
	s_nop 0
	global_load_lds_dwordx4 v140, s[26:27]
	s_waitcnt lgkmcnt(1)
	v_mfma_f32_16x16x32_bf16 v[120:123], v[206:209], v[174:177], v[120:123]
	s_waitcnt lgkmcnt(0)
	v_mfma_f32_16x16x32_bf16 v[116:119], v[214:217], v[174:177], v[116:119]
	v_mfma_f32_16x16x32_bf16 v[104:107], v[206:209], v[182:185], v[104:107]
	v_mfma_f32_16x16x32_bf16 v[100:103], v[214:217], v[182:185], v[100:103]
	ds_read_b128 v[210:213], v135 offset:1024
	v_mfma_f32_16x16x32_bf16 v[88:91], v[206:209], v[190:193], v[88:91]
	ds_read_b128 v[218:221], v135 offset:3072
	v_mfma_f32_16x16x32_bf16 v[84:87], v[214:217], v[190:193], v[84:87]
	v_mfma_f32_16x16x32_bf16 v[72:75], v[206:209], v[198:201], v[72:75]
	v_mfma_f32_16x16x32_bf16 v[68:71], v[214:217], v[198:201], v[68:71]
	s_waitcnt lgkmcnt(1)
	v_mfma_f32_16x16x32_bf16 v[120:123], v[210:213], v[178:181], v[120:123]
	s_waitcnt lgkmcnt(0)
	v_mfma_f32_16x16x32_bf16 v[116:119], v[218:221], v[178:181], v[116:119]
	v_mfma_f32_16x16x32_bf16 v[104:107], v[210:213], v[186:189], v[104:107]
	v_mfma_f32_16x16x32_bf16 v[100:103], v[218:221], v[186:189], v[100:103]
	v_mfma_f32_16x16x32_bf16 v[88:91], v[210:213], v[194:197], v[88:91]
	v_mfma_f32_16x16x32_bf16 v[84:87], v[218:221], v[194:197], v[84:87]
	v_mfma_f32_16x16x32_bf16 v[72:75], v[210:213], v[202:205], v[72:75]
	v_mfma_f32_16x16x32_bf16 v[68:71], v[218:221], v[202:205], v[68:71]
	s_waitcnt vmcnt(4) lgkmcnt(0)
	s_barrier
; template <class Epi, class Sched>
; __device__ __forceinline__ void gemm_simple(PG8_LAS unsigned char* lds, const Gemm g, const Sched& S, const Epi& E, int wave_s) {
;     ...
;         for (; t < nt; t += 2) {
;             const bool last = (t == nt - 2);
;             PG8_TILE(0, cA + (size_t)(t + 1) * kstep, cB + (size_t)(t + 1) * kstep, true);
;             const char* a2 = last ? nA : cA + (size_t)(t + 2) * kstep; const char* b2 = last ? nB : cB + (size_t)(t + 2) * kstep;
;             PG8_TILE(1, a2, b2, (!last || has_next));
	ds_read_b128 v[174:177], v154 offset:49152
	ds_read_b128 v[182:185], v154 offset:51200
	ds_read_b128 v[190:193], v154 offset:53248
	s_add_u32 s72, s72, 0x80000
	s_addc_u32 s73, s73, 0
	s_mov_b32 m0, s43
	s_nop 0
	global_load_lds_dwordx4 v139, s[72:73]
	s_mov_b32 m0, s44
	s_nop 0
	global_load_lds_dwordx4 v152, s[72:73]
	s_waitcnt lgkmcnt(2)
	v_mfma_f32_16x16x32_bf16 v[64:67], v[146:149], v[174:177], v[64:67]
	v_mfma_f32_16x16x32_bf16 v[60:63], v[160:163], v[174:177], v[60:63]
	ds_read_b128 v[198:201], v154 offset:55296
	s_waitcnt lgkmcnt(2)
	v_mfma_f32_16x16x32_bf16 v[48:51], v[146:149], v[182:185], v[48:51]
	v_mfma_f32_16x16x32_bf16 v[44:47], v[160:163], v[182:185], v[44:47]
	ds_read_b128 v[178:181], v154 offset:50176
	s_waitcnt lgkmcnt(2)
	v_mfma_f32_16x16x32_bf16 v[32:35], v[146:149], v[190:193], v[32:35]
	v_mfma_f32_16x16x32_bf16 v[28:31], v[160:163], v[190:193], v[28:31]
	ds_read_b128 v[186:189], v154 offset:52224
	s_waitcnt lgkmcnt(2)
	v_mfma_f32_16x16x32_bf16 v[16:19], v[146:149], v[198:201], v[16:19]
	v_mfma_f32_16x16x32_bf16 v[12:15], v[160:163], v[198:201], v[12:15]
	ds_read_b128 v[194:197], v154 offset:54272
	s_waitcnt lgkmcnt(2)
	v_mfma_f32_16x16x32_bf16 v[64:67], v[156:159], v[178:181], v[64:67]
	v_mfma_f32_16x16x32_bf16 v[60:63], v[170:173], v[178:181], v[60:63]
	ds_read_b128 v[202:205], v154 offset:56320
	s_waitcnt lgkmcnt(2)
	v_mfma_f32_16x16x32_bf16 v[48:51], v[156:159], v[186:189], v[48:51]
	v_mfma_f32_16x16x32_bf16 v[44:47], v[170:173], v[186:189], v[44:47]
	s_waitcnt lgkmcnt(1)
	v_mfma_f32_16x16x32_bf16 v[32:35], v[156:159], v[194:197], v[32:35]
	v_mfma_f32_16x16x32_bf16 v[28:31], v[170:173], v[194:197], v[28:31]
	s_waitcnt lgkmcnt(0)
	v_mfma_f32_16x16x32_bf16 v[16:19], v[156:159], v[202:205], v[16:19]
	v_mfma_f32_16x16x32_bf16 v[12:15], v[170:173], v[202:205], v[12:15]
	s_add_u32 s26, s26, 0x80000
	s_addc_u32 s27, s27, 0
	s_mov_b32 m0, s45
	s_nop 0
	global_load_lds_dwordx4 v138, s[26:27]
	s_mov_b32 m0, s46
	s_nop 0
	global_load_lds_dwordx4 v140, s[26:27]
	s_add_i32 s35, s35, 2
	s_add_u32 s24, s24, 0xffffff00
	s_addc_u32 s25, s25, -1
	s_add_u32 s59, s59, 0x100
	s_addc_u32 s60, s60, 0
	s_add_u32 s61, s61, 0x100
	s_addc_u32 s62, s62, 0
	s_add_u32 s63, s63, 0x100
	v_mfma_f32_16x16x32_bf16 v[56:59], v[206:209], v[174:177], v[56:59]
	s_addc_u32 s64, s64, 0
	s_add_u32 s65, s65, 0x100
	s_addc_u32 s66, s66, 0
	v_mfma_f32_16x16x32_bf16 v[52:55], v[214:217], v[174:177], v[52:55]
	s_add_u32 s67, s67, 0x100
	s_addc_u32 s68, s68, 0
	s_add_u32 s69, s69, 0x100
	v_mfma_f32_16x16x32_bf16 v[40:43], v[206:209], v[182:185], v[40:43]
	s_addc_u32 s70, s70, 0
	s_cmp_lt_u32 s35, 30
	v_mfma_f32_16x16x32_bf16 v[36:39], v[214:217], v[182:185], v[36:39]
	v_mfma_f32_16x16x32_bf16 v[24:27], v[206:209], v[190:193], v[24:27]
	v_mfma_f32_16x16x32_bf16 v[20:23], v[214:217], v[190:193], v[20:23]
	v_mfma_f32_16x16x32_bf16 v[8:11], v[206:209], v[198:201], v[8:11]
	v_mfma_f32_16x16x32_bf16 v[4:7], v[214:217], v[198:201], v[4:7]
	s_cbranch_scc1 .Lrt_119
; __device__ __forceinline__ unsigned cvt_pk_bf16(float lo, float hi) { unsigned r; asm volatile("v_cvt_pk_bf16_f32 %0, %1, %2" : "=v"(r) : "v"(lo), "v"(hi)); return r; }
; #define LAS __attribute__((address_space(3)))
; __device__ __forceinline__ float bflo(unsigned w) { return __uint_as_float(w << 16); }
; __device__ __forceinline__ float bfhi(unsigned w) { return __uint_as_float(w & 0xffff0000u); }
;     __device__ __forceinline__ void operator()(const f32x4 (&acc)[2][2][4][2], const Unit& u, int wr, int wc, int fr, int fq, const LAS float* rt) const {
;         const int row0 = u.pm * 256 + wr * 64 + fr, col0 = u.pn * 256 + wc * 32 + 8 * fq, lane = fq * 16 + fr;
; #pragma unroll
;         for (int ai = 0; ai < 2; ++ai)
; #pragma unroll
;             for (int m = 0; m < 4; ++m) { const size_t row = (size_t)(row0 + ai * 128 + m * 16); const float rs = (MODE == 1) ? rt[ai * 128 + wr * 64 + m * 16 + fr] : 1.0f; float ss = 0.f;
; #pragma unroll
;                 for (int bj = 0; bj < 2; ++bj) { const size_t o = row * DM + col0 + bj * 128; const u32x4 xv = *(const u32x4*)(xin + o);
;                     f32x4 v0 = acc[ai][bj][m][0], v1 = acc[ai][bj][m][1];
;                     if (MODE == 1) { const u32x4 p = *(const u32x4*)(pe + o);
;                         v0[0] = sigmoidf_(v0[0] * rs) * bflo(p.x); v0[1] = sigmoidf_(v0[1] * rs) * bfhi(p.x); v0[2] = sigmoidf_(v0[2] * rs) * bflo(p.y); v0[3] = sigmoidf_(v0[3] * rs) * bfhi(p.y);
;                         v1[0] = sigmoidf_(v1[0] * rs) * bflo(p.z); v1[1] = sigmoidf_(v1[1] * rs) * bfhi(p.z); v1[2] = sigmoidf_(v1[2] * rs) * bflo(p.w); v1[3] = sigmoidf_(v1[3] * rs) * bfhi(p.w); }
;                     v0[0] += bflo(xv.x); v0[1] += bfhi(xv.x); v0[2] += bflo(xv.y); v0[3] += bfhi(xv.y); v1[0] += bflo(xv.z); v1[1] += bfhi(xv.z); v1[2] += bflo(xv.w); v1[3] += bfhi(xv.w);
;                     ss += (v0[0] * v0[0] + v0[1] * v0[1]) + (v0[2] * v0[2] + v0[3] * v0[3]) + (v1[0] * v1[0] + v1[1] * v1[1]) + (v1[2] * v1[2] + v1[3] * v1[3]);
;                     u32x4 w; w.x = cvt_pk_bf16(v0[0], v0[1]); w.y = cvt_pk_bf16(v0[2], v0[3]); w.z = cvt_pk_bf16(v1[0], v1[1]); w.w = cvt_pk_bf16(v1[2], v1[3]);
;                     __builtin_nontemporal_store(w, (u32x4*)(xout + o)); }
;                 ss += shx(ss, 16, lane); ss += shx(ss, 32, lane);
;                 if (fq == 0) ssq_out[row * 32 + u.pn * 4 + wc] = ss; }
	v_mfma_f32_16x16x32_bf16 v[56:59], v[210:213], v[178:181], v[56:59]
	v_mfma_f32_16x16x32_bf16 v[52:55], v[218:221], v[178:181], v[52:55]
	v_mfma_f32_16x16x32_bf16 v[40:43], v[210:213], v[186:189], v[40:43]
	v_mfma_f32_16x16x32_bf16 v[36:39], v[218:221], v[186:189], v[36:39]
	v_mfma_f32_16x16x32_bf16 v[24:27], v[210:213], v[194:197], v[24:27]
	v_mfma_f32_16x16x32_bf16 v[20:23], v[218:221], v[194:197], v[20:23]
	v_mfma_f32_16x16x32_bf16 v[8:11], v[210:213], v[202:205], v[8:11]
	v_mfma_f32_16x16x32_bf16 v[4:7], v[218:221], v[202:205], v[4:7]
	v_mov_b32_e32 v132, v141
	s_lshl_b32 s5, s22, 8
	v_mbcnt_lo_u32_b32 v132, -1, v132
	v_mbcnt_hi_u32_b32 v135, -1, v132
	v_and_b32_e32 v136, 15, v135
	s_add_i32 s5, s5, s37
	v_or_b32_e32 v134, s5, v136
	s_lshl_b32 s5, s20, 8
	v_ashrrev_i32_e32 v137, 4, v135
	s_or_b32 s5, s5, s38
	v_lshl_add_u32 v132, v137, 3, s5
	v_lshlrev_b32_e32 v137, 6, v137
	v_lshlrev_b32_e32 v136, 2, v136
	s_movk_i32 s5, 0x80
	v_cmp_gt_u32_e32 vcc, 16, v135
	v_ashrrev_i32_e32 v135, 31, v134
	v_bitop3_b32 v156, v137, 64, v136 bitop3:0x36
	v_bitop3_b32 v155, v137, s5, v136 bitop3:0x36
	v_lshlrev_b64 v[136:137], 12, v[134:135]
	v_ashrrev_i32_e32 v133, 31, v132
	v_lshl_add_u64 v[136:137], s[94:95], 0, v[136:137]
	v_lshl_add_u64 v[136:137], v[132:133], 1, v[136:137]
	v_lshlrev_b32_e32 v236, 12, v134
	v_lshl_add_u32 v236, v132, 1, v236
	global_load_dwordx4 v[172:175], v236, s[94:95]
	global_load_dwordx4 v[176:179], v236, s[94:95] offset:256
	v_add_u32_e32 v237, 0x10000, v236
	global_load_dwordx4 v[180:183], v237, s[94:95]
	global_load_dwordx4 v[184:187], v237, s[94:95] offset:256
	v_add_u32_e32 v237, 0x20000, v236
	global_load_dwordx4 v[188:191], v237, s[94:95]
	global_load_dwordx4 v[192:195], v237, s[94:95] offset:256
	v_add_u32_e32 v237, 0x30000, v236
	global_load_dwordx4 v[196:199], v237, s[94:95]
	global_load_dwordx4 v[200:203], v237, s[94:95] offset:256
	v_add_u32_e32 v237, 0x80000, v236
	global_load_dwordx4 v[204:207], v237, s[94:95]
	global_load_dwordx4 v[208:211], v237, s[94:95] offset:256
	v_add_u32_e32 v237, 0x90000, v236
	global_load_dwordx4 v[212:215], v237, s[94:95]
	global_load_dwordx4 v[216:219], v237, s[94:95] offset:256
	v_add_u32_e32 v237, 0xa0000, v236
	global_load_dwordx4 v[220:223], v237, s[94:95]
	global_load_dwordx4 v[224:227], v237, s[94:95] offset:256
	v_add_u32_e32 v237, 0xb0000, v236
	global_load_dwordx4 v[228:231], v237, s[94:95]
	global_load_dwordx4 v[232:235], v237, s[94:95] offset:256
	s_lshl_b32 s20, s20, 2
	s_ashr_i32 s21, s20, 31
	s_waitcnt vmcnt(15)
	s_nop 1
	v_mov_b64_e32 v[146:147], v[172:173]
	v_mov_b64_e32 v[148:149], v[174:175]
	v_lshlrev_b32_e32 v142, 16, v146
	v_add_f32_e32 v128, v128, v142
	v_and_b32_e32 v142, 0xffff0000, v146
	v_add_f32_e32 v129, v129, v142
	v_lshlrev_b32_e32 v142, 16, v147
	v_add_f32_e32 v130, v130, v142
	v_and_b32_e32 v142, 0xffff0000, v147
	v_add_f32_e32 v131, v131, v142
	v_lshlrev_b32_e32 v142, 16, v148
	v_add_f32_e32 v142, v124, v142
	v_and_b32_e32 v124, 0xffff0000, v148
	v_add_f32_e32 v143, v125, v124
	v_lshlrev_b32_e32 v124, 16, v149
	v_add_f32_e32 v144, v126, v124
	v_and_b32_e32 v124, 0xffff0000, v149
	v_add_f32_e32 v127, v127, v124
	v_mul_f32_e32 v124, v129, v129
	v_mul_f32_e32 v125, v131, v131
	v_fmac_f32_e32 v124, v128, v128
	v_fmac_f32_e32 v125, v130, v130
	v_add_f32_e32 v124, v124, v125
	v_mul_f32_e32 v125, v143, v143
	v_fmac_f32_e32 v125, v142, v142
	v_add_f32_e32 v124, v125, v124
	v_mul_f32_e32 v125, v127, v127
	v_fmac_f32_e32 v125, v144, v144
	v_add_f32_e32 v145, v125, v124
	v_cvt_pk_bf16_f32 v124, v128, v129
	v_cvt_pk_bf16_f32 v125, v130, v131
	v_cvt_pk_bf16_f32 v126, v142, v143
	v_cvt_pk_bf16_f32 v127, v144, v127
	global_store_dwordx4 v[136:137], v[124:127], off nt
	s_waitcnt vmcnt(15)
	s_nop 1
	v_mov_b64_e32 v[124:125], v[176:177]
	v_mov_b64_e32 v[126:127], v[178:179]
	v_lshlrev_b32_e32 v128, 16, v124
	v_and_b32_e32 v124, 0xffff0000, v124
	v_add_f32_e32 v121, v121, v124
	v_lshlrev_b32_e32 v124, 16, v125
	v_add_f32_e32 v122, v122, v124
	v_and_b32_e32 v124, 0xffff0000, v125
	v_add_f32_e32 v123, v123, v124
	v_lshlrev_b32_e32 v124, 16, v126
	v_add_f32_e32 v124, v116, v124
	v_and_b32_e32 v116, 0xffff0000, v126
	v_add_f32_e32 v125, v117, v116
	v_lshlrev_b32_e32 v116, 16, v127
	v_add_f32_e32 v126, v118, v116
	v_and_b32_e32 v116, 0xffff0000, v127
	v_add_f32_e32 v120, v120, v128
	v_add_f32_e32 v119, v119, v116
	v_mul_f32_e32 v116, v121, v121
	v_mul_f32_e32 v117, v123, v123
	v_fmac_f32_e32 v116, v120, v120
	v_fmac_f32_e32 v117, v122, v122
	v_add_f32_e32 v116, v116, v117
	v_mul_f32_e32 v117, v125, v125
	v_fmac_f32_e32 v117, v124, v124
	v_add_f32_e32 v116, v117, v116
	v_mul_f32_e32 v117, v119, v119
	v_fmac_f32_e32 v117, v126, v126
	v_add_f32_e32 v116, v117, v116
	v_add_f32_e32 v127, v145, v116
	v_cvt_pk_bf16_f32 v116, v120, v121
	v_cvt_pk_bf16_f32 v117, v122, v123
	v_cvt_pk_bf16_f32 v118, v124, v125
	v_cvt_pk_bf16_f32 v119, v126, v119
	global_store_dwordx4 v[136:137], v[116:119], off offset:256 nt
	ds_bpermute_b32 v116, v156, v127
	s_waitcnt lgkmcnt(0)
	v_add_f32_e32 v116, v127, v116
	ds_bpermute_b32 v117, v155, v116
	s_and_saveexec_b64 s[22:23], vcc
	s_cbranch_execz .LBB0_122
	v_lshlrev_b64 v[118:119], 7, v[134:135]
	v_lshl_add_u64 v[118:119], s[0:1], 0, v[118:119]
	v_lshl_add_u64 v[118:119], s[20:21], 2, v[118:119]
	s_lshl_b32 s84, s36, 2
	v_lshl_add_u64 v[118:119], v[118:119], 0, s[84:85]
	s_waitcnt lgkmcnt(0)
	v_add_f32_e32 v116, v116, v117
	global_store_dword v[118:119], v116, off

; template <class Epi, class Sched>
; __device__ __forceinline__ void gemm_simple(PG8_LAS unsigned char* lds, const Gemm g, const Sched& S, const Epi& E, int wave_s) {
;     ...
;         const bool has_next = S.next(ui + 1, nxt);
;         const char* nA = has_next ? (const char*)g.A + (size_t)nxt.pm * tstep : cA; const char* nB = has_next ? (const char*)g.Bt + (size_t)nxt.pn * tstep : cB;
;         int t = 0;
;         if (ui > 0) {
;             if constexpr (Epi::NST >= 16) PG8_TILE_W(0, cA + kstep, cB + kstep, "18", "20"); else PG8_TILE_W(0, cA + kstep, cB + kstep, "10", "12");
;             PG8_TILE_W(1, cA + 2 * kstep, cB + 2 * kstep, "2", "4");
;             t = 2;
;         }
;         for (; t < nt; t += 2) {
;             const bool last = (t == nt - 2);
;             PG8_TILE(0, cA + (size_t)(t + 1) * kstep, cB + (size_t)(t + 1) * kstep, true);
;             const char* a2 = last ? nA : cA + (size_t)(t + 2) * kstep; const char* b2 = last ? nB : cB + (size_t)(t + 2) * kstep;
;             PG8_TILE(1, a2, b2, (!last || has_next));
.LBB0_172:
	s_ashr_i32 s9, s8, 31
	s_lshl_b64 s[10:11], s[8:9], 19
	v_readlane_b32 s16, v255, 4
	v_readlane_b32 s17, v255, 5
	s_add_u32 s10, s16, s10
	s_addc_u32 s11, s17, s11
	s_and_b64 s[16:17], vcc, exec
	s_cselect_b32 s9, s11, s23
	s_cselect_b32 s56, s10, s22
	s_ashr_i32 s5, s4, 31
	s_lshl_b64 s[16:17], s[4:5], 19
	s_add_u32 s16, s29, s16
	s_addc_u32 s17, s36, s17
	s_and_b64 s[26:27], vcc, exec
	s_cselect_b32 s5, s17, s21
	s_cselect_b32 s57, s16, s20
	s_add_i32 s58, s24, -2
	s_lshl_b32 s59, s24, 7
	s_mov_b64 s[24:25], 0x700
	s_branch .Lrt_top_173
.Lrt_173:
	v_mfma_f32_16x16x32_bf16 v[56:59], v[210:213], v[178:181], v[56:59]
	v_mfma_f32_16x16x32_bf16 v[52:55], v[218:221], v[178:181], v[52:55]
	v_mfma_f32_16x16x32_bf16 v[40:43], v[210:213], v[186:189], v[40:43]
	v_mfma_f32_16x16x32_bf16 v[36:39], v[218:221], v[186:189], v[36:39]
	v_mfma_f32_16x16x32_bf16 v[24:27], v[210:213], v[194:197], v[24:27]
	v_mfma_f32_16x16x32_bf16 v[20:23], v[218:221], v[194:197], v[20:23]
	v_mfma_f32_16x16x32_bf16 v[4:7], v[210:213], v[202:205], v[4:7]
	v_mfma_f32_16x16x32_bf16 v[8:11], v[218:221], v[202:205], v[8:11]
.Lrt_top_173:
.LBB0_173:
	s_waitcnt vmcnt(2) lgkmcnt(0)
	s_barrier
	ds_read_b128 v[146:149], v132
	ds_read_b128 v[174:177], v152
	ds_read_b128 v[158:161], v132 offset:2048
	ds_read_b128 v[182:185], v152 offset:2048
	ds_read_b128 v[190:193], v152 offset:4096
	s_add_u32 s60, s20, s59
	s_addc_u32 s61, s21, 0
	s_add_u32 s26, s60, 0x80
	s_addc_u32 s27, s61, 0
	s_mov_b32 m0, s46
	s_nop 0
	global_load_lds_dwordx4 v137, s[26:27]
	s_mov_b32 m0, s50
	s_nop 0
	global_load_lds_dwordx4 v139, s[26:27]
	s_waitcnt lgkmcnt(3)
	v_mfma_f32_16x16x32_bf16 v[128:131], v[146:149], v[174:177], v[128:131]
	s_waitcnt lgkmcnt(2)
	v_mfma_f32_16x16x32_bf16 v[124:127], v[158:161], v[174:177], v[124:127]
	ds_read_b128 v[198:201], v152 offset:6144
	s_waitcnt lgkmcnt(2)
	v_mfma_f32_16x16x32_bf16 v[112:115], v[146:149], v[182:185], v[112:115]
	v_mfma_f32_16x16x32_bf16 v[108:111], v[158:161], v[182:185], v[108:111]
	ds_read_b128 v[154:157], v132 offset:1024
	ds_read_b128 v[178:181], v152 offset:1024
	s_waitcnt lgkmcnt(3)
	v_mfma_f32_16x16x32_bf16 v[96:99], v[146:149], v[190:193], v[96:99]
	ds_read_b128 v[170:173], v132 offset:3072
	v_mfma_f32_16x16x32_bf16 v[92:95], v[158:161], v[190:193], v[92:95]
	ds_read_b128 v[186:189], v152 offset:3072
	s_waitcnt lgkmcnt(4)
	v_mfma_f32_16x16x32_bf16 v[80:83], v[146:149], v[198:201], v[80:83]
	v_mfma_f32_16x16x32_bf16 v[76:79], v[158:161], v[198:201], v[76:79]
	ds_read_b128 v[194:197], v152 offset:5120
	s_waitcnt lgkmcnt(3)
	v_mfma_f32_16x16x32_bf16 v[128:131], v[154:157], v[178:181], v[128:131]
	s_waitcnt lgkmcnt(2)
	v_mfma_f32_16x16x32_bf16 v[124:127], v[170:173], v[178:181], v[124:127]
	ds_read_b128 v[202:205], v152 offset:7168
	s_waitcnt lgkmcnt(2)
	v_mfma_f32_16x16x32_bf16 v[112:115], v[154:157], v[186:189], v[112:115]
	v_mfma_f32_16x16x32_bf16 v[108:111], v[170:173], v[186:189], v[108:111]
	ds_read_b128 v[206:209], v133
	s_waitcnt lgkmcnt(2)
	v_mfma_f32_16x16x32_bf16 v[96:99], v[154:157], v[194:197], v[96:99]
	ds_read_b128 v[214:217], v133 offset:2048
	v_mfma_f32_16x16x32_bf16 v[92:95], v[170:173], v[194:197], v[92:95]
	s_waitcnt lgkmcnt(2)
	v_mfma_f32_16x16x32_bf16 v[80:83], v[154:157], v[202:205], v[80:83]
	v_mfma_f32_16x16x32_bf16 v[76:79], v[170:173], v[202:205], v[76:79]
	s_add_u32 s62, s22, s59
	s_addc_u32 s63, s23, 0
	s_add_u32 s26, s62, 0x80
	s_addc_u32 s27, s63, 0
	s_mov_b32 m0, s47
	s_nop 0
	global_load_lds_dwordx4 v136, s[26:27]
	s_mov_b32 m0, s51
	s_nop 0
	global_load_lds_dwordx4 v138, s[26:27]
	s_waitcnt lgkmcnt(1)
	v_mfma_f32_16x16x32_bf16 v[120:123], v[206:209], v[174:177], v[120:123]
	s_waitcnt lgkmcnt(0)
	v_mfma_f32_16x16x32_bf16 v[116:119], v[214:217], v[174:177], v[116:119]
	v_mfma_f32_16x16x32_bf16 v[104:107], v[206:209], v[182:185], v[104:107]
	v_mfma_f32_16x16x32_bf16 v[100:103], v[214:217], v[182:185], v[100:103]
	ds_read_b128 v[210:213], v133 offset:1024
	v_mfma_f32_16x16x32_bf16 v[88:91], v[206:209], v[190:193], v[88:91]
	ds_read_b128 v[218:221], v133 offset:3072
	v_mfma_f32_16x16x32_bf16 v[84:87], v[214:217], v[190:193], v[84:87]
	v_mfma_f32_16x16x32_bf16 v[72:75], v[206:209], v[198:201], v[72:75]
	v_mfma_f32_16x16x32_bf16 v[68:71], v[214:217], v[198:201], v[68:71]
	s_waitcnt lgkmcnt(1)
	v_mfma_f32_16x16x32_bf16 v[120:123], v[210:213], v[178:181], v[120:123]
	s_waitcnt lgkmcnt(0)
	v_mfma_f32_16x16x32_bf16 v[116:119], v[218:221], v[178:181], v[116:119]
	v_mfma_f32_16x16x32_bf16 v[104:107], v[210:213], v[186:189], v[104:107]
	v_mfma_f32_16x16x32_bf16 v[100:103], v[218:221], v[186:189], v[100:103]
	v_mfma_f32_16x16x32_bf16 v[88:91], v[210:213], v[194:197], v[88:91]
	v_mfma_f32_16x16x32_bf16 v[84:87], v[218:221], v[194:197], v[84:87]
	v_mfma_f32_16x16x32_bf16 v[72:75], v[210:213], v[202:205], v[72:75]
	v_mfma_f32_16x16x32_bf16 v[68:71], v[218:221], v[202:205], v[68:71]
	s_waitcnt vmcnt(4) lgkmcnt(0)
	s_barrier
; template <class Epi, class Sched>
; __device__ __forceinline__ void gemm_simple(PG8_LAS unsigned char* lds, const Gemm g, const Sched& S, const Epi& E, int wave_s) {
;     ...
;         for (; t < nt; t += 2) {
;             const bool last = (t == nt - 2);
;             PG8_TILE(0, cA + (size_t)(t + 1) * kstep, cB + (size_t)(t + 1) * kstep, true);
;             const char* a2 = last ? nA : cA + (size_t)(t + 2) * kstep; const char* b2 = last ? nB : cB + (size_t)(t + 2) * kstep;
;             PG8_TILE(1, a2, b2, (!last || has_next));
	ds_read_b128 v[174:177], v152 offset:16384
	ds_read_b128 v[182:185], v152 offset:18432
	ds_read_b128 v[190:193], v152 offset:20480
	s_add_u32 s26, s60, 0x40080
	s_addc_u32 s27, s61, 0
	s_mov_b32 m0, s48
	s_nop 0
	global_load_lds_dwordx4 v137, s[26:27]
	s_mov_b32 m0, s52
	s_nop 0
	global_load_lds_dwordx4 v139, s[26:27]
	s_waitcnt lgkmcnt(2)
	v_mfma_f32_16x16x32_bf16 v[64:67], v[146:149], v[174:177], v[64:67]
	v_mfma_f32_16x16x32_bf16 v[60:63], v[158:161], v[174:177], v[60:63]
	ds_read_b128 v[198:201], v152 offset:22528
	s_waitcnt lgkmcnt(2)
	v_mfma_f32_16x16x32_bf16 v[48:51], v[146:149], v[182:185], v[48:51]
	v_mfma_f32_16x16x32_bf16 v[44:47], v[158:161], v[182:185], v[44:47]
	ds_read_b128 v[178:181], v152 offset:17408
	s_waitcnt lgkmcnt(2)
	v_mfma_f32_16x16x32_bf16 v[32:35], v[146:149], v[190:193], v[32:35]
	v_mfma_f32_16x16x32_bf16 v[28:31], v[158:161], v[190:193], v[28:31]
	ds_read_b128 v[186:189], v152 offset:19456
	s_waitcnt lgkmcnt(2)
	v_mfma_f32_16x16x32_bf16 v[16:19], v[146:149], v[198:201], v[16:19]
	v_mfma_f32_16x16x32_bf16 v[12:15], v[158:161], v[198:201], v[12:15]
	ds_read_b128 v[194:197], v152 offset:21504
	s_waitcnt lgkmcnt(2)
	v_mfma_f32_16x16x32_bf16 v[64:67], v[154:157], v[178:181], v[64:67]
	v_mfma_f32_16x16x32_bf16 v[60:63], v[170:173], v[178:181], v[60:63]
	ds_read_b128 v[202:205], v152 offset:23552
	s_waitcnt lgkmcnt(2)
	v_mfma_f32_16x16x32_bf16 v[48:51], v[154:157], v[186:189], v[48:51]
	v_mfma_f32_16x16x32_bf16 v[44:47], v[170:173], v[186:189], v[44:47]
	s_waitcnt lgkmcnt(1)
	v_mfma_f32_16x16x32_bf16 v[32:35], v[154:157], v[194:197], v[32:35]
	v_mfma_f32_16x16x32_bf16 v[28:31], v[170:173], v[194:197], v[28:31]
	s_waitcnt lgkmcnt(0)
	v_mfma_f32_16x16x32_bf16 v[16:19], v[154:157], v[202:205], v[16:19]
	v_mfma_f32_16x16x32_bf16 v[12:15], v[170:173], v[202:205], v[12:15]
	s_add_u32 s26, s62, 0x40080
	s_addc_u32 s27, s63, 0
	s_mov_b32 m0, s49
	s_nop 0
	global_load_lds_dwordx4 v136, s[26:27]
	s_mov_b32 m0, s53
	s_nop 0
	global_load_lds_dwordx4 v138, s[26:27]
	v_mfma_f32_16x16x32_bf16 v[56:59], v[206:209], v[174:177], v[56:59]
	s_add_u32 s26, s62, 0x100
	s_addc_u32 s27, s63, 0
	s_add_u32 s60, s60, 0x100
	v_mfma_f32_16x16x32_bf16 v[52:55], v[214:217], v[174:177], v[52:55]
	s_addc_u32 s61, s61, 0
	v_mfma_f32_16x16x32_bf16 v[40:43], v[206:209], v[182:185], v[40:43]
	v_mfma_f32_16x16x32_bf16 v[36:39], v[214:217], v[182:185], v[36:39]
	v_mfma_f32_16x16x32_bf16 v[24:27], v[206:209], v[190:193], v[24:27]
	v_mfma_f32_16x16x32_bf16 v[20:23], v[214:217], v[190:193], v[20:23]
	v_mfma_f32_16x16x32_bf16 v[4:7], v[206:209], v[198:201], v[4:7]
	v_mfma_f32_16x16x32_bf16 v[8:11], v[214:217], v[198:201], v[8:11]
	v_mfma_f32_16x16x32_bf16 v[56:59], v[210:213], v[178:181], v[56:59]
	v_mfma_f32_16x16x32_bf16 v[52:55], v[218:221], v[178:181], v[52:55]
	v_mfma_f32_16x16x32_bf16 v[40:43], v[210:213], v[186:189], v[40:43]
	v_mfma_f32_16x16x32_bf16 v[36:39], v[218:221], v[186:189], v[36:39]
	v_mfma_f32_16x16x32_bf16 v[24:27], v[210:213], v[194:197], v[24:27]
	v_mfma_f32_16x16x32_bf16 v[20:23], v[218:221], v[194:197], v[20:23]
	v_mfma_f32_16x16x32_bf16 v[4:7], v[210:213], v[202:205], v[4:7]
	v_mfma_f32_16x16x32_bf16 v[8:11], v[218:221], v[202:205], v[8:11]
	s_waitcnt vmcnt(2) lgkmcnt(0)
	s_barrier
	ds_read_b128 v[146:149], v134
	ds_read_b128 v[174:177], v152 offset:32768
	ds_read_b128 v[158:161], v134 offset:2048
	ds_read_b128 v[182:185], v152 offset:34816
	ds_read_b128 v[190:193], v152 offset:36864
	s_cmp_eq_u32 s59, s24
	s_cselect_b32 s27, s9, s27
	s_cselect_b32 s26, s56, s26
	s_cselect_b32 s61, s5, s61
	s_cselect_b32 s60, s57, s60
	s_mov_b32 m0, s39
	s_nop 0
	global_load_lds_dwordx4 v137, s[60:61]
	s_mov_b32 m0, s40
	s_nop 0
	global_load_lds_dwordx4 v139, s[60:61]
	s_waitcnt lgkmcnt(3)
	v_mfma_f32_16x16x32_bf16 v[128:131], v[146:149], v[174:177], v[128:131]
	s_waitcnt lgkmcnt(2)
	v_mfma_f32_16x16x32_bf16 v[124:127], v[158:161], v[174:177], v[124:127]
	ds_read_b128 v[198:201], v152 offset:38912
	s_waitcnt lgkmcnt(2)
	v_mfma_f32_16x16x32_bf16 v[112:115], v[146:149], v[182:185], v[112:115]
	v_mfma_f32_16x16x32_bf16 v[108:111], v[158:161], v[182:185], v[108:111]
	ds_read_b128 v[154:157], v134 offset:1024
	ds_read_b128 v[178:181], v152 offset:33792
	s_waitcnt lgkmcnt(3)
	v_mfma_f32_16x16x32_bf16 v[96:99], v[146:149], v[190:193], v[96:99]
	ds_read_b128 v[170:173], v134 offset:3072
	v_mfma_f32_16x16x32_bf16 v[92:95], v[158:161], v[190:193], v[92:95]
	ds_read_b128 v[186:189], v152 offset:35840
	s_waitcnt lgkmcnt(4)
	v_mfma_f32_16x16x32_bf16 v[80:83], v[146:149], v[198:201], v[80:83]
	v_mfma_f32_16x16x32_bf16 v[76:79], v[158:161], v[198:201], v[76:79]
	ds_read_b128 v[194:197], v152 offset:37888
	s_waitcnt lgkmcnt(3)
	v_mfma_f32_16x16x32_bf16 v[128:131], v[154:157], v[178:181], v[128:131]
	s_waitcnt lgkmcnt(2)
	v_mfma_f32_16x16x32_bf16 v[124:127], v[170:173], v[178:181], v[124:127]
	ds_read_b128 v[202:205], v152 offset:39936
	s_waitcnt lgkmcnt(2)
	v_mfma_f32_16x16x32_bf16 v[112:115], v[154:157], v[186:189], v[112:115]
	v_mfma_f32_16x16x32_bf16 v[108:111], v[170:173], v[186:189], v[108:111]
	ds_read_b128 v[206:209], v135
	s_waitcnt lgkmcnt(2)
	v_mfma_f32_16x16x32_bf16 v[96:99], v[154:157], v[194:197], v[96:99]
	ds_read_b128 v[214:217], v135 offset:2048
	v_mfma_f32_16x16x32_bf16 v[92:95], v[170:173], v[194:197], v[92:95]
	s_waitcnt lgkmcnt(2)
	v_mfma_f32_16x16x32_bf16 v[80:83], v[154:157], v[202:205], v[80:83]
	v_mfma_f32_16x16x32_bf16 v[76:79], v[170:173], v[202:205], v[76:79]
	s_mov_b32 m0, s19
	s_nop 0
	global_load_lds_dwordx4 v136, s[26:27]
	s_mov_b32 m0, s41
	s_nop 0
	global_load_lds_dwordx4 v138, s[26:27]
	s_waitcnt lgkmcnt(1)
	v_mfma_f32_16x16x32_bf16 v[120:123], v[206:209], v[174:177], v[120:123]
	s_waitcnt lgkmcnt(0)
	v_mfma_f32_16x16x32_bf16 v[116:119], v[214:217], v[174:177], v[116:119]
	v_mfma_f32_16x16x32_bf16 v[104:107], v[206:209], v[182:185], v[104:107]
	v_mfma_f32_16x16x32_bf16 v[100:103], v[214:217], v[182:185], v[100:103]
	ds_read_b128 v[210:213], v135 offset:1024
	v_mfma_f32_16x16x32_bf16 v[88:91], v[206:209], v[190:193], v[88:91]
	ds_read_b128 v[218:221], v135 offset:3072
	v_mfma_f32_16x16x32_bf16 v[84:87], v[214:217], v[190:193], v[84:87]
	v_mfma_f32_16x16x32_bf16 v[72:75], v[206:209], v[198:201], v[72:75]
	v_mfma_f32_16x16x32_bf16 v[68:71], v[214:217], v[198:201], v[68:71]
	s_waitcnt lgkmcnt(1)
	v_mfma_f32_16x16x32_bf16 v[120:123], v[210:213], v[178:181], v[120:123]
	s_waitcnt lgkmcnt(0)
	v_mfma_f32_16x16x32_bf16 v[116:119], v[218:221], v[178:181], v[116:119]
	v_mfma_f32_16x16x32_bf16 v[104:107], v[210:213], v[186:189], v[104:107]
	v_mfma_f32_16x16x32_bf16 v[100:103], v[218:221], v[186:189], v[100:103]
	v_mfma_f32_16x16x32_bf16 v[88:91], v[210:213], v[194:197], v[88:91]
	v_mfma_f32_16x16x32_bf16 v[84:87], v[218:221], v[194:197], v[84:87]
	v_mfma_f32_16x16x32_bf16 v[72:75], v[210:213], v[202:205], v[72:75]
	v_mfma_f32_16x16x32_bf16 v[68:71], v[218:221], v[202:205], v[68:71]
	s_waitcnt vmcnt(4) lgkmcnt(0)
	s_barrier
; __device__ __forceinline__ unsigned cvt_pk_bf16(float lo, float hi) { unsigned r; asm volatile("v_cvt_pk_bf16_f32 %0, %1, %2" : "=v"(r) : "v"(lo), "v"(hi)); return r; }
; #define LAS __attribute__((address_space(3)))
; __device__ __forceinline__ float bflo(unsigned w) { return __uint_as_float(w << 16); }
; __device__ __forceinline__ float bfhi(unsigned w) { return __uint_as_float(w & 0xffff0000u); }
; template <class Epi, class Sched>
; __device__ __forceinline__ void gemm_simple(PG8_LAS unsigned char* lds, const Gemm g, const Sched& S, const Epi& E, int wave_s) {
;     ...
;         for (; t < nt; t += 2) {
;             const bool last = (t == nt - 2);
;             PG8_TILE(0, cA + (size_t)(t + 1) * kstep, cB + (size_t)(t + 1) * kstep, true);
;             const char* a2 = last ? nA : cA + (size_t)(t + 2) * kstep; const char* b2 = last ? nB : cB + (size_t)(t + 2) * kstep;
;             PG8_TILE(1, a2, b2, (!last || has_next));
;     __device__ __forceinline__ void operator()(const f32x4 (&acc)[2][2][4][2], const Unit& u, int wr, int wc, int fr, int fq, const LAS float*) const {
;         const int row0 = u.pm * 256 + wr * 64 + fr, col0 = u.pn * 256 + wc * 32 + 8 * fq;
; #pragma unroll
;         for (int ai = 0; ai < 2; ++ai)
; #pragma unroll
;             for (int m = 0; m < 4; ++m) { const size_t row = (size_t)(row0 + ai * 128 + m * 16);
; #pragma unroll
;                 for (int bj = 0; bj < 2; ++bj) { const int col = col0 + bj * 128;
;                     const u32x4 g = *(const u32x4*)(G + row * NGATE + MODE * DM + col);
;                     f32x4 v0 = acc[ai][bj][m][0], v1 = acc[ai][bj][m][1];
;                     v0[0] *= bflo(g.x); v0[1] *= bfhi(g.x); v0[2] *= bflo(g.y); v0[3] *= bfhi(g.y); v1[0] *= bflo(g.z); v1[1] *= bfhi(g.z); v1[2] *= bflo(g.w); v1[3] *= bfhi(g.w);
;                     bf16_t* tp = T + row * DM + col;
;                     if (MODE == 1) { const u32x4 t = *(const u32x4*)tp;
;                         v0[0] += bflo(t.x); v0[1] += bfhi(t.x); v0[2] += bflo(t.y); v0[3] += bfhi(t.y); v1[0] += bflo(t.z); v1[1] += bfhi(t.z); v1[2] += bflo(t.w); v1[3] += bfhi(t.w); }
;                     u32x4 w; w.x = cvt_pk_bf16(v0[0], v0[1]); w.y = cvt_pk_bf16(v0[2], v0[3]); w.z = cvt_pk_bf16(v1[0], v1[1]); w.w = cvt_pk_bf16(v1[2], v1[3]);
;                     *(u32x4*)tp = w; } }
	ds_read_b128 v[174:177], v152 offset:49152
	ds_read_b128 v[182:185], v152 offset:51200
	ds_read_b128 v[190:193], v152 offset:53248
	s_add_u32 s60, s60, 0x40000
	s_addc_u32 s61, s61, 0
	s_mov_b32 m0, s42
	s_nop 0
	global_load_lds_dwordx4 v137, s[60:61]
	s_mov_b32 m0, s43
	s_nop 0
	global_load_lds_dwordx4 v139, s[60:61]
	s_waitcnt lgkmcnt(2)
	v_mfma_f32_16x16x32_bf16 v[64:67], v[146:149], v[174:177], v[64:67]
	v_mfma_f32_16x16x32_bf16 v[60:63], v[158:161], v[174:177], v[60:63]
	ds_read_b128 v[198:201], v152 offset:55296
	s_waitcnt lgkmcnt(2)
	v_mfma_f32_16x16x32_bf16 v[48:51], v[146:149], v[182:185], v[48:51]
	v_mfma_f32_16x16x32_bf16 v[44:47], v[158:161], v[182:185], v[44:47]
	ds_read_b128 v[178:181], v152 offset:50176
	s_waitcnt lgkmcnt(2)
	v_mfma_f32_16x16x32_bf16 v[32:35], v[146:149], v[190:193], v[32:35]
	v_mfma_f32_16x16x32_bf16 v[28:31], v[158:161], v[190:193], v[28:31]
	ds_read_b128 v[186:189], v152 offset:52224
	s_waitcnt lgkmcnt(2)
	v_mfma_f32_16x16x32_bf16 v[16:19], v[146:149], v[198:201], v[16:19]
	v_mfma_f32_16x16x32_bf16 v[12:15], v[158:161], v[198:201], v[12:15]
	ds_read_b128 v[194:197], v152 offset:54272
	s_waitcnt lgkmcnt(2)
	v_mfma_f32_16x16x32_bf16 v[64:67], v[154:157], v[178:181], v[64:67]
	v_mfma_f32_16x16x32_bf16 v[60:63], v[170:173], v[178:181], v[60:63]
	ds_read_b128 v[202:205], v152 offset:56320
	s_waitcnt lgkmcnt(2)
	v_mfma_f32_16x16x32_bf16 v[48:51], v[154:157], v[186:189], v[48:51]
	v_mfma_f32_16x16x32_bf16 v[44:47], v[170:173], v[186:189], v[44:47]
	s_waitcnt lgkmcnt(1)
	v_mfma_f32_16x16x32_bf16 v[32:35], v[154:157], v[194:197], v[32:35]
	v_mfma_f32_16x16x32_bf16 v[28:31], v[170:173], v[194:197], v[28:31]
	s_waitcnt lgkmcnt(0)
	v_mfma_f32_16x16x32_bf16 v[16:19], v[154:157], v[202:205], v[16:19]
	v_mfma_f32_16x16x32_bf16 v[12:15], v[170:173], v[202:205], v[12:15]
	s_add_u32 s26, s26, 0x40000
	s_addc_u32 s27, s27, 0
	s_mov_b32 m0, s44
	s_nop 0
	global_load_lds_dwordx4 v136, s[26:27]
	s_mov_b32 m0, s45
	s_nop 0
	global_load_lds_dwordx4 v138, s[26:27]
	v_mfma_f32_16x16x32_bf16 v[56:59], v[206:209], v[174:177], v[56:59]
	s_add_i32 s58, s58, 2
	s_add_u32 s24, s24, 0xffffff00
	s_addc_u32 s25, s25, -1
	v_mfma_f32_16x16x32_bf16 v[52:55], v[214:217], v[174:177], v[52:55]
	s_add_u32 s20, s20, 0x100
	s_addc_u32 s21, s21, 0
	s_add_u32 s22, s22, 0x100
	v_mfma_f32_16x16x32_bf16 v[40:43], v[206:209], v[182:185], v[40:43]
	s_addc_u32 s23, s23, 0
	s_cmp_lt_u32 s58, 14
	v_mfma_f32_16x16x32_bf16 v[36:39], v[214:217], v[182:185], v[36:39]
	v_mfma_f32_16x16x32_bf16 v[24:27], v[206:209], v[190:193], v[24:27]
	v_mfma_f32_16x16x32_bf16 v[20:23], v[214:217], v[190:193], v[20:23]
	v_mfma_f32_16x16x32_bf16 v[4:7], v[206:209], v[198:201], v[4:7]
	v_mfma_f32_16x16x32_bf16 v[8:11], v[214:217], v[198:201], v[8:11]
	s_cbranch_scc1 .Lrt_173
	v_mfma_f32_16x16x32_bf16 v[56:59], v[210:213], v[178:181], v[56:59]
	v_mfma_f32_16x16x32_bf16 v[52:55], v[218:221], v[178:181], v[52:55]
	v_mfma_f32_16x16x32_bf16 v[40:43], v[210:213], v[186:189], v[40:43]
	v_mfma_f32_16x16x32_bf16 v[36:39], v[218:221], v[186:189], v[36:39]
	v_mfma_f32_16x16x32_bf16 v[24:27], v[210:213], v[194:197], v[24:27]
	v_mfma_f32_16x16x32_bf16 v[20:23], v[218:221], v[194:197], v[20:23]
	v_mfma_f32_16x16x32_bf16 v[4:7], v[210:213], v[202:205], v[4:7]
	v_mfma_f32_16x16x32_bf16 v[8:11], v[218:221], v[202:205], v[8:11]
	v_mov_b32_e32 v132, v141
	s_lshl_b32 s5, s18, 8
	v_mbcnt_lo_u32_b32 v132, -1, v132
	v_mbcnt_hi_u32_b32 v132, -1, v132
	s_add_i32 s5, s5, s37
	v_and_or_b32 v134, v132, 15, s5
	s_lshl_b32 s5, s35, 8
	v_ashrrev_i32_e32 v132, 1, v132
	s_or_b32 s5, s5, s38
	v_and_b32_e32 v132, -8, v132
	v_add_u32_e32 v132, s5, v132
	v_ashrrev_i32_e32 v135, 31, v134
	v_lshlrev_b64 v[142:143], 13, v[134:135]
	v_ashrrev_i32_e32 v133, 31, v132
	v_lshl_add_u64 v[142:143], s[2:3], 0, v[142:143]
	v_lshlrev_b64 v[132:133], 1, v[132:133]
	v_lshl_add_u64 v[142:143], v[142:143], 0, v[132:133]
	s_mov_b64 s[20:21], 0x1000
	v_lshl_add_u64 v[154:155], v[142:143], 0, s[20:21]
	v_add_co_u32_e32 v142, vcc, s76, v142
	v_lshlrev_b64 v[144:145], 12, v[134:135]
	s_nop 0
	v_addc_co_u32_e32 v143, vcc, 0, v143, vcc
	v_lshlrev_b32_e32 v236, 13, v134
	v_add_u32_e32 v236, v236, v132
	v_add_u32_e32 v236, 0x1000, v236
	v_lshlrev_b32_e32 v238, 12, v134
	v_add_u32_e32 v238, v238, v132
	global_load_dwordx4 v[172:175], v236, s[2:3]
	global_load_dwordx4 v[176:179], v238, s[12:13]
	global_load_dwordx4 v[180:183], v236, s[2:3] offset:256
	global_load_dwordx4 v[184:187], v238, s[12:13] offset:256
	v_add_u32_e32 v237, 0x20000, v236
	v_add_u32_e32 v239, 0x10000, v238
	global_load_dwordx4 v[188:191], v237, s[2:3]
	global_load_dwordx4 v[192:195], v239, s[12:13]
	global_load_dwordx4 v[196:199], v237, s[2:3] offset:256
	global_load_dwordx4 v[200:203], v239, s[12:13] offset:256
	v_add_u32_e32 v237, 0x40000, v236
	v_add_u32_e32 v239, 0x20000, v238
	global_load_dwordx4 v[204:207], v237, s[2:3]
	global_load_dwordx4 v[208:211], v239, s[12:13]
	global_load_dwordx4 v[212:215], v237, s[2:3] offset:256
	global_load_dwordx4 v[216:219], v239, s[12:13] offset:256
	v_add_u32_e32 v237, 0x60000, v236
	v_add_u32_e32 v239, 0x30000, v238
	global_load_dwordx4 v[220:223], v237, s[2:3]
	global_load_dwordx4 v[224:227], v239, s[12:13]
	global_load_dwordx4 v[228:231], v237, s[2:3] offset:256
	global_load_dwordx4 v[232:235], v239, s[12:13] offset:256
	v_lshl_add_u64 v[142:143], s[12:13], 0, v[144:145]
	v_lshl_add_u64 v[142:143], v[142:143], 0, v[132:133]
	s_mov_b32 s35, s4
	s_mov_b32 s18, s8
	s_mov_b64 s[22:23], s[10:11]
	s_mov_b32 s9, s55
	s_waitcnt vmcnt(15)
; __device__ __forceinline__ unsigned cvt_pk_bf16(float lo, float hi) { unsigned r; asm volatile("v_cvt_pk_bf16_f32 %0, %1, %2" : "=v"(r) : "v"(lo), "v"(hi)); return r; }
; #define LAS __attribute__((address_space(3)))
; __device__ __forceinline__ float bflo(unsigned w) { return __uint_as_float(w << 16); }
; __device__ __forceinline__ float bfhi(unsigned w) { return __uint_as_float(w & 0xffff0000u); }
;     __device__ __forceinline__ void operator()(const f32x4 (&acc)[2][2][4][2], const Unit& u, int wr, int wc, int fr, int fq, const LAS float*) const {
;         const int row0 = u.pm * 256 + wr * 64 + fr, col0 = u.pn * 256 + wc * 32 + 8 * fq;
; #pragma unroll
;         for (int ai = 0; ai < 2; ++ai)
; #pragma unroll
;             for (int m = 0; m < 4; ++m) { const size_t row = (size_t)(row0 + ai * 128 + m * 16);
; #pragma unroll
;                 for (int bj = 0; bj < 2; ++bj) { const int col = col0 + bj * 128;
;                     const u32x4 g = *(const u32x4*)(G + row * NGATE + MODE * DM + col);
;                     f32x4 v0 = acc[ai][bj][m][0], v1 = acc[ai][bj][m][1];
;                     v0[0] *= bflo(g.x); v0[1] *= bfhi(g.x); v0[2] *= bflo(g.y); v0[3] *= bfhi(g.y); v1[0] *= bflo(g.z); v1[1] *= bfhi(g.z); v1[2] *= bflo(g.w); v1[3] *= bfhi(g.w);
;                     bf16_t* tp = T + row * DM + col;
;                     if (MODE == 1) { const u32x4 t = *(const u32x4*)tp;
;                         v0[0] += bflo(t.x); v0[1] += bfhi(t.x); v0[2] += bflo(t.y); v0[3] += bfhi(t.y); v1[0] += bflo(t.z); v1[1] += bfhi(t.z); v1[2] += bflo(t.w); v1[3] += bfhi(t.w); }
;                     u32x4 w; w.x = cvt_pk_bf16(v0[0], v0[1]); w.y = cvt_pk_bf16(v0[2], v0[3]); w.z = cvt_pk_bf16(v1[0], v1[1]); w.w = cvt_pk_bf16(v1[2], v1[3]);
;                     *(u32x4*)tp = w; } }
	s_nop 1
	v_mov_b64_e32 v[146:147], v[172:173]
	v_mov_b64_e32 v[148:149], v[174:175]
	v_lshlrev_b32_e32 v135, 16, v146
	v_and_b32_e32 v153, 0xffff0000, v146
	v_lshlrev_b32_e32 v156, 16, v147
	v_and_b32_e32 v157, 0xffff0000, v147
	v_lshlrev_b32_e32 v158, 16, v148
	v_and_b32_e32 v159, 0xffff0000, v148
	v_lshlrev_b32_e32 v160, 16, v149
	v_and_b32_e32 v161, 0xffff0000, v149
	s_waitcnt vmcnt(14)
	s_nop 1
	v_mov_b64_e32 v[146:147], v[176:177]
	v_mov_b64_e32 v[148:149], v[178:179]
	v_lshlrev_b32_e32 v144, 16, v146
	v_fmac_f32_e32 v144, v128, v135
	v_and_b32_e32 v128, 0xffff0000, v146
	v_fmac_f32_e32 v128, v129, v153
	v_lshlrev_b32_e32 v129, 16, v147
	v_fmac_f32_e32 v129, v130, v156
	v_and_b32_e32 v130, 0xffff0000, v147
	v_fmac_f32_e32 v130, v131, v157
	v_lshlrev_b32_e32 v131, 16, v148
	v_and_b32_e32 v135, 0xffff0000, v148
	v_lshlrev_b32_e32 v145, 16, v149
	v_and_b32_e32 v146, 0xffff0000, v149
	v_fmac_f32_e32 v131, v124, v158
	v_fmac_f32_e32 v135, v125, v159
	v_fmac_f32_e32 v145, v126, v160
	v_fmac_f32_e32 v146, v127, v161
	v_cvt_pk_bf16_f32 v124, v144, v128
	v_cvt_pk_bf16_f32 v125, v129, v130
	v_cvt_pk_bf16_f32 v126, v131, v135
	v_cvt_pk_bf16_f32 v127, v145, v146
	global_store_dwordx4 v[142:143], v[124:127], off
	s_waitcnt vmcnt(14)
	s_nop 1
	v_mov_b64_e32 v[124:125], v[180:181]
	v_mov_b64_e32 v[126:127], v[182:183]
	v_lshlrev_b32_e32 v128, 16, v124
	v_and_b32_e32 v129, 0xffff0000, v124
	v_lshlrev_b32_e32 v130, 16, v125
	v_and_b32_e32 v131, 0xffff0000, v125
	v_lshlrev_b32_e32 v135, 16, v126
	v_and_b32_e32 v144, 0xffff0000, v126
	v_lshlrev_b32_e32 v145, 16, v127
	v_and_b32_e32 v146, 0xffff0000, v127
	s_waitcnt vmcnt(13)
	s_nop 1
	v_mov_b64_e32 v[124:125], v[184:185]
	v_mov_b64_e32 v[126:127], v[186:187]
	v_lshlrev_b32_e32 v147, 16, v124
	v_fmac_f32_e32 v147, v120, v128
	v_and_b32_e32 v120, 0xffff0000, v124
	v_fmac_f32_e32 v120, v121, v129
	v_lshlrev_b32_e32 v121, 16, v125
	v_fmac_f32_e32 v121, v122, v130
	v_and_b32_e32 v122, 0xffff0000, v125
	v_fmac_f32_e32 v122, v123, v131
	v_lshlrev_b32_e32 v123, 16, v126
	v_fmac_f32_e32 v123, v116, v135
	v_and_b32_e32 v124, 0xffff0000, v126
	v_lshlrev_b32_e32 v125, 16, v127
	v_and_b32_e32 v126, 0xffff0000, v127
	v_cvt_pk_bf16_f32 v116, v147, v120
	v_fmac_f32_e32 v124, v117, v144
	v_fmac_f32_e32 v125, v118, v145
	v_fmac_f32_e32 v126, v119, v146
	v_cvt_pk_bf16_f32 v117, v121, v122
	v_cvt_pk_bf16_f32 v118, v123, v124
	v_cvt_pk_bf16_f32 v119, v125, v126
	global_store_dwordx4 v[142:143], v[116:119], off offset:256
	v_add_u32_e32 v237, 0x100000, v236
	v_add_u32_e32 v239, 0x80000, v238
	global_load_dwordx4 v[172:175], v237, s[2:3]
	global_load_dwordx4 v[176:179], v239, s[12:13]
	global_load_dwordx4 v[180:183], v237, s[2:3] offset:256
	global_load_dwordx4 v[184:187], v239, s[12:13] offset:256
	s_nop 1
	v_or_b32_e32 v116, 16, v134
	v_ashrrev_i32_e32 v117, 31, v116
	v_lshlrev_b64 v[118:119], 13, v[116:117]
	v_lshlrev_b64 v[122:123], 12, v[116:117]
	v_lshl_add_u64 v[116:117], s[2:3], 0, v[118:119]
	v_lshl_add_u64 v[118:119], v[116:117], 0, v[132:133]
	v_lshl_add_u64 v[116:117], v[118:119], 0, s[20:21]
	v_add_co_u32_e32 v118, vcc, s76, v118
	s_nop 1
	v_addc_co_u32_e32 v119, vcc, 0, v119, vcc
	s_waitcnt vmcnt(17)
	s_nop 1
	v_mov_b64_e32 v[118:119], v[188:189]
	v_mov_b64_e32 v[120:121], v[190:191]
	v_lshlrev_b32_e32 v124, 16, v118
	v_and_b32_e32 v125, 0xffff0000, v118
	v_lshlrev_b32_e32 v126, 16, v119
	v_and_b32_e32 v127, 0xffff0000, v119
	v_lshl_add_u64 v[118:119], s[12:13], 0, v[122:123]
	v_lshl_add_u64 v[122:123], v[118:119], 0, v[132:133]
	v_lshlrev_b32_e32 v128, 16, v120
	v_and_b32_e32 v129, 0xffff0000, v120
	v_lshlrev_b32_e32 v130, 16, v121
	v_and_b32_e32 v131, 0xffff0000, v121
	s_waitcnt vmcnt(16)
	s_nop 1
	v_mov_b64_e32 v[118:119], v[192:193]
	v_mov_b64_e32 v[120:121], v[194:195]
	v_lshlrev_b32_e32 v135, 16, v118
	v_fmac_f32_e32 v135, v112, v124
	v_and_b32_e32 v112, 0xffff0000, v118
	v_fmac_f32_e32 v112, v113, v125
	v_lshlrev_b32_e32 v113, 16, v119
	v_fmac_f32_e32 v113, v114, v126
	v_and_b32_e32 v114, 0xffff0000, v119
	v_fmac_f32_e32 v114, v115, v127
	v_lshlrev_b32_e32 v115, 16, v120
	v_and_b32_e32 v118, 0xffff0000, v120
	v_lshlrev_b32_e32 v119, 16, v121
	v_and_b32_e32 v120, 0xffff0000, v121
	v_fmac_f32_e32 v115, v108, v128
	v_fmac_f32_e32 v118, v109, v129
	v_fmac_f32_e32 v119, v110, v130
	v_fmac_f32_e32 v120, v111, v131
	v_cvt_pk_bf16_f32 v108, v135, v112
	v_cvt_pk_bf16_f32 v109, v113, v114
	v_cvt_pk_bf16_f32 v110, v115, v118
	v_cvt_pk_bf16_f32 v111, v119, v120
	global_store_dwordx4 v[122:123], v[108:111], off
	s_waitcnt vmcnt(16)
	s_nop 1
	v_mov_b64_e32 v[108:109], v[196:197]
	v_mov_b64_e32 v[110:111], v[198:199]
	v_lshlrev_b32_e32 v112, 16, v108
	v_and_b32_e32 v113, 0xffff0000, v108
	v_lshlrev_b32_e32 v114, 16, v109
	v_and_b32_e32 v115, 0xffff0000, v109
	v_lshlrev_b32_e32 v116, 16, v110
	v_and_b32_e32 v117, 0xffff0000, v110
	v_lshlrev_b32_e32 v118, 16, v111
	v_and_b32_e32 v119, 0xffff0000, v111
	s_waitcnt vmcnt(15)
; __device__ __forceinline__ unsigned cvt_pk_bf16(float lo, float hi) { unsigned r; asm volatile("v_cvt_pk_bf16_f32 %0, %1, %2" : "=v"(r) : "v"(lo), "v"(hi)); return r; }
; #define LAS __attribute__((address_space(3)))
; __device__ __forceinline__ float bflo(unsigned w) { return __uint_as_float(w << 16); }
; __device__ __forceinline__ float bfhi(unsigned w) { return __uint_as_float(w & 0xffff0000u); }
;     __device__ __forceinline__ void operator()(const f32x4 (&acc)[2][2][4][2], const Unit& u, int wr, int wc, int fr, int fq, const LAS float*) const {
;         const int row0 = u.pm * 256 + wr * 64 + fr, col0 = u.pn * 256 + wc * 32 + 8 * fq;
; #pragma unroll
;         for (int ai = 0; ai < 2; ++ai)
; #pragma unroll
;             for (int m = 0; m < 4; ++m) { const size_t row = (size_t)(row0 + ai * 128 + m * 16);
; #pragma unroll
;                 for (int bj = 0; bj < 2; ++bj) { const int col = col0 + bj * 128;
;                     const u32x4 g = *(const u32x4*)(G + row * NGATE + MODE * DM + col);
;                     f32x4 v0 = acc[ai][bj][m][0], v1 = acc[ai][bj][m][1];
;                     v0[0] *= bflo(g.x); v0[1] *= bfhi(g.x); v0[2] *= bflo(g.y); v0[3] *= bfhi(g.y); v1[0] *= bflo(g.z); v1[1] *= bfhi(g.z); v1[2] *= bflo(g.w); v1[3] *= bfhi(g.w);
;                     bf16_t* tp = T + row * DM + col;
;                     if (MODE == 1) { const u32x4 t = *(const u32x4*)tp;
;                         v0[0] += bflo(t.x); v0[1] += bfhi(t.x); v0[2] += bflo(t.y); v0[3] += bfhi(t.y); v1[0] += bflo(t.z); v1[1] += bfhi(t.z); v1[2] += bflo(t.w); v1[3] += bfhi(t.w); }
;                     u32x4 w; w.x = cvt_pk_bf16(v0[0], v0[1]); w.y = cvt_pk_bf16(v0[2], v0[3]); w.z = cvt_pk_bf16(v1[0], v1[1]); w.w = cvt_pk_bf16(v1[2], v1[3]);
;                     *(u32x4*)tp = w; } }
	s_nop 1
	v_mov_b64_e32 v[108:109], v[200:201]
	v_mov_b64_e32 v[110:111], v[202:203]
	v_lshlrev_b32_e32 v120, 16, v108
	v_fmac_f32_e32 v120, v104, v112
	v_and_b32_e32 v104, 0xffff0000, v108
	v_fmac_f32_e32 v104, v105, v113
	v_lshlrev_b32_e32 v105, 16, v109
	v_fmac_f32_e32 v105, v106, v114
	v_and_b32_e32 v106, 0xffff0000, v109
	v_fmac_f32_e32 v106, v107, v115
	v_lshlrev_b32_e32 v107, 16, v110
	v_fmac_f32_e32 v107, v100, v116
	v_and_b32_e32 v108, 0xffff0000, v110
	v_lshlrev_b32_e32 v109, 16, v111
	v_and_b32_e32 v110, 0xffff0000, v111
	v_cvt_pk_bf16_f32 v100, v120, v104
	v_fmac_f32_e32 v108, v101, v117
	v_fmac_f32_e32 v109, v102, v118
	v_fmac_f32_e32 v110, v103, v119
	v_cvt_pk_bf16_f32 v101, v105, v106
	v_cvt_pk_bf16_f32 v102, v107, v108
	v_cvt_pk_bf16_f32 v103, v109, v110
	global_store_dwordx4 v[122:123], v[100:103], off offset:256
	v_add_u32_e32 v237, 0x120000, v236
	v_add_u32_e32 v239, 0x90000, v238
	global_load_dwordx4 v[188:191], v237, s[2:3]
	global_load_dwordx4 v[192:195], v239, s[12:13]
	global_load_dwordx4 v[196:199], v237, s[2:3] offset:256
	global_load_dwordx4 v[200:203], v239, s[12:13] offset:256
	s_nop 1
	v_or_b32_e32 v100, 32, v134
	v_ashrrev_i32_e32 v101, 31, v100
	v_lshlrev_b64 v[102:103], 13, v[100:101]
	v_lshlrev_b64 v[106:107], 12, v[100:101]
	v_lshl_add_u64 v[100:101], s[2:3], 0, v[102:103]
	v_lshl_add_u64 v[102:103], v[100:101], 0, v[132:133]
	v_lshl_add_u64 v[100:101], v[102:103], 0, s[20:21]
	v_add_co_u32_e32 v102, vcc, s76, v102
	s_nop 1
	v_addc_co_u32_e32 v103, vcc, 0, v103, vcc
	s_waitcnt vmcnt(19)
	s_nop 1
	v_mov_b64_e32 v[102:103], v[204:205]
	v_mov_b64_e32 v[104:105], v[206:207]
	v_lshlrev_b32_e32 v108, 16, v102
	v_and_b32_e32 v109, 0xffff0000, v102
	v_lshlrev_b32_e32 v110, 16, v103
	v_and_b32_e32 v111, 0xffff0000, v103
	v_lshl_add_u64 v[102:103], s[12:13], 0, v[106:107]
	v_lshl_add_u64 v[106:107], v[102:103], 0, v[132:133]
	v_lshlrev_b32_e32 v112, 16, v104
	v_and_b32_e32 v113, 0xffff0000, v104
	v_lshlrev_b32_e32 v114, 16, v105
	v_and_b32_e32 v115, 0xffff0000, v105
	s_waitcnt vmcnt(18)
	s_nop 1
	v_mov_b64_e32 v[102:103], v[208:209]
	v_mov_b64_e32 v[104:105], v[210:211]
	v_lshlrev_b32_e32 v116, 16, v102
	v_fmac_f32_e32 v116, v96, v108
	v_and_b32_e32 v96, 0xffff0000, v102
	v_fmac_f32_e32 v96, v97, v109
	v_lshlrev_b32_e32 v97, 16, v103
	v_fmac_f32_e32 v97, v98, v110
	v_and_b32_e32 v98, 0xffff0000, v103
	v_fmac_f32_e32 v98, v99, v111
	v_lshlrev_b32_e32 v99, 16, v104
	v_and_b32_e32 v102, 0xffff0000, v104
	v_lshlrev_b32_e32 v103, 16, v105
	v_and_b32_e32 v104, 0xffff0000, v105
	v_fmac_f32_e32 v99, v92, v112
	v_fmac_f32_e32 v102, v93, v113
	v_fmac_f32_e32 v103, v94, v114
	v_fmac_f32_e32 v104, v95, v115
	v_cvt_pk_bf16_f32 v92, v116, v96
	v_cvt_pk_bf16_f32 v93, v97, v98
	v_cvt_pk_bf16_f32 v94, v99, v102
	v_cvt_pk_bf16_f32 v95, v103, v104
	global_store_dwordx4 v[106:107], v[92:95], off
	s_waitcnt vmcnt(18)
	s_nop 1
	v_mov_b64_e32 v[92:93], v[212:213]
	v_mov_b64_e32 v[94:95], v[214:215]
	v_lshlrev_b32_e32 v96, 16, v92
	v_and_b32_e32 v97, 0xffff0000, v92
	v_lshlrev_b32_e32 v98, 16, v93
	v_and_b32_e32 v99, 0xffff0000, v93
	v_lshlrev_b32_e32 v100, 16, v94
	v_and_b32_e32 v101, 0xffff0000, v94
	v_lshlrev_b32_e32 v102, 16, v95
	v_and_b32_e32 v103, 0xffff0000, v95
	s_waitcnt vmcnt(17)
	s_nop 1
	v_mov_b64_e32 v[92:93], v[216:217]
	v_mov_b64_e32 v[94:95], v[218:219]
	v_lshlrev_b32_e32 v104, 16, v92
	v_fmac_f32_e32 v104, v88, v96
	v_and_b32_e32 v88, 0xffff0000, v92
	v_fmac_f32_e32 v88, v89, v97
	v_lshlrev_b32_e32 v89, 16, v93
	v_fmac_f32_e32 v89, v90, v98
	v_and_b32_e32 v90, 0xffff0000, v93
	v_fmac_f32_e32 v90, v91, v99
	v_lshlrev_b32_e32 v91, 16, v94
	v_fmac_f32_e32 v91, v84, v100
	v_and_b32_e32 v92, 0xffff0000, v94
	v_lshlrev_b32_e32 v93, 16, v95
	v_and_b32_e32 v94, 0xffff0000, v95
	v_cvt_pk_bf16_f32 v84, v104, v88
	v_fmac_f32_e32 v92, v85, v101
	v_fmac_f32_e32 v93, v86, v102
	v_fmac_f32_e32 v94, v87, v103
	v_cvt_pk_bf16_f32 v85, v89, v90
	v_cvt_pk_bf16_f32 v86, v91, v92
	v_cvt_pk_bf16_f32 v87, v93, v94
	global_store_dwordx4 v[106:107], v[84:87], off offset:256
	v_add_u32_e32 v237, 0x140000, v236
	v_add_u32_e32 v239, 0xa0000, v238
	global_load_dwordx4 v[204:207], v237, s[2:3]
	global_load_dwordx4 v[208:211], v239, s[12:13]
	global_load_dwordx4 v[212:215], v237, s[2:3] offset:256
	global_load_dwordx4 v[216:219], v239, s[12:13] offset:256
	s_nop 1
	v_or_b32_e32 v84, 48, v134
	v_ashrrev_i32_e32 v85, 31, v84
	v_lshlrev_b64 v[86:87], 13, v[84:85]
	v_lshlrev_b64 v[90:91], 12, v[84:85]
	v_lshl_add_u64 v[84:85], s[2:3], 0, v[86:87]
	v_lshl_add_u64 v[86:87], v[84:85], 0, v[132:133]
	v_lshl_add_u64 v[84:85], v[86:87], 0, s[20:21]
	v_add_co_u32_e32 v86, vcc, s76, v86
	s_nop 1
	v_addc_co_u32_e32 v87, vcc, 0, v87, vcc
	s_waitcnt vmcnt(21)
	s_nop 1
	v_mov_b64_e32 v[86:87], v[220:221]
	v_mov_b64_e32 v[88:89], v[222:223]
	v_lshlrev_b32_e32 v92, 16, v86
	v_and_b32_e32 v93, 0xffff0000, v86
	v_lshlrev_b32_e32 v94, 16, v87
	v_and_b32_e32 v95, 0xffff0000, v87
	v_lshl_add_u64 v[86:87], s[12:13], 0, v[90:91]
	v_lshl_add_u64 v[90:91], v[86:87], 0, v[132:133]
	v_lshlrev_b32_e32 v96, 16, v88
	v_and_b32_e32 v97, 0xffff0000, v88
	v_lshlrev_b32_e32 v98, 16, v89
	v_and_b32_e32 v99, 0xffff0000, v89
	s_waitcnt vmcnt(20)
	s_nop 1
	v_mov_b64_e32 v[86:87], v[224:225]
	v_mov_b64_e32 v[88:89], v[226:227]
	v_lshlrev_b32_e32 v100, 16, v86
	v_fmac_f32_e32 v100, v80, v92
	v_and_b32_e32 v80, 0xffff0000, v86
	v_fmac_f32_e32 v80, v81, v93
	v_lshlrev_b32_e32 v81, 16, v87
	v_fmac_f32_e32 v81, v82, v94
	v_and_b32_e32 v82, 0xffff0000, v87
	v_fmac_f32_e32 v82, v83, v95
	v_lshlrev_b32_e32 v83, 16, v88
	v_and_b32_e32 v86, 0xffff0000, v88
	v_lshlrev_b32_e32 v87, 16, v89
	v_and_b32_e32 v88, 0xffff0000, v89
	v_fmac_f32_e32 v83, v76, v96
	v_fmac_f32_e32 v86, v77, v97
	v_fmac_f32_e32 v87, v78, v98
	v_fmac_f32_e32 v88, v79, v99
	v_cvt_pk_bf16_f32 v76, v100, v80
	v_cvt_pk_bf16_f32 v77, v81, v82
	v_cvt_pk_bf16_f32 v78, v83, v86
	v_cvt_pk_bf16_f32 v79, v87, v88
	global_store_dwordx4 v[90:91], v[76:79], off
	s_waitcnt vmcnt(20)
; __device__ __forceinline__ unsigned cvt_pk_bf16(float lo, float hi) { unsigned r; asm volatile("v_cvt_pk_bf16_f32 %0, %1, %2" : "=v"(r) : "v"(lo), "v"(hi)); return r; }
; #define LAS __attribute__((address_space(3)))
; __device__ __forceinline__ float bflo(unsigned w) { return __uint_as_float(w << 16); }
; __device__ __forceinline__ float bfhi(unsigned w) { return __uint_as_float(w & 0xffff0000u); }
;     __device__ __forceinline__ void operator()(const f32x4 (&acc)[2][2][4][2], const Unit& u, int wr, int wc, int fr, int fq, const LAS float*) const {
;         const int row0 = u.pm * 256 + wr * 64 + fr, col0 = u.pn * 256 + wc * 32 + 8 * fq;
; #pragma unroll
;         for (int ai = 0; ai < 2; ++ai)
; #pragma unroll
;             for (int m = 0; m < 4; ++m) { const size_t row = (size_t)(row0 + ai * 128 + m * 16);
; #pragma unroll
;                 for (int bj = 0; bj < 2; ++bj) { const int col = col0 + bj * 128;
;                     const u32x4 g = *(const u32x4*)(G + row * NGATE + MODE * DM + col);
;                     f32x4 v0 = acc[ai][bj][m][0], v1 = acc[ai][bj][m][1];
;                     v0[0] *= bflo(g.x); v0[1] *= bfhi(g.x); v0[2] *= bflo(g.y); v0[3] *= bfhi(g.y); v1[0] *= bflo(g.z); v1[1] *= bfhi(g.z); v1[2] *= bflo(g.w); v1[3] *= bfhi(g.w);
;                     bf16_t* tp = T + row * DM + col;
;                     if (MODE == 1) { const u32x4 t = *(const u32x4*)tp;
;                         v0[0] += bflo(t.x); v0[1] += bfhi(t.x); v0[2] += bflo(t.y); v0[3] += bfhi(t.y); v1[0] += bflo(t.z); v1[1] += bfhi(t.z); v1[2] += bflo(t.w); v1[3] += bfhi(t.w); }
;                     u32x4 w; w.x = cvt_pk_bf16(v0[0], v0[1]); w.y = cvt_pk_bf16(v0[2], v0[3]); w.z = cvt_pk_bf16(v1[0], v1[1]); w.w = cvt_pk_bf16(v1[2], v1[3]);
;                     *(u32x4*)tp = w; } }
	s_nop 1
	v_mov_b64_e32 v[76:77], v[228:229]
	v_mov_b64_e32 v[78:79], v[230:231]
	v_lshlrev_b32_e32 v80, 16, v76
	v_and_b32_e32 v81, 0xffff0000, v76
	v_lshlrev_b32_e32 v82, 16, v77
	v_and_b32_e32 v83, 0xffff0000, v77
	v_lshlrev_b32_e32 v84, 16, v78
	v_and_b32_e32 v85, 0xffff0000, v78
	v_lshlrev_b32_e32 v86, 16, v79
	v_and_b32_e32 v87, 0xffff0000, v79
	s_waitcnt vmcnt(19)
	s_nop 1
	v_mov_b64_e32 v[76:77], v[232:233]
	v_mov_b64_e32 v[78:79], v[234:235]
	v_lshlrev_b32_e32 v88, 16, v76
	v_fmac_f32_e32 v88, v72, v80
	v_and_b32_e32 v72, 0xffff0000, v76
	v_fmac_f32_e32 v72, v73, v81
	v_lshlrev_b32_e32 v73, 16, v77
	v_fmac_f32_e32 v73, v74, v82
	v_and_b32_e32 v74, 0xffff0000, v77
	v_fmac_f32_e32 v74, v75, v83
	v_lshlrev_b32_e32 v75, 16, v78
	v_fmac_f32_e32 v75, v68, v84
	v_and_b32_e32 v76, 0xffff0000, v78
	v_lshlrev_b32_e32 v77, 16, v79
	v_and_b32_e32 v78, 0xffff0000, v79
	v_cvt_pk_bf16_f32 v68, v88, v72
	v_fmac_f32_e32 v76, v69, v85
	v_fmac_f32_e32 v77, v70, v86
	v_fmac_f32_e32 v78, v71, v87
	v_cvt_pk_bf16_f32 v69, v73, v74
	v_cvt_pk_bf16_f32 v70, v75, v76
	v_cvt_pk_bf16_f32 v71, v77, v78
	global_store_dwordx4 v[90:91], v[68:71], off offset:256
	v_add_u32_e32 v237, 0x160000, v236
	v_add_u32_e32 v239, 0xb0000, v238
	global_load_dwordx4 v[220:223], v237, s[2:3]
	global_load_dwordx4 v[224:227], v239, s[12:13]
	global_load_dwordx4 v[228:231], v237, s[2:3] offset:256
	global_load_dwordx4 v[232:235], v239, s[12:13] offset:256
	s_nop 1
	v_add_u32_e32 v68, 0x80, v134
	v_ashrrev_i32_e32 v69, 31, v68
	v_lshlrev_b64 v[70:71], 13, v[68:69]
	v_lshlrev_b64 v[74:75], 12, v[68:69]
	v_lshl_add_u64 v[68:69], s[2:3], 0, v[70:71]
	v_lshl_add_u64 v[70:71], v[68:69], 0, v[132:133]
	v_lshl_add_u64 v[68:69], v[70:71], 0, s[20:21]
	v_add_co_u32_e32 v70, vcc, s76, v70
	s_nop 1
	v_addc_co_u32_e32 v71, vcc, 0, v71, vcc
	s_waitcnt vmcnt(21)
	s_nop 1
	v_mov_b64_e32 v[70:71], v[172:173]
	v_mov_b64_e32 v[72:73], v[174:175]
	v_lshlrev_b32_e32 v76, 16, v70
	v_and_b32_e32 v77, 0xffff0000, v70
	v_lshlrev_b32_e32 v78, 16, v71
	v_and_b32_e32 v79, 0xffff0000, v71
	v_lshl_add_u64 v[70:71], s[12:13], 0, v[74:75]
	v_lshl_add_u64 v[74:75], v[70:71], 0, v[132:133]
	v_lshlrev_b32_e32 v80, 16, v72
	v_and_b32_e32 v81, 0xffff0000, v72
	v_lshlrev_b32_e32 v82, 16, v73
	v_and_b32_e32 v83, 0xffff0000, v73
	s_waitcnt vmcnt(20)
	s_nop 1
	v_mov_b64_e32 v[70:71], v[176:177]
	v_mov_b64_e32 v[72:73], v[178:179]
	v_lshlrev_b32_e32 v84, 16, v70
	v_fmac_f32_e32 v84, v64, v76
	v_and_b32_e32 v64, 0xffff0000, v70
	v_fmac_f32_e32 v64, v65, v77
	v_lshlrev_b32_e32 v65, 16, v71
	v_fmac_f32_e32 v65, v66, v78
	v_and_b32_e32 v66, 0xffff0000, v71
	v_fmac_f32_e32 v66, v67, v79
	v_lshlrev_b32_e32 v67, 16, v72
	v_and_b32_e32 v70, 0xffff0000, v72
	v_lshlrev_b32_e32 v71, 16, v73
	v_and_b32_e32 v72, 0xffff0000, v73
	v_fmac_f32_e32 v67, v60, v80
	v_fmac_f32_e32 v70, v61, v81
	v_fmac_f32_e32 v71, v62, v82
	v_fmac_f32_e32 v72, v63, v83
	v_cvt_pk_bf16_f32 v60, v84, v64
	v_cvt_pk_bf16_f32 v61, v65, v66
	v_cvt_pk_bf16_f32 v62, v67, v70
	v_cvt_pk_bf16_f32 v63, v71, v72
	global_store_dwordx4 v[74:75], v[60:63], off
	s_waitcnt vmcnt(20)
	s_nop 1
	v_mov_b64_e32 v[60:61], v[180:181]
	v_mov_b64_e32 v[62:63], v[182:183]
	v_lshlrev_b32_e32 v64, 16, v60
	v_and_b32_e32 v65, 0xffff0000, v60
	v_lshlrev_b32_e32 v66, 16, v61
	v_and_b32_e32 v67, 0xffff0000, v61
	v_lshlrev_b32_e32 v68, 16, v62
	v_and_b32_e32 v69, 0xffff0000, v62
	v_lshlrev_b32_e32 v70, 16, v63
	v_and_b32_e32 v71, 0xffff0000, v63
	s_waitcnt vmcnt(19)
	s_nop 1
	v_mov_b64_e32 v[60:61], v[184:185]
	v_mov_b64_e32 v[62:63], v[186:187]
	v_lshlrev_b32_e32 v72, 16, v60
	v_fmac_f32_e32 v72, v56, v64
	v_and_b32_e32 v56, 0xffff0000, v60
	v_fmac_f32_e32 v56, v57, v65
	v_lshlrev_b32_e32 v57, 16, v61
	v_fmac_f32_e32 v57, v58, v66
	v_and_b32_e32 v58, 0xffff0000, v61
	v_fmac_f32_e32 v58, v59, v67
	v_lshlrev_b32_e32 v59, 16, v62
	v_fmac_f32_e32 v59, v52, v68
	v_and_b32_e32 v60, 0xffff0000, v62
	v_lshlrev_b32_e32 v61, 16, v63
	v_and_b32_e32 v62, 0xffff0000, v63
	v_cvt_pk_bf16_f32 v52, v72, v56
	v_fmac_f32_e32 v60, v53, v69
	v_fmac_f32_e32 v61, v54, v70
	v_fmac_f32_e32 v62, v55, v71
	v_cvt_pk_bf16_f32 v53, v57, v58
	v_cvt_pk_bf16_f32 v54, v59, v60
	v_cvt_pk_bf16_f32 v55, v61, v62
	global_store_dwordx4 v[74:75], v[52:55], off offset:256
	s_nop 1
	v_add_u32_e32 v52, 0x90, v134
	v_ashrrev_i32_e32 v53, 31, v52
	v_lshlrev_b64 v[54:55], 13, v[52:53]
	v_lshlrev_b64 v[58:59], 12, v[52:53]
	v_lshl_add_u64 v[52:53], s[2:3], 0, v[54:55]
	v_lshl_add_u64 v[54:55], v[52:53], 0, v[132:133]
	v_lshl_add_u64 v[52:53], v[54:55], 0, s[20:21]
	v_add_co_u32_e32 v54, vcc, s76, v54
	s_nop 1
	v_addc_co_u32_e32 v55, vcc, 0, v55, vcc
	s_waitcnt vmcnt(17)
	s_nop 1
	v_mov_b64_e32 v[54:55], v[188:189]
	v_mov_b64_e32 v[56:57], v[190:191]
	v_lshlrev_b32_e32 v60, 16, v54
	v_and_b32_e32 v61, 0xffff0000, v54
	v_lshlrev_b32_e32 v62, 16, v55
	v_and_b32_e32 v63, 0xffff0000, v55
	v_lshl_add_u64 v[54:55], s[12:13], 0, v[58:59]
	v_lshl_add_u64 v[58:59], v[54:55], 0, v[132:133]
	v_lshlrev_b32_e32 v64, 16, v56
	v_and_b32_e32 v65, 0xffff0000, v56
	v_lshlrev_b32_e32 v66, 16, v57
	v_and_b32_e32 v67, 0xffff0000, v57
	s_waitcnt vmcnt(16)
	s_nop 1
	v_mov_b64_e32 v[54:55], v[192:193]
	v_mov_b64_e32 v[56:57], v[194:195]
	v_lshlrev_b32_e32 v68, 16, v54
	v_fmac_f32_e32 v68, v48, v60
	v_and_b32_e32 v48, 0xffff0000, v54
	v_fmac_f32_e32 v48, v49, v61
	v_lshlrev_b32_e32 v49, 16, v55
	v_fmac_f32_e32 v49, v50, v62
	v_and_b32_e32 v50, 0xffff0000, v55
	v_fmac_f32_e32 v50, v51, v63
	v_lshlrev_b32_e32 v51, 16, v56
	v_and_b32_e32 v54, 0xffff0000, v56
	v_lshlrev_b32_e32 v55, 16, v57
	v_and_b32_e32 v56, 0xffff0000, v57
	v_fmac_f32_e32 v51, v44, v64
	v_fmac_f32_e32 v54, v45, v65
	v_fmac_f32_e32 v55, v46, v66
	v_fmac_f32_e32 v56, v47, v67
	v_cvt_pk_bf16_f32 v44, v68, v48
	v_cvt_pk_bf16_f32 v45, v49, v50
	v_cvt_pk_bf16_f32 v46, v51, v54
	v_cvt_pk_bf16_f32 v47, v55, v56
	global_store_dwordx4 v[58:59], v[44:47], off
	s_waitcnt vmcnt(16)
; __device__ __forceinline__ unsigned cvt_pk_bf16(float lo, float hi) { unsigned r; asm volatile("v_cvt_pk_bf16_f32 %0, %1, %2" : "=v"(r) : "v"(lo), "v"(hi)); return r; }
; #define PG8_SYNC() do { asm volatile("s_waitcnt vmcnt(0) lgkmcnt(0)" ::: "memory"); __builtin_amdgcn_s_barrier(); asm volatile("" ::: "memory"); } while (0)
; #define LAS __attribute__((address_space(3)))
; template <class Epi, class Sched>
; __device__ __forceinline__ void gemm_simple(PG8_LAS unsigned char* lds, const Gemm g, const Sched& S, const Epi& E, int wave_s) {
;     ...
;         if (!has_next) break;
; #pragma unroll
;         for (int a = 0; a < 2; ++a)
; #pragma unroll
;             for (int b = 0; b < 2; ++b)
; #pragma unroll
;                 for (int m = 0; m < 4; ++m)
; #pragma unroll
;                     for (int n = 0; n < 2; ++n) acc[a][b][m][n] = (f32x4){zero_o, zero_o, zero_o, zero_o};
;         cur = nxt; cA = nA; cB = nB; ++ui;
;     }
;     PG8_SYNC();
;     __device__ __forceinline__ void operator()(const f32x4 (&acc)[2][2][4][2], const Unit& u, int wr, int wc, int fr, int fq, const LAS float*) const {
;         const int row0 = u.pm * 256 + wr * 64 + fr, col0 = u.pn * 256 + wc * 32 + 8 * fq;
; #pragma unroll
;         for (int ai = 0; ai < 2; ++ai)
; #pragma unroll
;             for (int m = 0; m < 4; ++m) { const size_t row = (size_t)(row0 + ai * 128 + m * 16);
; #pragma unroll
;                 for (int bj = 0; bj < 2; ++bj) { const int col = col0 + bj * 128;
;                     const u32x4 g = *(const u32x4*)(G + row * NGATE + MODE * DM + col);
;                     f32x4 v0 = acc[ai][bj][m][0], v1 = acc[ai][bj][m][1];
;                     v0[0] *= bflo(g.x); v0[1] *= bfhi(g.x); v0[2] *= bflo(g.y); v0[3] *= bfhi(g.y); v1[0] *= bflo(g.z); v1[1] *= bfhi(g.z); v1[2] *= bflo(g.w); v1[3] *= bfhi(g.w);
;                     bf16_t* tp = T + row * DM + col;
;                     if (MODE == 1) { const u32x4 t = *(const u32x4*)tp;
;                         v0[0] += bflo(t.x); v0[1] += bfhi(t.x); v0[2] += bflo(t.y); v0[3] += bfhi(t.y); v1[0] += bflo(t.z); v1[1] += bfhi(t.z); v1[2] += bflo(t.w); v1[3] += bfhi(t.w); }
;                     u32x4 w; w.x = cvt_pk_bf16(v0[0], v0[1]); w.y = cvt_pk_bf16(v0[2], v0[3]); w.z = cvt_pk_bf16(v1[0], v1[1]); w.w = cvt_pk_bf16(v1[2], v1[3]);
;                     *(u32x4*)tp = w; } }
	s_nop 1
	v_mov_b64_e32 v[44:45], v[196:197]
	v_mov_b64_e32 v[46:47], v[198:199]
	v_lshlrev_b32_e32 v48, 16, v44
	v_and_b32_e32 v49, 0xffff0000, v44
	v_lshlrev_b32_e32 v50, 16, v45
	v_and_b32_e32 v51, 0xffff0000, v45
	v_lshlrev_b32_e32 v52, 16, v46
	v_and_b32_e32 v53, 0xffff0000, v46
	v_lshlrev_b32_e32 v54, 16, v47
	v_and_b32_e32 v55, 0xffff0000, v47
	s_waitcnt vmcnt(15)
	s_nop 1
	v_mov_b64_e32 v[44:45], v[200:201]
	v_mov_b64_e32 v[46:47], v[202:203]
	v_lshlrev_b32_e32 v56, 16, v44
	v_fmac_f32_e32 v56, v40, v48
	v_and_b32_e32 v40, 0xffff0000, v44
	v_fmac_f32_e32 v40, v41, v49
	v_lshlrev_b32_e32 v41, 16, v45
	v_fmac_f32_e32 v41, v42, v50
	v_and_b32_e32 v42, 0xffff0000, v45
	v_fmac_f32_e32 v42, v43, v51
	v_lshlrev_b32_e32 v43, 16, v46
	v_fmac_f32_e32 v43, v36, v52
	v_and_b32_e32 v44, 0xffff0000, v46
	v_lshlrev_b32_e32 v45, 16, v47
	v_and_b32_e32 v46, 0xffff0000, v47
	v_cvt_pk_bf16_f32 v36, v56, v40
	v_fmac_f32_e32 v44, v37, v53
	v_fmac_f32_e32 v45, v38, v54
	v_fmac_f32_e32 v46, v39, v55
	v_cvt_pk_bf16_f32 v37, v41, v42
	v_cvt_pk_bf16_f32 v38, v43, v44
	v_cvt_pk_bf16_f32 v39, v45, v46
	global_store_dwordx4 v[58:59], v[36:39], off offset:256
	s_nop 1
	v_add_u32_e32 v36, 0xa0, v134
	v_ashrrev_i32_e32 v37, 31, v36
	v_lshlrev_b64 v[38:39], 13, v[36:37]
	v_lshlrev_b64 v[42:43], 12, v[36:37]
	v_lshl_add_u64 v[36:37], s[2:3], 0, v[38:39]
	v_lshl_add_u64 v[38:39], v[36:37], 0, v[132:133]
	v_lshl_add_u64 v[36:37], v[38:39], 0, s[20:21]
	v_add_co_u32_e32 v38, vcc, s76, v38
	s_nop 1
	v_addc_co_u32_e32 v39, vcc, 0, v39, vcc
	s_waitcnt vmcnt(13)
	s_nop 1
	v_mov_b64_e32 v[38:39], v[204:205]
	v_mov_b64_e32 v[40:41], v[206:207]
	v_lshlrev_b32_e32 v44, 16, v38
	v_and_b32_e32 v45, 0xffff0000, v38
	v_lshlrev_b32_e32 v46, 16, v39
	v_and_b32_e32 v47, 0xffff0000, v39
	v_lshl_add_u64 v[38:39], s[12:13], 0, v[42:43]
	v_lshl_add_u64 v[42:43], v[38:39], 0, v[132:133]
	v_lshlrev_b32_e32 v48, 16, v40
	v_and_b32_e32 v49, 0xffff0000, v40
	v_lshlrev_b32_e32 v50, 16, v41
	v_and_b32_e32 v51, 0xffff0000, v41
	s_waitcnt vmcnt(12)
	s_nop 1
	v_mov_b64_e32 v[38:39], v[208:209]
	v_mov_b64_e32 v[40:41], v[210:211]
	v_lshlrev_b32_e32 v52, 16, v38
	v_fmac_f32_e32 v52, v32, v44
	v_and_b32_e32 v32, 0xffff0000, v38
	v_fmac_f32_e32 v32, v33, v45
	v_lshlrev_b32_e32 v33, 16, v39
	v_fmac_f32_e32 v33, v34, v46
	v_and_b32_e32 v34, 0xffff0000, v39
	v_fmac_f32_e32 v34, v35, v47
	v_lshlrev_b32_e32 v35, 16, v40
	v_and_b32_e32 v38, 0xffff0000, v40
	v_lshlrev_b32_e32 v39, 16, v41
	v_and_b32_e32 v40, 0xffff0000, v41
	v_fmac_f32_e32 v35, v28, v48
	v_fmac_f32_e32 v38, v29, v49
	v_fmac_f32_e32 v39, v30, v50
	v_fmac_f32_e32 v40, v31, v51
	v_cvt_pk_bf16_f32 v28, v52, v32
	v_cvt_pk_bf16_f32 v29, v33, v34
	v_cvt_pk_bf16_f32 v30, v35, v38
	v_cvt_pk_bf16_f32 v31, v39, v40
	global_store_dwordx4 v[42:43], v[28:31], off
	s_waitcnt vmcnt(12)
	s_nop 1
	v_mov_b64_e32 v[28:29], v[212:213]
	v_mov_b64_e32 v[30:31], v[214:215]
	v_lshlrev_b32_e32 v32, 16, v28
	v_and_b32_e32 v33, 0xffff0000, v28
	v_lshlrev_b32_e32 v34, 16, v29
	v_and_b32_e32 v35, 0xffff0000, v29
	v_lshlrev_b32_e32 v36, 16, v30
	v_and_b32_e32 v37, 0xffff0000, v30
	v_lshlrev_b32_e32 v38, 16, v31
	v_and_b32_e32 v39, 0xffff0000, v31
	s_waitcnt vmcnt(11)
	s_nop 1
	v_mov_b64_e32 v[28:29], v[216:217]
	v_mov_b64_e32 v[30:31], v[218:219]
	v_lshlrev_b32_e32 v40, 16, v28
	v_fmac_f32_e32 v40, v24, v32
	v_and_b32_e32 v24, 0xffff0000, v28
	v_fmac_f32_e32 v24, v25, v33
	v_lshlrev_b32_e32 v25, 16, v29
	v_fmac_f32_e32 v25, v26, v34
	v_and_b32_e32 v26, 0xffff0000, v29
	v_fmac_f32_e32 v26, v27, v35
	v_lshlrev_b32_e32 v27, 16, v30
	v_fmac_f32_e32 v27, v20, v36
	v_and_b32_e32 v28, 0xffff0000, v30
	v_lshlrev_b32_e32 v29, 16, v31
	v_and_b32_e32 v30, 0xffff0000, v31
	v_cvt_pk_bf16_f32 v20, v40, v24
	v_fmac_f32_e32 v28, v21, v37
	v_fmac_f32_e32 v29, v22, v38
	v_fmac_f32_e32 v30, v23, v39
	v_cvt_pk_bf16_f32 v21, v25, v26
	v_cvt_pk_bf16_f32 v22, v27, v28
	v_cvt_pk_bf16_f32 v23, v29, v30
	global_store_dwordx4 v[42:43], v[20:23], off offset:256
	s_nop 1
	v_add_u32_e32 v20, 0xb0, v134
	v_ashrrev_i32_e32 v21, 31, v20
	v_lshlrev_b64 v[22:23], 13, v[20:21]
	v_lshlrev_b64 v[26:27], 12, v[20:21]
	v_lshl_add_u64 v[20:21], s[2:3], 0, v[22:23]
	v_lshl_add_u64 v[22:23], v[20:21], 0, v[132:133]
	v_lshl_add_u64 v[20:21], v[22:23], 0, s[20:21]
	v_add_co_u32_e32 v22, vcc, s76, v22
	s_mov_b64 s[20:21], s[16:17]
	s_nop 0
	v_addc_co_u32_e32 v23, vcc, 0, v23, vcc
	s_andn2_b64 vcc, exec, s[6:7]
	s_waitcnt vmcnt(9)
	s_nop 1
	v_mov_b64_e32 v[22:23], v[220:221]
	v_mov_b64_e32 v[24:25], v[222:223]
	v_lshlrev_b32_e32 v28, 16, v22
	v_and_b32_e32 v29, 0xffff0000, v22
	v_lshlrev_b32_e32 v30, 16, v23
	v_and_b32_e32 v31, 0xffff0000, v23
	v_lshl_add_u64 v[22:23], s[12:13], 0, v[26:27]
	v_lshl_add_u64 v[26:27], v[22:23], 0, v[132:133]
	v_lshlrev_b32_e32 v32, 16, v24
	v_and_b32_e32 v33, 0xffff0000, v24
	v_lshlrev_b32_e32 v34, 16, v25
	v_and_b32_e32 v35, 0xffff0000, v25
	s_waitcnt vmcnt(8)
	s_nop 1
	v_mov_b64_e32 v[22:23], v[224:225]
	v_mov_b64_e32 v[24:25], v[226:227]
	v_lshlrev_b32_e32 v36, 16, v22
	v_fmac_f32_e32 v36, v16, v28
	v_and_b32_e32 v16, 0xffff0000, v22
	v_fmac_f32_e32 v16, v17, v29
	v_lshlrev_b32_e32 v17, 16, v23
	v_fmac_f32_e32 v17, v18, v30
	v_and_b32_e32 v18, 0xffff0000, v23
	v_fmac_f32_e32 v18, v19, v31
	v_lshlrev_b32_e32 v19, 16, v24
	v_and_b32_e32 v22, 0xffff0000, v24
	v_lshlrev_b32_e32 v23, 16, v25
	v_and_b32_e32 v24, 0xffff0000, v25
	v_fmac_f32_e32 v19, v12, v32
	v_fmac_f32_e32 v22, v13, v33
	v_fmac_f32_e32 v23, v14, v34
	v_fmac_f32_e32 v24, v15, v35
	v_cvt_pk_bf16_f32 v12, v36, v16
	v_cvt_pk_bf16_f32 v13, v17, v18
	v_cvt_pk_bf16_f32 v14, v19, v22
	v_cvt_pk_bf16_f32 v15, v23, v24
	global_store_dwordx4 v[26:27], v[12:15], off
	s_waitcnt vmcnt(8)
	s_nop 1
	v_mov_b64_e32 v[12:13], v[228:229]
	v_mov_b64_e32 v[14:15], v[230:231]
	v_lshlrev_b32_e32 v16, 16, v12
	v_and_b32_e32 v17, 0xffff0000, v12
	v_lshlrev_b32_e32 v18, 16, v13
	v_and_b32_e32 v19, 0xffff0000, v13
	v_lshlrev_b32_e32 v20, 16, v14
	v_and_b32_e32 v21, 0xffff0000, v14
	v_lshlrev_b32_e32 v22, 16, v15
	v_and_b32_e32 v23, 0xffff0000, v15
	s_waitcnt vmcnt(7)
	s_nop 1
	v_mov_b64_e32 v[12:13], v[232:233]
	v_mov_b64_e32 v[14:15], v[234:235]
	v_lshlrev_b32_e32 v24, 16, v12
	v_fmac_f32_e32 v24, v4, v16
	v_and_b32_e32 v4, 0xffff0000, v12
	v_fmac_f32_e32 v4, v5, v17
	v_lshlrev_b32_e32 v5, 16, v13
	v_fmac_f32_e32 v5, v6, v18
	v_and_b32_e32 v6, 0xffff0000, v13
	v_fmac_f32_e32 v6, v7, v19
	v_lshlrev_b32_e32 v7, 16, v14
	v_fmac_f32_e32 v7, v8, v20
	v_and_b32_e32 v8, 0xffff0000, v14
	v_fmac_f32_e32 v8, v9, v21
	v_lshlrev_b32_e32 v9, 16, v15
	v_fmac_f32_e32 v9, v10, v22
	v_and_b32_e32 v10, 0xffff0000, v15
	v_fmac_f32_e32 v10, v11, v23
	v_cvt_pk_bf16_f32 v4, v24, v4
	v_cvt_pk_bf16_f32 v5, v5, v6
	v_cvt_pk_bf16_f32 v6, v7, v8
	v_cvt_pk_bf16_f32 v7, v9, v10
	global_store_dwordx4 v[26:27], v[4:7], off offset:256
	s_cbranch_vccnz .LBB0_164
	s_waitcnt vmcnt(0) lgkmcnt(0)
	s_barrier

; template <class Epi, class Sched>
; __device__ __forceinline__ void gemm_simple(PG8_LAS unsigned char* lds, const Gemm g, const Sched& S, const Epi& E, int wave_s) {
;     ...
;         const bool has_next = S.next(ui + 1, nxt);
;         const char* nA = has_next ? (const char*)g.A + (size_t)nxt.pm * tstep : cA; const char* nB = has_next ? (const char*)g.Bt + (size_t)nxt.pn * tstep : cB;
;         int t = 0;
;         if (ui > 0) {
;             if constexpr (Epi::NST >= 16) PG8_TILE_W(0, cA + kstep, cB + kstep, "18", "20"); else PG8_TILE_W(0, cA + kstep, cB + kstep, "10", "12");
;             PG8_TILE_W(1, cA + 2 * kstep, cB + 2 * kstep, "2", "4");
;             t = 2;
;         }
;         for (; t < nt; t += 2) {
.LBB0_194:
	s_ashr_i32 s9, s8, 31
	s_lshl_b64 s[10:11], s[8:9], 18
	s_add_u32 s10, s96, s10
	s_addc_u32 s11, s97, s11
	s_and_b64 s[14:15], vcc, exec
	s_cselect_b32 s9, s11, s21
	s_cselect_b32 s54, s10, s20
	s_ashr_i32 s5, s4, 31
	s_lshl_b64 s[14:15], s[4:5], 18
	s_add_u32 s14, s27, s14
	s_addc_u32 s15, s28, s15
	s_and_b64 s[24:25], vcc, exec
	s_cselect_b32 s5, s15, s19
	s_cselect_b32 s55, s14, s18
	s_add_i32 s56, s22, -2
	s_lshl_b32 s57, s22, 7
	s_mov_b64 s[22:23], 0x300
	s_branch .Lrt_top_195

; template <class Epi, class Sched>
; __device__ __forceinline__ void gemm_simple(PG8_LAS unsigned char* lds, const Gemm g, const Sched& S, const Epi& E, int wave_s) {
;     ...
;         for (; t < nt; t += 2) {
;             const bool last = (t == nt - 2);
;             PG8_TILE(0, cA + (size_t)(t + 1) * kstep, cB + (size_t)(t + 1) * kstep, true);
.Lrt_top_195:
.LBB0_195:
	s_waitcnt vmcnt(2) lgkmcnt(0)
	s_barrier
	ds_read_b128 v[146:149], v132
	ds_read_b128 v[174:177], v152
	ds_read_b128 v[158:161], v132 offset:2048
	ds_read_b128 v[182:185], v152 offset:2048
	ds_read_b128 v[190:193], v152 offset:4096
	s_add_u32 s58, s18, s57
	s_addc_u32 s59, s19, 0
	s_add_u32 s24, s58, 0x80
	s_addc_u32 s25, s59, 0
	s_mov_b32 m0, s43
	s_nop 0
	global_load_lds_dwordx4 v137, s[24:25]
	s_mov_b32 m0, s47
	s_nop 0
	global_load_lds_dwordx4 v139, s[24:25]
	s_waitcnt lgkmcnt(3)
	v_mfma_f32_16x16x32_bf16 v[128:131], v[146:149], v[174:177], v[128:131]
	s_waitcnt lgkmcnt(2)
	v_mfma_f32_16x16x32_bf16 v[124:127], v[158:161], v[174:177], v[124:127]
	ds_read_b128 v[198:201], v152 offset:6144
	s_waitcnt lgkmcnt(2)
	v_mfma_f32_16x16x32_bf16 v[112:115], v[146:149], v[182:185], v[112:115]
	v_mfma_f32_16x16x32_bf16 v[108:111], v[158:161], v[182:185], v[108:111]
	ds_read_b128 v[154:157], v132 offset:1024
	ds_read_b128 v[178:181], v152 offset:1024
	s_waitcnt lgkmcnt(3)
	v_mfma_f32_16x16x32_bf16 v[96:99], v[146:149], v[190:193], v[96:99]
	ds_read_b128 v[170:173], v132 offset:3072
	v_mfma_f32_16x16x32_bf16 v[92:95], v[158:161], v[190:193], v[92:95]
	ds_read_b128 v[186:189], v152 offset:3072
	s_waitcnt lgkmcnt(4)
	v_mfma_f32_16x16x32_bf16 v[80:83], v[146:149], v[198:201], v[80:83]
	v_mfma_f32_16x16x32_bf16 v[76:79], v[158:161], v[198:201], v[76:79]
	ds_read_b128 v[194:197], v152 offset:5120
	s_waitcnt lgkmcnt(3)
	v_mfma_f32_16x16x32_bf16 v[128:131], v[154:157], v[178:181], v[128:131]
	s_waitcnt lgkmcnt(2)
	v_mfma_f32_16x16x32_bf16 v[124:127], v[170:173], v[178:181], v[124:127]
	ds_read_b128 v[202:205], v152 offset:7168
	s_waitcnt lgkmcnt(2)
	v_mfma_f32_16x16x32_bf16 v[112:115], v[154:157], v[186:189], v[112:115]
	v_mfma_f32_16x16x32_bf16 v[108:111], v[170:173], v[186:189], v[108:111]
	ds_read_b128 v[206:209], v133
	s_waitcnt lgkmcnt(2)
	v_mfma_f32_16x16x32_bf16 v[96:99], v[154:157], v[194:197], v[96:99]
	ds_read_b128 v[214:217], v133 offset:2048
	v_mfma_f32_16x16x32_bf16 v[92:95], v[170:173], v[194:197], v[92:95]
	s_waitcnt lgkmcnt(2)
	v_mfma_f32_16x16x32_bf16 v[80:83], v[154:157], v[202:205], v[80:83]
	v_mfma_f32_16x16x32_bf16 v[76:79], v[170:173], v[202:205], v[76:79]
	s_add_u32 s60, s20, s57
	s_addc_u32 s61, s21, 0
	s_add_u32 s24, s60, 0x80
	s_addc_u32 s25, s61, 0
	s_mov_b32 m0, s44
	s_nop 0
	global_load_lds_dwordx4 v136, s[24:25]
	s_mov_b32 m0, s48
	s_nop 0
	global_load_lds_dwordx4 v138, s[24:25]
	s_waitcnt lgkmcnt(1)
	v_mfma_f32_16x16x32_bf16 v[120:123], v[206:209], v[174:177], v[120:123]
	s_waitcnt lgkmcnt(0)
	v_mfma_f32_16x16x32_bf16 v[116:119], v[214:217], v[174:177], v[116:119]
	v_mfma_f32_16x16x32_bf16 v[104:107], v[206:209], v[182:185], v[104:107]
	v_mfma_f32_16x16x32_bf16 v[100:103], v[214:217], v[182:185], v[100:103]
	ds_read_b128 v[210:213], v133 offset:1024
	v_mfma_f32_16x16x32_bf16 v[88:91], v[206:209], v[190:193], v[88:91]
	ds_read_b128 v[218:221], v133 offset:3072
	v_mfma_f32_16x16x32_bf16 v[84:87], v[214:217], v[190:193], v[84:87]
	v_mfma_f32_16x16x32_bf16 v[72:75], v[206:209], v[198:201], v[72:75]
	v_mfma_f32_16x16x32_bf16 v[68:71], v[214:217], v[198:201], v[68:71]
	s_waitcnt lgkmcnt(1)
	v_mfma_f32_16x16x32_bf16 v[120:123], v[210:213], v[178:181], v[120:123]
	s_waitcnt lgkmcnt(0)
	v_mfma_f32_16x16x32_bf16 v[116:119], v[218:221], v[178:181], v[116:119]
	v_mfma_f32_16x16x32_bf16 v[104:107], v[210:213], v[186:189], v[104:107]
	v_mfma_f32_16x16x32_bf16 v[100:103], v[218:221], v[186:189], v[100:103]
	v_mfma_f32_16x16x32_bf16 v[88:91], v[210:213], v[194:197], v[88:91]
	v_mfma_f32_16x16x32_bf16 v[84:87], v[218:221], v[194:197], v[84:87]
	v_mfma_f32_16x16x32_bf16 v[72:75], v[210:213], v[202:205], v[72:75]
	v_mfma_f32_16x16x32_bf16 v[68:71], v[218:221], v[202:205], v[68:71]
	s_waitcnt vmcnt(4) lgkmcnt(0)
	s_barrier
	ds_read_b128 v[174:177], v152 offset:16384
	ds_read_b128 v[182:185], v152 offset:18432
	ds_read_b128 v[190:193], v152 offset:20480
	s_add_u32 s24, s58, 0x20080
	s_addc_u32 s25, s59, 0
	s_mov_b32 m0, s45
	s_nop 0
	global_load_lds_dwordx4 v137, s[24:25]
	s_mov_b32 m0, s49
	s_nop 0
	global_load_lds_dwordx4 v139, s[24:25]
	s_waitcnt lgkmcnt(2)
	v_mfma_f32_16x16x32_bf16 v[64:67], v[146:149], v[174:177], v[64:67]
	v_mfma_f32_16x16x32_bf16 v[60:63], v[158:161], v[174:177], v[60:63]
	ds_read_b128 v[198:201], v152 offset:22528
	s_waitcnt lgkmcnt(2)
	v_mfma_f32_16x16x32_bf16 v[48:51], v[146:149], v[182:185], v[48:51]
	v_mfma_f32_16x16x32_bf16 v[44:47], v[158:161], v[182:185], v[44:47]
	ds_read_b128 v[178:181], v152 offset:17408
	s_waitcnt lgkmcnt(2)
	v_mfma_f32_16x16x32_bf16 v[32:35], v[146:149], v[190:193], v[32:35]
	v_mfma_f32_16x16x32_bf16 v[28:31], v[158:161], v[190:193], v[28:31]
	ds_read_b128 v[186:189], v152 offset:19456
	s_waitcnt lgkmcnt(2)
	v_mfma_f32_16x16x32_bf16 v[16:19], v[146:149], v[198:201], v[16:19]
	v_mfma_f32_16x16x32_bf16 v[12:15], v[158:161], v[198:201], v[12:15]
	ds_read_b128 v[194:197], v152 offset:21504
	s_waitcnt lgkmcnt(2)
	v_mfma_f32_16x16x32_bf16 v[64:67], v[154:157], v[178:181], v[64:67]
	v_mfma_f32_16x16x32_bf16 v[60:63], v[170:173], v[178:181], v[60:63]
	ds_read_b128 v[202:205], v152 offset:23552
	s_waitcnt lgkmcnt(2)
	v_mfma_f32_16x16x32_bf16 v[48:51], v[154:157], v[186:189], v[48:51]
	v_mfma_f32_16x16x32_bf16 v[44:47], v[170:173], v[186:189], v[44:47]
	s_waitcnt lgkmcnt(1)
	v_mfma_f32_16x16x32_bf16 v[32:35], v[154:157], v[194:197], v[32:35]
	v_mfma_f32_16x16x32_bf16 v[28:31], v[170:173], v[194:197], v[28:31]
	s_waitcnt lgkmcnt(0)
; template <class Epi, class Sched>
; __device__ __forceinline__ void gemm_simple(PG8_LAS unsigned char* lds, const Gemm g, const Sched& S, const Epi& E, int wave_s) {
;     ...
;             const char* a2 = last ? nA : cA + (size_t)(t + 2) * kstep; const char* b2 = last ? nB : cB + (size_t)(t + 2) * kstep;
;             PG8_TILE(1, a2, b2, (!last || has_next));
	v_mfma_f32_16x16x32_bf16 v[16:19], v[154:157], v[202:205], v[16:19]
	v_mfma_f32_16x16x32_bf16 v[12:15], v[170:173], v[202:205], v[12:15]
	s_add_u32 s24, s60, 0x20080
	s_addc_u32 s25, s61, 0
	s_mov_b32 m0, s46
	s_nop 0
	global_load_lds_dwordx4 v136, s[24:25]
	s_mov_b32 m0, s50
	s_nop 0
	global_load_lds_dwordx4 v138, s[24:25]
	v_mfma_f32_16x16x32_bf16 v[56:59], v[206:209], v[174:177], v[56:59]
	s_add_u32 s24, s60, 0x100
	s_addc_u32 s25, s61, 0
	s_add_u32 s58, s58, 0x100
	v_mfma_f32_16x16x32_bf16 v[52:55], v[214:217], v[174:177], v[52:55]
	s_addc_u32 s59, s59, 0
	v_mfma_f32_16x16x32_bf16 v[40:43], v[206:209], v[182:185], v[40:43]
	v_mfma_f32_16x16x32_bf16 v[36:39], v[214:217], v[182:185], v[36:39]
	v_mfma_f32_16x16x32_bf16 v[24:27], v[206:209], v[190:193], v[24:27]
	v_mfma_f32_16x16x32_bf16 v[20:23], v[214:217], v[190:193], v[20:23]
	v_mfma_f32_16x16x32_bf16 v[4:7], v[206:209], v[198:201], v[4:7]
	v_mfma_f32_16x16x32_bf16 v[8:11], v[214:217], v[198:201], v[8:11]
	v_mfma_f32_16x16x32_bf16 v[56:59], v[210:213], v[178:181], v[56:59]
	v_mfma_f32_16x16x32_bf16 v[52:55], v[218:221], v[178:181], v[52:55]
	v_mfma_f32_16x16x32_bf16 v[40:43], v[210:213], v[186:189], v[40:43]
	v_mfma_f32_16x16x32_bf16 v[36:39], v[218:221], v[186:189], v[36:39]
	v_mfma_f32_16x16x32_bf16 v[24:27], v[210:213], v[194:197], v[24:27]
	v_mfma_f32_16x16x32_bf16 v[20:23], v[218:221], v[194:197], v[20:23]
	v_mfma_f32_16x16x32_bf16 v[4:7], v[210:213], v[202:205], v[4:7]
	v_mfma_f32_16x16x32_bf16 v[8:11], v[218:221], v[202:205], v[8:11]
	s_waitcnt vmcnt(2) lgkmcnt(0)
	s_barrier
	ds_read_b128 v[146:149], v134
	ds_read_b128 v[174:177], v152 offset:32768
	ds_read_b128 v[158:161], v134 offset:2048
	ds_read_b128 v[182:185], v152 offset:34816
	ds_read_b128 v[190:193], v152 offset:36864
	s_cmp_eq_u32 s57, s22
	s_cselect_b32 s25, s9, s25
	s_cselect_b32 s24, s54, s24
	s_cselect_b32 s59, s5, s59
	s_cselect_b32 s58, s55, s58
	s_mov_b32 m0, s36
	s_nop 0
	global_load_lds_dwordx4 v137, s[58:59]
	s_mov_b32 m0, s37
	s_nop 0
	global_load_lds_dwordx4 v139, s[58:59]
	s_waitcnt lgkmcnt(3)
	v_mfma_f32_16x16x32_bf16 v[128:131], v[146:149], v[174:177], v[128:131]
	s_waitcnt lgkmcnt(2)
	v_mfma_f32_16x16x32_bf16 v[124:127], v[158:161], v[174:177], v[124:127]
	ds_read_b128 v[198:201], v152 offset:38912
	s_waitcnt lgkmcnt(2)
	v_mfma_f32_16x16x32_bf16 v[112:115], v[146:149], v[182:185], v[112:115]
	v_mfma_f32_16x16x32_bf16 v[108:111], v[158:161], v[182:185], v[108:111]
	ds_read_b128 v[154:157], v134 offset:1024
	ds_read_b128 v[178:181], v152 offset:33792
	s_waitcnt lgkmcnt(3)
	v_mfma_f32_16x16x32_bf16 v[96:99], v[146:149], v[190:193], v[96:99]
	ds_read_b128 v[170:173], v134 offset:3072
	v_mfma_f32_16x16x32_bf16 v[92:95], v[158:161], v[190:193], v[92:95]
	ds_read_b128 v[186:189], v152 offset:35840
	s_waitcnt lgkmcnt(4)
	v_mfma_f32_16x16x32_bf16 v[80:83], v[146:149], v[198:201], v[80:83]
	v_mfma_f32_16x16x32_bf16 v[76:79], v[158:161], v[198:201], v[76:79]
	ds_read_b128 v[194:197], v152 offset:37888
	s_waitcnt lgkmcnt(3)
	v_mfma_f32_16x16x32_bf16 v[128:131], v[154:157], v[178:181], v[128:131]
	s_waitcnt lgkmcnt(2)
	v_mfma_f32_16x16x32_bf16 v[124:127], v[170:173], v[178:181], v[124:127]
	ds_read_b128 v[202:205], v152 offset:39936
	s_waitcnt lgkmcnt(2)
	v_mfma_f32_16x16x32_bf16 v[112:115], v[154:157], v[186:189], v[112:115]
	v_mfma_f32_16x16x32_bf16 v[108:111], v[170:173], v[186:189], v[108:111]
	ds_read_b128 v[206:209], v135
	s_waitcnt lgkmcnt(2)
	v_mfma_f32_16x16x32_bf16 v[96:99], v[154:157], v[194:197], v[96:99]
	ds_read_b128 v[214:217], v135 offset:2048
	v_mfma_f32_16x16x32_bf16 v[92:95], v[170:173], v[194:197], v[92:95]
	s_waitcnt lgkmcnt(2)
	v_mfma_f32_16x16x32_bf16 v[80:83], v[154:157], v[202:205], v[80:83]
	v_mfma_f32_16x16x32_bf16 v[76:79], v[170:173], v[202:205], v[76:79]
	s_mov_b32 m0, s17
	s_nop 0
	global_load_lds_dwordx4 v136, s[24:25]
	s_mov_b32 m0, s38
	s_nop 0
	global_load_lds_dwordx4 v138, s[24:25]
	s_waitcnt lgkmcnt(1)
	v_mfma_f32_16x16x32_bf16 v[120:123], v[206:209], v[174:177], v[120:123]
	s_waitcnt lgkmcnt(0)
	v_mfma_f32_16x16x32_bf16 v[116:119], v[214:217], v[174:177], v[116:119]
	v_mfma_f32_16x16x32_bf16 v[104:107], v[206:209], v[182:185], v[104:107]
	v_mfma_f32_16x16x32_bf16 v[100:103], v[214:217], v[182:185], v[100:103]
	ds_read_b128 v[210:213], v135 offset:1024
	v_mfma_f32_16x16x32_bf16 v[88:91], v[206:209], v[190:193], v[88:91]
	ds_read_b128 v[218:221], v135 offset:3072
	v_mfma_f32_16x16x32_bf16 v[84:87], v[214:217], v[190:193], v[84:87]
	v_mfma_f32_16x16x32_bf16 v[72:75], v[206:209], v[198:201], v[72:75]
	v_mfma_f32_16x16x32_bf16 v[68:71], v[214:217], v[198:201], v[68:71]
	s_waitcnt lgkmcnt(1)
	v_mfma_f32_16x16x32_bf16 v[120:123], v[210:213], v[178:181], v[120:123]
	s_waitcnt lgkmcnt(0)
	v_mfma_f32_16x16x32_bf16 v[116:119], v[218:221], v[178:181], v[116:119]
	v_mfma_f32_16x16x32_bf16 v[104:107], v[210:213], v[186:189], v[104:107]
	v_mfma_f32_16x16x32_bf16 v[100:103], v[218:221], v[186:189], v[100:103]
	v_mfma_f32_16x16x32_bf16 v[88:91], v[210:213], v[194:197], v[88:91]
	v_mfma_f32_16x16x32_bf16 v[84:87], v[218:221], v[194:197], v[84:87]
	v_mfma_f32_16x16x32_bf16 v[72:75], v[210:213], v[202:205], v[72:75]
	v_mfma_f32_16x16x32_bf16 v[68:71], v[218:221], v[202:205], v[68:71]
	s_waitcnt vmcnt(4) lgkmcnt(0)
	s_barrier
; __device__ __forceinline__ unsigned cvt_pk_bf16(float lo, float hi) { unsigned r; asm volatile("v_cvt_pk_bf16_f32 %0, %1, %2" : "=v"(r) : "v"(lo), "v"(hi)); return r; }
; #define LAS __attribute__((address_space(3)))
; __device__ __forceinline__ float bflo(unsigned w) { return __uint_as_float(w << 16); }
; __device__ __forceinline__ float bfhi(unsigned w) { return __uint_as_float(w & 0xffff0000u); }
; template <class Epi, class Sched>
; __device__ __forceinline__ void gemm_simple(PG8_LAS unsigned char* lds, const Gemm g, const Sched& S, const Epi& E, int wave_s) {
;     ...
;         for (; t < nt; t += 2) {
;             const bool last = (t == nt - 2);
;             PG8_TILE(0, cA + (size_t)(t + 1) * kstep, cB + (size_t)(t + 1) * kstep, true);
;             const char* a2 = last ? nA : cA + (size_t)(t + 2) * kstep; const char* b2 = last ? nB : cB + (size_t)(t + 2) * kstep;
;             PG8_TILE(1, a2, b2, (!last || has_next));
;     __device__ __forceinline__ void operator()(const f32x4 (&acc)[2][2][4][2], const Unit& u, int wr, int wc, int fr, int fq, const LAS float*) const {
;         const int row0 = u.pm * 256 + wr * 64 + fr, col0 = u.pn * 256 + wc * 32 + 8 * fq;
; #pragma unroll
;         for (int ai = 0; ai < 2; ++ai)
; #pragma unroll
;             for (int m = 0; m < 4; ++m) { const size_t row = (size_t)(row0 + ai * 128 + m * 16);
; #pragma unroll
;                 for (int bj = 0; bj < 2; ++bj) { const int col = col0 + bj * 128;
;                     const u32x4 g = *(const u32x4*)(G + row * NGATE + MODE * DM + col);
;                     f32x4 v0 = acc[ai][bj][m][0], v1 = acc[ai][bj][m][1];
;                     v0[0] *= bflo(g.x); v0[1] *= bfhi(g.x); v0[2] *= bflo(g.y); v0[3] *= bfhi(g.y); v1[0] *= bflo(g.z); v1[1] *= bfhi(g.z); v1[2] *= bflo(g.w); v1[3] *= bfhi(g.w);
;                     bf16_t* tp = T + row * DM + col;
;                     if (MODE == 1) { const u32x4 t = *(const u32x4*)tp;
;                         v0[0] += bflo(t.x); v0[1] += bfhi(t.x); v0[2] += bflo(t.y); v0[3] += bfhi(t.y); v1[0] += bflo(t.z); v1[1] += bfhi(t.z); v1[2] += bflo(t.w); v1[3] += bfhi(t.w); }
;                     u32x4 w; w.x = cvt_pk_bf16(v0[0], v0[1]); w.y = cvt_pk_bf16(v0[2], v0[3]); w.z = cvt_pk_bf16(v1[0], v1[1]); w.w = cvt_pk_bf16(v1[2], v1[3]);
;                     *(u32x4*)tp = w; } }
	ds_read_b128 v[174:177], v152 offset:49152
	ds_read_b128 v[182:185], v152 offset:51200
	ds_read_b128 v[190:193], v152 offset:53248
	s_add_u32 s58, s58, 0x20000
	s_addc_u32 s59, s59, 0
	s_mov_b32 m0, s39
	s_nop 0
	global_load_lds_dwordx4 v137, s[58:59]
	s_mov_b32 m0, s40
	s_nop 0
	global_load_lds_dwordx4 v139, s[58:59]
	s_waitcnt lgkmcnt(2)
	v_mfma_f32_16x16x32_bf16 v[64:67], v[146:149], v[174:177], v[64:67]
	v_mfma_f32_16x16x32_bf16 v[60:63], v[158:161], v[174:177], v[60:63]
	ds_read_b128 v[198:201], v152 offset:55296
	s_waitcnt lgkmcnt(2)
	v_mfma_f32_16x16x32_bf16 v[48:51], v[146:149], v[182:185], v[48:51]
	v_mfma_f32_16x16x32_bf16 v[44:47], v[158:161], v[182:185], v[44:47]
	ds_read_b128 v[178:181], v152 offset:50176
	s_waitcnt lgkmcnt(2)
	v_mfma_f32_16x16x32_bf16 v[32:35], v[146:149], v[190:193], v[32:35]
	v_mfma_f32_16x16x32_bf16 v[28:31], v[158:161], v[190:193], v[28:31]
	ds_read_b128 v[186:189], v152 offset:52224
	s_waitcnt lgkmcnt(2)
	v_mfma_f32_16x16x32_bf16 v[16:19], v[146:149], v[198:201], v[16:19]
	v_mfma_f32_16x16x32_bf16 v[12:15], v[158:161], v[198:201], v[12:15]
	ds_read_b128 v[194:197], v152 offset:54272
	s_waitcnt lgkmcnt(2)
	v_mfma_f32_16x16x32_bf16 v[64:67], v[154:157], v[178:181], v[64:67]
	v_mfma_f32_16x16x32_bf16 v[60:63], v[170:173], v[178:181], v[60:63]
	ds_read_b128 v[202:205], v152 offset:56320
	s_waitcnt lgkmcnt(2)
	v_mfma_f32_16x16x32_bf16 v[48:51], v[154:157], v[186:189], v[48:51]
	v_mfma_f32_16x16x32_bf16 v[44:47], v[170:173], v[186:189], v[44:47]
	s_waitcnt lgkmcnt(1)
	v_mfma_f32_16x16x32_bf16 v[32:35], v[154:157], v[194:197], v[32:35]
	v_mfma_f32_16x16x32_bf16 v[28:31], v[170:173], v[194:197], v[28:31]
	s_waitcnt lgkmcnt(0)
	v_mfma_f32_16x16x32_bf16 v[16:19], v[154:157], v[202:205], v[16:19]
	v_mfma_f32_16x16x32_bf16 v[12:15], v[170:173], v[202:205], v[12:15]
	s_add_u32 s24, s24, 0x20000
	s_addc_u32 s25, s25, 0
	s_mov_b32 m0, s41
	s_nop 0
	global_load_lds_dwordx4 v136, s[24:25]
	s_mov_b32 m0, s42
	s_nop 0
	global_load_lds_dwordx4 v138, s[24:25]
	v_mfma_f32_16x16x32_bf16 v[56:59], v[206:209], v[174:177], v[56:59]
	s_add_i32 s56, s56, 2
	s_add_u32 s22, s22, 0xffffff00
	s_addc_u32 s23, s23, -1
	v_mfma_f32_16x16x32_bf16 v[52:55], v[214:217], v[174:177], v[52:55]
	s_add_u32 s18, s18, 0x100
	s_addc_u32 s19, s19, 0
	s_add_u32 s20, s20, 0x100
	v_mfma_f32_16x16x32_bf16 v[40:43], v[206:209], v[182:185], v[40:43]
	s_addc_u32 s21, s21, 0
	s_cmp_lt_u32 s56, 6
	v_mfma_f32_16x16x32_bf16 v[36:39], v[214:217], v[182:185], v[36:39]
	v_mfma_f32_16x16x32_bf16 v[24:27], v[206:209], v[190:193], v[24:27]
	v_mfma_f32_16x16x32_bf16 v[20:23], v[214:217], v[190:193], v[20:23]
	v_mfma_f32_16x16x32_bf16 v[4:7], v[206:209], v[198:201], v[4:7]
	v_mfma_f32_16x16x32_bf16 v[8:11], v[214:217], v[198:201], v[8:11]
	s_cbranch_scc1 .Lrt_195
	v_mfma_f32_16x16x32_bf16 v[56:59], v[210:213], v[178:181], v[56:59]
	v_mfma_f32_16x16x32_bf16 v[52:55], v[218:221], v[178:181], v[52:55]
	v_mfma_f32_16x16x32_bf16 v[40:43], v[210:213], v[186:189], v[40:43]
	v_mfma_f32_16x16x32_bf16 v[36:39], v[218:221], v[186:189], v[36:39]
	v_mfma_f32_16x16x32_bf16 v[24:27], v[210:213], v[194:197], v[24:27]
	v_mfma_f32_16x16x32_bf16 v[20:23], v[218:221], v[194:197], v[20:23]
	v_mfma_f32_16x16x32_bf16 v[4:7], v[210:213], v[202:205], v[4:7]
	v_mfma_f32_16x16x32_bf16 v[8:11], v[218:221], v[202:205], v[8:11]
	v_mov_b32_e32 v132, v141
	s_lshl_b32 s5, s16, 8
	v_mbcnt_lo_u32_b32 v132, -1, v132
	v_mbcnt_hi_u32_b32 v132, -1, v132
	s_add_i32 s5, s5, s29
	v_and_or_b32 v134, v132, 15, s5
	s_lshl_b32 s5, s53, 8
	v_ashrrev_i32_e32 v132, 1, v132
	s_or_b32 s5, s5, s35
	v_and_b32_e32 v132, -8, v132
	v_add_u32_e32 v132, s5, v132
	v_ashrrev_i32_e32 v135, 31, v134
	v_lshlrev_b64 v[142:143], 13, v[134:135]
	v_ashrrev_i32_e32 v133, 31, v132
	v_lshl_add_u64 v[142:143], s[2:3], 0, v[142:143]
	v_lshlrev_b64 v[132:133], 1, v[132:133]
	v_lshl_add_u64 v[142:143], v[142:143], 0, v[132:133]
	v_lshlrev_b32_e32 v236, 13, v134
	v_add_u32_e32 v236, v236, v132
	global_load_dwordx4 v[172:175], v236, s[2:3]
	global_load_dwordx4 v[176:179], v236, s[2:3] offset:256
	v_add_u32_e32 v237, 0x20000, v236
	global_load_dwordx4 v[180:183], v237, s[2:3]
	global_load_dwordx4 v[184:187], v237, s[2:3] offset:256
	v_add_u32_e32 v237, 0x40000, v236
	global_load_dwordx4 v[188:191], v237, s[2:3]
	global_load_dwordx4 v[192:195], v237, s[2:3] offset:256
	v_add_u32_e32 v237, 0x60000, v236
	global_load_dwordx4 v[196:199], v237, s[2:3]
	global_load_dwordx4 v[200:203], v237, s[2:3] offset:256
	v_add_u32_e32 v237, 0x100000, v236
	global_load_dwordx4 v[204:207], v237, s[2:3]
	global_load_dwordx4 v[208:211], v237, s[2:3] offset:256
	v_add_u32_e32 v237, 0x120000, v236
	global_load_dwordx4 v[212:215], v237, s[2:3]
	global_load_dwordx4 v[216:219], v237, s[2:3] offset:256
	v_add_u32_e32 v237, 0x140000, v236
	global_load_dwordx4 v[220:223], v237, s[2:3]
	global_load_dwordx4 v[224:227], v237, s[2:3] offset:256
	v_add_u32_e32 v237, 0x160000, v236
	global_load_dwordx4 v[228:231], v237, s[2:3]
	global_load_dwordx4 v[232:235], v237, s[2:3] offset:256
	v_lshlrev_b64 v[144:145], 12, v[134:135]
	s_andn2_b64 vcc, exec, s[6:7]
	s_mov_b32 s53, s4
	s_mov_b32 s16, s8
	s_mov_b64 s[18:19], s[14:15]
	s_mov_b64 s[20:21], s[10:11]
	s_mov_b32 s9, s52
	s_waitcnt vmcnt(15)
; __device__ __forceinline__ unsigned cvt_pk_bf16(float lo, float hi) { unsigned r; asm volatile("v_cvt_pk_bf16_f32 %0, %1, %2" : "=v"(r) : "v"(lo), "v"(hi)); return r; }
; #define LAS __attribute__((address_space(3)))
; __device__ __forceinline__ float bflo(unsigned w) { return __uint_as_float(w << 16); }
; __device__ __forceinline__ float bfhi(unsigned w) { return __uint_as_float(w & 0xffff0000u); }
;     __device__ __forceinline__ void operator()(const f32x4 (&acc)[2][2][4][2], const Unit& u, int wr, int wc, int fr, int fq, const LAS float*) const {
;         const int row0 = u.pm * 256 + wr * 64 + fr, col0 = u.pn * 256 + wc * 32 + 8 * fq;
; #pragma unroll
;         for (int ai = 0; ai < 2; ++ai)
; #pragma unroll
;             for (int m = 0; m < 4; ++m) { const size_t row = (size_t)(row0 + ai * 128 + m * 16);
; #pragma unroll
;                 for (int bj = 0; bj < 2; ++bj) { const int col = col0 + bj * 128;
;                     const u32x4 g = *(const u32x4*)(G + row * NGATE + MODE * DM + col);
;                     f32x4 v0 = acc[ai][bj][m][0], v1 = acc[ai][bj][m][1];
;                     v0[0] *= bflo(g.x); v0[1] *= bfhi(g.x); v0[2] *= bflo(g.y); v0[3] *= bfhi(g.y); v1[0] *= bflo(g.z); v1[1] *= bfhi(g.z); v1[2] *= bflo(g.w); v1[3] *= bfhi(g.w);
;                     bf16_t* tp = T + row * DM + col;
;                     if (MODE == 1) { const u32x4 t = *(const u32x4*)tp;
;                         v0[0] += bflo(t.x); v0[1] += bfhi(t.x); v0[2] += bflo(t.y); v0[3] += bfhi(t.y); v1[0] += bflo(t.z); v1[1] += bfhi(t.z); v1[2] += bflo(t.w); v1[3] += bfhi(t.w); }
;                     u32x4 w; w.x = cvt_pk_bf16(v0[0], v0[1]); w.y = cvt_pk_bf16(v0[2], v0[3]); w.z = cvt_pk_bf16(v1[0], v1[1]); w.w = cvt_pk_bf16(v1[2], v1[3]);
;                     *(u32x4*)tp = w; } }
	s_nop 1
	v_mov_b64_e32 v[146:147], v[172:173]
	v_mov_b64_e32 v[148:149], v[174:175]
	v_lshlrev_b32_e32 v135, 16, v146
	v_mul_f32_e32 v135, v128, v135
	v_and_b32_e32 v128, 0xffff0000, v146
	v_mul_f32_e32 v146, v129, v128
	v_lshlrev_b32_e32 v128, 16, v147
	v_mul_f32_e32 v130, v130, v128
	v_and_b32_e32 v128, 0xffff0000, v147
	v_mul_f32_e32 v131, v131, v128
	v_lshlrev_b32_e32 v128, 16, v148
	v_mul_f32_e32 v147, v124, v128
	v_and_b32_e32 v124, 0xffff0000, v148
	v_mul_f32_e32 v148, v125, v124
	v_lshlrev_b32_e32 v124, 16, v149
	v_mul_f32_e32 v153, v126, v124
	v_and_b32_e32 v124, 0xffff0000, v149
	v_mul_f32_e32 v127, v127, v124
	v_lshl_add_u64 v[124:125], s[12:13], 0, v[144:145]
	v_lshl_add_u64 v[128:129], v[124:125], 0, v[132:133]
	v_cvt_pk_bf16_f32 v124, v135, v146
	v_cvt_pk_bf16_f32 v125, v130, v131
	v_cvt_pk_bf16_f32 v126, v147, v148
	v_cvt_pk_bf16_f32 v127, v153, v127
	global_store_dwordx4 v[128:129], v[124:127], off
	s_waitcnt vmcnt(15)
	s_nop 1
	v_mov_b64_e32 v[124:125], v[176:177]
	v_mov_b64_e32 v[126:127], v[178:179]
	v_lshlrev_b32_e32 v130, 16, v124
	v_and_b32_e32 v124, 0xffff0000, v124
	v_mul_f32_e32 v121, v121, v124
	v_lshlrev_b32_e32 v124, 16, v125
	v_mul_f32_e32 v122, v122, v124
	v_and_b32_e32 v124, 0xffff0000, v125
	v_mul_f32_e32 v123, v123, v124
	v_lshlrev_b32_e32 v124, 16, v126
	v_mul_f32_e32 v124, v116, v124
	v_and_b32_e32 v116, 0xffff0000, v126
	v_mul_f32_e32 v125, v117, v116
	v_lshlrev_b32_e32 v116, 16, v127
	v_mul_f32_e32 v126, v118, v116
	v_and_b32_e32 v116, 0xffff0000, v127
	v_mul_f32_e32 v120, v120, v130
	v_mul_f32_e32 v119, v119, v116
	v_cvt_pk_bf16_f32 v116, v120, v121
	v_cvt_pk_bf16_f32 v117, v122, v123
	v_cvt_pk_bf16_f32 v118, v124, v125
	v_cvt_pk_bf16_f32 v119, v126, v119
	global_store_dwordx4 v[128:129], v[116:119], off offset:256
	s_nop 1
	v_or_b32_e32 v116, 16, v134
	v_ashrrev_i32_e32 v117, 31, v116
	v_lshlrev_b64 v[118:119], 13, v[116:117]
	v_lshlrev_b64 v[120:121], 12, v[116:117]
	v_lshl_add_u64 v[116:117], s[2:3], 0, v[118:119]
	v_lshl_add_u64 v[122:123], v[116:117], 0, v[132:133]
	s_waitcnt vmcnt(15)
	s_nop 1
	v_mov_b64_e32 v[116:117], v[180:181]
	v_mov_b64_e32 v[118:119], v[182:183]
	v_lshlrev_b32_e32 v124, 16, v116
	v_mul_f32_e32 v124, v112, v124
	v_and_b32_e32 v112, 0xffff0000, v116
	v_mul_f32_e32 v116, v113, v112
	v_lshlrev_b32_e32 v112, 16, v117
	v_mul_f32_e32 v114, v114, v112
	v_and_b32_e32 v112, 0xffff0000, v117
	v_mul_f32_e32 v115, v115, v112
	v_lshlrev_b32_e32 v112, 16, v118
	v_mul_f32_e32 v117, v108, v112
	v_and_b32_e32 v108, 0xffff0000, v118
	v_mul_f32_e32 v118, v109, v108
	v_lshlrev_b32_e32 v108, 16, v119
	v_mul_f32_e32 v125, v110, v108
	v_and_b32_e32 v108, 0xffff0000, v119
	v_mul_f32_e32 v111, v111, v108
	v_lshl_add_u64 v[108:109], s[12:13], 0, v[120:121]
	v_lshl_add_u64 v[112:113], v[108:109], 0, v[132:133]
	v_cvt_pk_bf16_f32 v108, v124, v116
	v_cvt_pk_bf16_f32 v109, v114, v115
	v_cvt_pk_bf16_f32 v110, v117, v118
	v_cvt_pk_bf16_f32 v111, v125, v111
	global_store_dwordx4 v[112:113], v[108:111], off
	s_waitcnt vmcnt(15)
	s_nop 1
	v_mov_b64_e32 v[108:109], v[184:185]
	v_mov_b64_e32 v[110:111], v[186:187]
	v_lshlrev_b32_e32 v114, 16, v108
	v_and_b32_e32 v108, 0xffff0000, v108
	v_mul_f32_e32 v105, v105, v108
	v_lshlrev_b32_e32 v108, 16, v109
	v_mul_f32_e32 v106, v106, v108
	v_and_b32_e32 v108, 0xffff0000, v109
	v_mul_f32_e32 v107, v107, v108
	v_lshlrev_b32_e32 v108, 16, v110
	v_mul_f32_e32 v108, v100, v108
	v_and_b32_e32 v100, 0xffff0000, v110
	v_mul_f32_e32 v109, v101, v100
	v_lshlrev_b32_e32 v100, 16, v111
	v_mul_f32_e32 v110, v102, v100
	v_and_b32_e32 v100, 0xffff0000, v111
	v_mul_f32_e32 v104, v104, v114
	v_mul_f32_e32 v103, v103, v100
	v_cvt_pk_bf16_f32 v100, v104, v105
	v_cvt_pk_bf16_f32 v101, v106, v107
	v_cvt_pk_bf16_f32 v102, v108, v109
	v_cvt_pk_bf16_f32 v103, v110, v103
	global_store_dwordx4 v[112:113], v[100:103], off offset:256
	s_nop 1
	v_or_b32_e32 v100, 32, v134
	v_ashrrev_i32_e32 v101, 31, v100
	v_lshlrev_b64 v[102:103], 13, v[100:101]
	v_lshlrev_b64 v[104:105], 12, v[100:101]
	v_lshl_add_u64 v[100:101], s[2:3], 0, v[102:103]
	v_lshl_add_u64 v[106:107], v[100:101], 0, v[132:133]
	s_waitcnt vmcnt(15)
	s_nop 1
	v_mov_b64_e32 v[100:101], v[188:189]
	v_mov_b64_e32 v[102:103], v[190:191]
	v_lshlrev_b32_e32 v108, 16, v100
	v_mul_f32_e32 v108, v96, v108
	v_and_b32_e32 v96, 0xffff0000, v100
	v_mul_f32_e32 v100, v97, v96
	v_lshlrev_b32_e32 v96, 16, v101
	v_mul_f32_e32 v98, v98, v96
	v_and_b32_e32 v96, 0xffff0000, v101
	v_mul_f32_e32 v99, v99, v96
	v_lshlrev_b32_e32 v96, 16, v102
	v_mul_f32_e32 v101, v92, v96
	v_and_b32_e32 v92, 0xffff0000, v102
	v_mul_f32_e32 v102, v93, v92
	v_lshlrev_b32_e32 v92, 16, v103
	v_mul_f32_e32 v109, v94, v92
	v_and_b32_e32 v92, 0xffff0000, v103
	v_mul_f32_e32 v95, v95, v92
	v_lshl_add_u64 v[92:93], s[12:13], 0, v[104:105]
	v_lshl_add_u64 v[96:97], v[92:93], 0, v[132:133]
	v_cvt_pk_bf16_f32 v92, v108, v100
	v_cvt_pk_bf16_f32 v93, v98, v99
	v_cvt_pk_bf16_f32 v94, v101, v102
	v_cvt_pk_bf16_f32 v95, v109, v95
	global_store_dwordx4 v[96:97], v[92:95], off
	s_waitcnt vmcnt(15)
	s_nop 1
	v_mov_b64_e32 v[92:93], v[192:193]
	v_mov_b64_e32 v[94:95], v[194:195]
	v_lshlrev_b32_e32 v98, 16, v92
	v_and_b32_e32 v92, 0xffff0000, v92
	v_mul_f32_e32 v89, v89, v92
	v_lshlrev_b32_e32 v92, 16, v93
	v_mul_f32_e32 v90, v90, v92
	v_and_b32_e32 v92, 0xffff0000, v93
	v_mul_f32_e32 v91, v91, v92
	v_lshlrev_b32_e32 v92, 16, v94
	v_mul_f32_e32 v92, v84, v92
	v_and_b32_e32 v84, 0xffff0000, v94
	v_mul_f32_e32 v93, v85, v84
	v_lshlrev_b32_e32 v84, 16, v95
	v_mul_f32_e32 v94, v86, v84
	v_and_b32_e32 v84, 0xffff0000, v95
	v_mul_f32_e32 v88, v88, v98
	v_mul_f32_e32 v87, v87, v84
	v_cvt_pk_bf16_f32 v84, v88, v89
	v_cvt_pk_bf16_f32 v85, v90, v91
	v_cvt_pk_bf16_f32 v86, v92, v93
	v_cvt_pk_bf16_f32 v87, v94, v87
	global_store_dwordx4 v[96:97], v[84:87], off offset:256
	s_nop 1
	v_or_b32_e32 v84, 48, v134
	v_ashrrev_i32_e32 v85, 31, v84
	v_lshlrev_b64 v[86:87], 13, v[84:85]
	v_lshlrev_b64 v[88:89], 12, v[84:85]
	v_lshl_add_u64 v[84:85], s[2:3], 0, v[86:87]
	v_lshl_add_u64 v[90:91], v[84:85], 0, v[132:133]
	s_waitcnt vmcnt(15)
; __device__ __forceinline__ unsigned cvt_pk_bf16(float lo, float hi) { unsigned r; asm volatile("v_cvt_pk_bf16_f32 %0, %1, %2" : "=v"(r) : "v"(lo), "v"(hi)); return r; }
; #define LAS __attribute__((address_space(3)))
; __device__ __forceinline__ float bflo(unsigned w) { return __uint_as_float(w << 16); }
; __device__ __forceinline__ float bfhi(unsigned w) { return __uint_as_float(w & 0xffff0000u); }
;     __device__ __forceinline__ void operator()(const f32x4 (&acc)[2][2][4][2], const Unit& u, int wr, int wc, int fr, int fq, const LAS float*) const {
;         const int row0 = u.pm * 256 + wr * 64 + fr, col0 = u.pn * 256 + wc * 32 + 8 * fq;
; #pragma unroll
;         for (int ai = 0; ai < 2; ++ai)
; #pragma unroll
;             for (int m = 0; m < 4; ++m) { const size_t row = (size_t)(row0 + ai * 128 + m * 16);
; #pragma unroll
;                 for (int bj = 0; bj < 2; ++bj) { const int col = col0 + bj * 128;
;                     const u32x4 g = *(const u32x4*)(G + row * NGATE + MODE * DM + col);
;                     f32x4 v0 = acc[ai][bj][m][0], v1 = acc[ai][bj][m][1];
;                     v0[0] *= bflo(g.x); v0[1] *= bfhi(g.x); v0[2] *= bflo(g.y); v0[3] *= bfhi(g.y); v1[0] *= bflo(g.z); v1[1] *= bfhi(g.z); v1[2] *= bflo(g.w); v1[3] *= bfhi(g.w);
;                     bf16_t* tp = T + row * DM + col;
;                     if (MODE == 1) { const u32x4 t = *(const u32x4*)tp;
;                         v0[0] += bflo(t.x); v0[1] += bfhi(t.x); v0[2] += bflo(t.y); v0[3] += bfhi(t.y); v1[0] += bflo(t.z); v1[1] += bfhi(t.z); v1[2] += bflo(t.w); v1[3] += bfhi(t.w); }
;                     u32x4 w; w.x = cvt_pk_bf16(v0[0], v0[1]); w.y = cvt_pk_bf16(v0[2], v0[3]); w.z = cvt_pk_bf16(v1[0], v1[1]); w.w = cvt_pk_bf16(v1[2], v1[3]);
;                     *(u32x4*)tp = w; } }
	s_nop 1
	v_mov_b64_e32 v[84:85], v[196:197]
	v_mov_b64_e32 v[86:87], v[198:199]
	v_lshlrev_b32_e32 v92, 16, v84
	v_mul_f32_e32 v92, v80, v92
	v_and_b32_e32 v80, 0xffff0000, v84
	v_mul_f32_e32 v84, v81, v80
	v_lshlrev_b32_e32 v80, 16, v85
	v_mul_f32_e32 v82, v82, v80
	v_and_b32_e32 v80, 0xffff0000, v85
	v_mul_f32_e32 v83, v83, v80
	v_lshlrev_b32_e32 v80, 16, v86
	v_mul_f32_e32 v85, v76, v80
	v_and_b32_e32 v76, 0xffff0000, v86
	v_mul_f32_e32 v86, v77, v76
	v_lshlrev_b32_e32 v76, 16, v87
	v_mul_f32_e32 v93, v78, v76
	v_and_b32_e32 v76, 0xffff0000, v87
	v_mul_f32_e32 v79, v79, v76
	v_lshl_add_u64 v[76:77], s[12:13], 0, v[88:89]
	v_lshl_add_u64 v[80:81], v[76:77], 0, v[132:133]
	v_cvt_pk_bf16_f32 v76, v92, v84
	v_cvt_pk_bf16_f32 v77, v82, v83
	v_cvt_pk_bf16_f32 v78, v85, v86
	v_cvt_pk_bf16_f32 v79, v93, v79
	global_store_dwordx4 v[80:81], v[76:79], off
	s_waitcnt vmcnt(15)
	s_nop 1
	v_mov_b64_e32 v[76:77], v[200:201]
	v_mov_b64_e32 v[78:79], v[202:203]
	v_lshlrev_b32_e32 v82, 16, v76
	v_and_b32_e32 v76, 0xffff0000, v76
	v_mul_f32_e32 v73, v73, v76
	v_lshlrev_b32_e32 v76, 16, v77
	v_mul_f32_e32 v74, v74, v76
	v_and_b32_e32 v76, 0xffff0000, v77
	v_mul_f32_e32 v75, v75, v76
	v_lshlrev_b32_e32 v76, 16, v78
	v_mul_f32_e32 v76, v68, v76
	v_and_b32_e32 v68, 0xffff0000, v78
	v_mul_f32_e32 v77, v69, v68
	v_lshlrev_b32_e32 v68, 16, v79
	v_mul_f32_e32 v78, v70, v68
	v_and_b32_e32 v68, 0xffff0000, v79
	v_mul_f32_e32 v72, v72, v82
	v_mul_f32_e32 v71, v71, v68
	v_cvt_pk_bf16_f32 v68, v72, v73
	v_cvt_pk_bf16_f32 v69, v74, v75
	v_cvt_pk_bf16_f32 v70, v76, v77
	v_cvt_pk_bf16_f32 v71, v78, v71
	global_store_dwordx4 v[80:81], v[68:71], off offset:256
	s_nop 1
	v_add_u32_e32 v68, 0x80, v134
	v_ashrrev_i32_e32 v69, 31, v68
	v_lshlrev_b64 v[70:71], 13, v[68:69]
	v_lshlrev_b64 v[72:73], 12, v[68:69]
	v_lshl_add_u64 v[68:69], s[2:3], 0, v[70:71]
	v_lshl_add_u64 v[74:75], v[68:69], 0, v[132:133]
	s_waitcnt vmcnt(15)
	s_nop 1
	v_mov_b64_e32 v[68:69], v[204:205]
	v_mov_b64_e32 v[70:71], v[206:207]
	v_lshlrev_b32_e32 v76, 16, v68
	v_mul_f32_e32 v76, v64, v76
	v_and_b32_e32 v64, 0xffff0000, v68
	v_mul_f32_e32 v68, v65, v64
	v_lshlrev_b32_e32 v64, 16, v69
	v_mul_f32_e32 v66, v66, v64
	v_and_b32_e32 v64, 0xffff0000, v69
	v_mul_f32_e32 v67, v67, v64
	v_lshlrev_b32_e32 v64, 16, v70
	v_mul_f32_e32 v69, v60, v64
	v_and_b32_e32 v60, 0xffff0000, v70
	v_mul_f32_e32 v70, v61, v60
	v_lshlrev_b32_e32 v60, 16, v71
	v_mul_f32_e32 v77, v62, v60
	v_and_b32_e32 v60, 0xffff0000, v71
	v_mul_f32_e32 v63, v63, v60
	v_lshl_add_u64 v[60:61], s[12:13], 0, v[72:73]
	v_lshl_add_u64 v[64:65], v[60:61], 0, v[132:133]
	v_cvt_pk_bf16_f32 v60, v76, v68
	v_cvt_pk_bf16_f32 v61, v66, v67
	v_cvt_pk_bf16_f32 v62, v69, v70
	v_cvt_pk_bf16_f32 v63, v77, v63
	global_store_dwordx4 v[64:65], v[60:63], off
	s_waitcnt vmcnt(15)
	s_nop 1
	v_mov_b64_e32 v[60:61], v[208:209]
	v_mov_b64_e32 v[62:63], v[210:211]
	v_lshlrev_b32_e32 v66, 16, v60
	v_and_b32_e32 v60, 0xffff0000, v60
	v_mul_f32_e32 v57, v57, v60
	v_lshlrev_b32_e32 v60, 16, v61
	v_mul_f32_e32 v58, v58, v60
	v_and_b32_e32 v60, 0xffff0000, v61
	v_mul_f32_e32 v59, v59, v60
	v_lshlrev_b32_e32 v60, 16, v62
	v_mul_f32_e32 v60, v52, v60
	v_and_b32_e32 v52, 0xffff0000, v62
	v_mul_f32_e32 v61, v53, v52
	v_lshlrev_b32_e32 v52, 16, v63
	v_mul_f32_e32 v62, v54, v52
	v_and_b32_e32 v52, 0xffff0000, v63
	v_mul_f32_e32 v56, v56, v66
	v_mul_f32_e32 v55, v55, v52
	v_cvt_pk_bf16_f32 v52, v56, v57
	v_cvt_pk_bf16_f32 v53, v58, v59
	v_cvt_pk_bf16_f32 v54, v60, v61
	v_cvt_pk_bf16_f32 v55, v62, v55
	global_store_dwordx4 v[64:65], v[52:55], off offset:256
	s_nop 1
	v_add_u32_e32 v52, 0x90, v134
	v_ashrrev_i32_e32 v53, 31, v52
	v_lshlrev_b64 v[54:55], 13, v[52:53]
	v_lshlrev_b64 v[56:57], 12, v[52:53]
	v_lshl_add_u64 v[52:53], s[2:3], 0, v[54:55]
	v_lshl_add_u64 v[58:59], v[52:53], 0, v[132:133]
	s_waitcnt vmcnt(15)
	s_nop 1
	v_mov_b64_e32 v[52:53], v[212:213]
	v_mov_b64_e32 v[54:55], v[214:215]
	v_lshlrev_b32_e32 v60, 16, v52
	v_mul_f32_e32 v60, v48, v60
	v_and_b32_e32 v48, 0xffff0000, v52
	v_mul_f32_e32 v52, v49, v48
	v_lshlrev_b32_e32 v48, 16, v53
	v_mul_f32_e32 v50, v50, v48
	v_and_b32_e32 v48, 0xffff0000, v53
	v_mul_f32_e32 v51, v51, v48
	v_lshlrev_b32_e32 v48, 16, v54
	v_mul_f32_e32 v53, v44, v48
	v_and_b32_e32 v44, 0xffff0000, v54
	v_mul_f32_e32 v54, v45, v44
	v_lshlrev_b32_e32 v44, 16, v55
	v_mul_f32_e32 v61, v46, v44
	v_and_b32_e32 v44, 0xffff0000, v55
	v_mul_f32_e32 v47, v47, v44
	v_lshl_add_u64 v[44:45], s[12:13], 0, v[56:57]
	v_lshl_add_u64 v[48:49], v[44:45], 0, v[132:133]
	v_cvt_pk_bf16_f32 v44, v60, v52
	v_cvt_pk_bf16_f32 v45, v50, v51
	v_cvt_pk_bf16_f32 v46, v53, v54
	v_cvt_pk_bf16_f32 v47, v61, v47
	global_store_dwordx4 v[48:49], v[44:47], off
	s_waitcnt vmcnt(15)
; __device__ __forceinline__ unsigned cvt_pk_bf16(float lo, float hi) { unsigned r; asm volatile("v_cvt_pk_bf16_f32 %0, %1, %2" : "=v"(r) : "v"(lo), "v"(hi)); return r; }
; #define PG8_SYNC() do { asm volatile("s_waitcnt vmcnt(0) lgkmcnt(0)" ::: "memory"); __builtin_amdgcn_s_barrier(); asm volatile("" ::: "memory"); } while (0)
; #define LAS __attribute__((address_space(3)))
; template <class Epi, class Sched>
; __device__ __forceinline__ void gemm_simple(PG8_LAS unsigned char* lds, const Gemm g, const Sched& S, const Epi& E, int wave_s) {
;     ...
;         if (!has_next) break;
; #pragma unroll
;         for (int a = 0; a < 2; ++a)
; #pragma unroll
;             for (int b = 0; b < 2; ++b)
; #pragma unroll
;                 for (int m = 0; m < 4; ++m)
; #pragma unroll
;                     for (int n = 0; n < 2; ++n) acc[a][b][m][n] = (f32x4){zero_o, zero_o, zero_o, zero_o};
;         cur = nxt; cA = nA; cB = nB; ++ui;
;     }
;     PG8_SYNC();
;     __device__ __forceinline__ void operator()(const f32x4 (&acc)[2][2][4][2], const Unit& u, int wr, int wc, int fr, int fq, const LAS float*) const {
;         const int row0 = u.pm * 256 + wr * 64 + fr, col0 = u.pn * 256 + wc * 32 + 8 * fq;
; #pragma unroll
;         for (int ai = 0; ai < 2; ++ai)
; #pragma unroll
;             for (int m = 0; m < 4; ++m) { const size_t row = (size_t)(row0 + ai * 128 + m * 16);
; #pragma unroll
;                 for (int bj = 0; bj < 2; ++bj) { const int col = col0 + bj * 128;
;                     const u32x4 g = *(const u32x4*)(G + row * NGATE + MODE * DM + col);
;                     f32x4 v0 = acc[ai][bj][m][0], v1 = acc[ai][bj][m][1];
;                     v0[0] *= bflo(g.x); v0[1] *= bfhi(g.x); v0[2] *= bflo(g.y); v0[3] *= bfhi(g.y); v1[0] *= bflo(g.z); v1[1] *= bfhi(g.z); v1[2] *= bflo(g.w); v1[3] *= bfhi(g.w);
;                     bf16_t* tp = T + row * DM + col;
;                     if (MODE == 1) { const u32x4 t = *(const u32x4*)tp;
;                         v0[0] += bflo(t.x); v0[1] += bfhi(t.x); v0[2] += bflo(t.y); v0[3] += bfhi(t.y); v1[0] += bflo(t.z); v1[1] += bfhi(t.z); v1[2] += bflo(t.w); v1[3] += bfhi(t.w); }
;                     u32x4 w; w.x = cvt_pk_bf16(v0[0], v0[1]); w.y = cvt_pk_bf16(v0[2], v0[3]); w.z = cvt_pk_bf16(v1[0], v1[1]); w.w = cvt_pk_bf16(v1[2], v1[3]);
;                     *(u32x4*)tp = w; } }
	s_nop 1
	v_mov_b64_e32 v[44:45], v[216:217]
	v_mov_b64_e32 v[46:47], v[218:219]
	v_lshlrev_b32_e32 v50, 16, v44
	v_and_b32_e32 v44, 0xffff0000, v44
	v_mul_f32_e32 v41, v41, v44
	v_lshlrev_b32_e32 v44, 16, v45
	v_mul_f32_e32 v42, v42, v44
	v_and_b32_e32 v44, 0xffff0000, v45
	v_mul_f32_e32 v43, v43, v44
	v_lshlrev_b32_e32 v44, 16, v46
	v_mul_f32_e32 v44, v36, v44
	v_and_b32_e32 v36, 0xffff0000, v46
	v_mul_f32_e32 v45, v37, v36
	v_lshlrev_b32_e32 v36, 16, v47
	v_mul_f32_e32 v46, v38, v36
	v_and_b32_e32 v36, 0xffff0000, v47
	v_mul_f32_e32 v40, v40, v50
	v_mul_f32_e32 v39, v39, v36
	v_cvt_pk_bf16_f32 v36, v40, v41
	v_cvt_pk_bf16_f32 v37, v42, v43
	v_cvt_pk_bf16_f32 v38, v44, v45
	v_cvt_pk_bf16_f32 v39, v46, v39
	global_store_dwordx4 v[48:49], v[36:39], off offset:256
	s_nop 1
	v_add_u32_e32 v36, 0xa0, v134
	v_ashrrev_i32_e32 v37, 31, v36
	v_lshlrev_b64 v[38:39], 13, v[36:37]
	v_lshlrev_b64 v[40:41], 12, v[36:37]
	v_lshl_add_u64 v[36:37], s[2:3], 0, v[38:39]
	v_lshl_add_u64 v[42:43], v[36:37], 0, v[132:133]
	s_waitcnt vmcnt(15)
	s_nop 1
	v_mov_b64_e32 v[36:37], v[220:221]
	v_mov_b64_e32 v[38:39], v[222:223]
	v_lshlrev_b32_e32 v44, 16, v36
	v_mul_f32_e32 v44, v32, v44
	v_and_b32_e32 v32, 0xffff0000, v36
	v_mul_f32_e32 v36, v33, v32
	v_lshlrev_b32_e32 v32, 16, v37
	v_mul_f32_e32 v34, v34, v32
	v_and_b32_e32 v32, 0xffff0000, v37
	v_mul_f32_e32 v35, v35, v32
	v_lshlrev_b32_e32 v32, 16, v38
	v_mul_f32_e32 v37, v28, v32
	v_and_b32_e32 v28, 0xffff0000, v38
	v_mul_f32_e32 v38, v29, v28
	v_lshlrev_b32_e32 v28, 16, v39
	v_mul_f32_e32 v45, v30, v28
	v_and_b32_e32 v28, 0xffff0000, v39
	v_mul_f32_e32 v31, v31, v28
	v_lshl_add_u64 v[28:29], s[12:13], 0, v[40:41]
	v_lshl_add_u64 v[32:33], v[28:29], 0, v[132:133]
	v_cvt_pk_bf16_f32 v28, v44, v36
	v_cvt_pk_bf16_f32 v29, v34, v35
	v_cvt_pk_bf16_f32 v30, v37, v38
	v_cvt_pk_bf16_f32 v31, v45, v31
	global_store_dwordx4 v[32:33], v[28:31], off
	s_waitcnt vmcnt(15)
	s_nop 1
	v_mov_b64_e32 v[28:29], v[224:225]
	v_mov_b64_e32 v[30:31], v[226:227]
	v_lshlrev_b32_e32 v34, 16, v28
	v_and_b32_e32 v28, 0xffff0000, v28
	v_mul_f32_e32 v25, v25, v28
	v_lshlrev_b32_e32 v28, 16, v29
	v_mul_f32_e32 v26, v26, v28
	v_and_b32_e32 v28, 0xffff0000, v29
	v_mul_f32_e32 v27, v27, v28
	v_lshlrev_b32_e32 v28, 16, v30
	v_mul_f32_e32 v28, v20, v28
	v_and_b32_e32 v20, 0xffff0000, v30
	v_mul_f32_e32 v29, v21, v20
	v_lshlrev_b32_e32 v20, 16, v31
	v_mul_f32_e32 v30, v22, v20
	v_and_b32_e32 v20, 0xffff0000, v31
	v_mul_f32_e32 v24, v24, v34
	v_mul_f32_e32 v23, v23, v20
	v_cvt_pk_bf16_f32 v20, v24, v25
	v_cvt_pk_bf16_f32 v21, v26, v27
	v_cvt_pk_bf16_f32 v22, v28, v29
	v_cvt_pk_bf16_f32 v23, v30, v23
	global_store_dwordx4 v[32:33], v[20:23], off offset:256
	s_nop 1
	v_add_u32_e32 v20, 0xb0, v134
	v_ashrrev_i32_e32 v21, 31, v20
	v_lshlrev_b64 v[22:23], 13, v[20:21]
	v_lshlrev_b64 v[24:25], 12, v[20:21]
	v_lshl_add_u64 v[20:21], s[2:3], 0, v[22:23]
	v_lshl_add_u64 v[26:27], v[20:21], 0, v[132:133]
	s_waitcnt vmcnt(15)
	s_nop 1
	v_mov_b64_e32 v[20:21], v[228:229]
	v_mov_b64_e32 v[22:23], v[230:231]
	v_lshlrev_b32_e32 v28, 16, v20
	v_mul_f32_e32 v28, v16, v28
	v_and_b32_e32 v16, 0xffff0000, v20
	v_mul_f32_e32 v20, v17, v16
	v_lshlrev_b32_e32 v16, 16, v21
	v_mul_f32_e32 v18, v18, v16
	v_and_b32_e32 v16, 0xffff0000, v21
	v_mul_f32_e32 v19, v19, v16
	v_lshlrev_b32_e32 v16, 16, v22
	v_mul_f32_e32 v21, v12, v16
	v_and_b32_e32 v12, 0xffff0000, v22
	v_mul_f32_e32 v22, v13, v12
	v_lshlrev_b32_e32 v12, 16, v23
	v_mul_f32_e32 v29, v14, v12
	v_and_b32_e32 v12, 0xffff0000, v23
	v_mul_f32_e32 v15, v15, v12
	v_lshl_add_u64 v[12:13], s[12:13], 0, v[24:25]
	v_lshl_add_u64 v[16:17], v[12:13], 0, v[132:133]
	v_cvt_pk_bf16_f32 v12, v28, v20
	v_cvt_pk_bf16_f32 v13, v18, v19
	v_cvt_pk_bf16_f32 v14, v21, v22
	v_cvt_pk_bf16_f32 v15, v29, v15
	global_store_dwordx4 v[16:17], v[12:15], off
	s_waitcnt vmcnt(15)
	s_nop 1
	v_mov_b64_e32 v[12:13], v[232:233]
	v_mov_b64_e32 v[14:15], v[234:235]
	v_lshlrev_b32_e32 v18, 16, v12
	v_and_b32_e32 v12, 0xffff0000, v12
	v_mul_f32_e32 v5, v5, v12
	v_lshlrev_b32_e32 v12, 16, v13
	v_mul_f32_e32 v6, v6, v12
	v_and_b32_e32 v12, 0xffff0000, v13
	v_mul_f32_e32 v7, v7, v12
	v_lshlrev_b32_e32 v12, 16, v14
	v_mul_f32_e32 v8, v8, v12
	v_and_b32_e32 v12, 0xffff0000, v14
	v_mul_f32_e32 v9, v9, v12
	v_lshlrev_b32_e32 v12, 16, v15
	v_mul_f32_e32 v4, v4, v18
	v_mul_f32_e32 v10, v10, v12
	v_and_b32_e32 v12, 0xffff0000, v15
	v_mul_f32_e32 v11, v11, v12
	v_cvt_pk_bf16_f32 v4, v4, v5
	v_cvt_pk_bf16_f32 v5, v6, v7
	v_cvt_pk_bf16_f32 v6, v8, v9
	v_cvt_pk_bf16_f32 v7, v10, v11
	global_store_dwordx4 v[16:17], v[4:7], off offset:256
	s_cbranch_vccnz .LBB0_186
	s_waitcnt vmcnt(0) lgkmcnt(0)
	s_barrier

; template <class Epi, class Sched>
; __device__ __forceinline__ void gemm_simple(PG8_LAS unsigned char* lds, const Gemm g, const Sched& S, const Epi& E, int wave_s) {
;     ...
;         const bool has_next = S.next(ui + 1, nxt);
;         const char* nA = has_next ? (const char*)g.A + (size_t)nxt.pm * tstep : cA; const char* nB = has_next ? (const char*)g.Bt + (size_t)nxt.pn * tstep : cB;
;         int t = 0;
;         if (ui > 0) {
;             if constexpr (Epi::NST >= 16) PG8_TILE_W(0, cA + kstep, cB + kstep, "18", "20"); else PG8_TILE_W(0, cA + kstep, cB + kstep, "10", "12");
;             PG8_TILE_W(1, cA + 2 * kstep, cB + 2 * kstep, "2", "4");
;             t = 2;
;         }
;         for (; t < nt; t += 2) {
;             const bool last = (t == nt - 2);
;             PG8_TILE(0, cA + (size_t)(t + 1) * kstep, cB + (size_t)(t + 1) * kstep, true);
;             const char* a2 = last ? nA : cA + (size_t)(t + 2) * kstep; const char* b2 = last ? nB : cB + (size_t)(t + 2) * kstep;
;             PG8_TILE(1, a2, b2, (!last || has_next));
.LBB0_220:
	s_ashr_i32 s13, s12, 31
	s_lshl_b64 s[14:15], s[12:13], 20
	s_add_u32 s14, s94, s14
	s_addc_u32 s15, s95, s15
	s_and_b64 s[16:17], exec, s[8:9]
	s_cselect_b32 s13, s21, s15
	s_cselect_b32 s56, s20, s14
	s_ashr_i32 s5, s4, 31
	s_lshl_b64 s[16:17], s[4:5], 20
	s_add_u32 s16, s27, s16
	s_addc_u32 s17, s28, s17
	s_and_b64 s[24:25], exec, s[8:9]
	s_cselect_b32 s5, s11, s17
	s_cselect_b32 s57, s10, s16
	s_add_i32 s58, s22, -2
	s_lshl_b32 s59, s22, 7
	s_mov_b64 s[22:23], 0xf00
	s_branch .Lrt_top_221
.Lrt_221:
	v_mfma_f32_16x16x32_bf16 v[56:59], v[214:217], v[182:185], v[56:59]
	v_mfma_f32_16x16x32_bf16 v[52:55], v[222:225], v[182:185], v[52:55]
	v_mfma_f32_16x16x32_bf16 v[40:43], v[214:217], v[190:193], v[40:43]
	v_mfma_f32_16x16x32_bf16 v[36:39], v[222:225], v[190:193], v[36:39]
	v_mfma_f32_16x16x32_bf16 v[24:27], v[214:217], v[198:201], v[24:27]
	v_mfma_f32_16x16x32_bf16 v[20:23], v[222:225], v[198:201], v[20:23]
	v_mfma_f32_16x16x32_bf16 v[4:7], v[214:217], v[206:209], v[4:7]
	v_mfma_f32_16x16x32_bf16 v[8:11], v[222:225], v[206:209], v[8:11]
.Lrt_top_221:
.LBB0_221:
	s_waitcnt vmcnt(2) lgkmcnt(0)
	s_barrier
	ds_read_b128 v[146:149], v132
	ds_read_b128 v[178:181], v156
	ds_read_b128 v[170:173], v132 offset:2048
	ds_read_b128 v[186:189], v156 offset:2048
	ds_read_b128 v[194:197], v156 offset:4096
	s_add_u32 s60, s10, s59
	s_addc_u32 s61, s11, 0
	s_add_u32 s24, s60, 0x80
	s_addc_u32 s25, s61, 0
	s_mov_b32 m0, s44
	s_nop 0
	global_load_lds_dwordx4 v140, s[24:25]
	s_mov_b32 m0, s48
	s_nop 0
	global_load_lds_dwordx4 v153, s[24:25]
	s_waitcnt lgkmcnt(3)
	v_mfma_f32_16x16x32_bf16 v[128:131], v[146:149], v[178:181], v[128:131]
	s_waitcnt lgkmcnt(2)
	v_mfma_f32_16x16x32_bf16 v[124:127], v[170:173], v[178:181], v[124:127]
	ds_read_b128 v[202:205], v156 offset:6144
	s_waitcnt lgkmcnt(2)
	v_mfma_f32_16x16x32_bf16 v[112:115], v[146:149], v[186:189], v[112:115]
	v_mfma_f32_16x16x32_bf16 v[108:111], v[170:173], v[186:189], v[108:111]
	ds_read_b128 v[158:161], v132 offset:1024
	ds_read_b128 v[182:185], v156 offset:1024
	s_waitcnt lgkmcnt(3)
	v_mfma_f32_16x16x32_bf16 v[96:99], v[146:149], v[194:197], v[96:99]
	ds_read_b128 v[174:177], v132 offset:3072
	v_mfma_f32_16x16x32_bf16 v[92:95], v[170:173], v[194:197], v[92:95]
	ds_read_b128 v[190:193], v156 offset:3072
	s_waitcnt lgkmcnt(4)
	v_mfma_f32_16x16x32_bf16 v[80:83], v[146:149], v[202:205], v[80:83]
	v_mfma_f32_16x16x32_bf16 v[76:79], v[170:173], v[202:205], v[76:79]
	ds_read_b128 v[198:201], v156 offset:5120
	s_waitcnt lgkmcnt(3)
	v_mfma_f32_16x16x32_bf16 v[128:131], v[158:161], v[182:185], v[128:131]
	s_waitcnt lgkmcnt(2)
	v_mfma_f32_16x16x32_bf16 v[124:127], v[174:177], v[182:185], v[124:127]
	ds_read_b128 v[206:209], v156 offset:7168
	s_waitcnt lgkmcnt(2)
	v_mfma_f32_16x16x32_bf16 v[112:115], v[158:161], v[190:193], v[112:115]
	v_mfma_f32_16x16x32_bf16 v[108:111], v[174:177], v[190:193], v[108:111]
	ds_read_b128 v[210:213], v133
	s_waitcnt lgkmcnt(2)
	v_mfma_f32_16x16x32_bf16 v[96:99], v[158:161], v[198:201], v[96:99]
	ds_read_b128 v[218:221], v133 offset:2048
	v_mfma_f32_16x16x32_bf16 v[92:95], v[174:177], v[198:201], v[92:95]
	s_waitcnt lgkmcnt(2)
	v_mfma_f32_16x16x32_bf16 v[80:83], v[158:161], v[206:209], v[80:83]
	v_mfma_f32_16x16x32_bf16 v[76:79], v[174:177], v[206:209], v[76:79]
	s_add_u32 s62, s20, s59
	s_addc_u32 s63, s21, 0
	s_add_u32 s24, s62, 0x80
	s_addc_u32 s25, s63, 0
	s_mov_b32 m0, s45
	s_nop 0
	global_load_lds_dwordx4 v139, s[24:25]
	s_mov_b32 m0, s49
	s_nop 0
	global_load_lds_dwordx4 v152, s[24:25]
	s_waitcnt lgkmcnt(1)
	v_mfma_f32_16x16x32_bf16 v[120:123], v[210:213], v[178:181], v[120:123]
	s_waitcnt lgkmcnt(0)
	v_mfma_f32_16x16x32_bf16 v[116:119], v[218:221], v[178:181], v[116:119]
	v_mfma_f32_16x16x32_bf16 v[104:107], v[210:213], v[186:189], v[104:107]
	v_mfma_f32_16x16x32_bf16 v[100:103], v[218:221], v[186:189], v[100:103]
	ds_read_b128 v[214:217], v133 offset:1024
	v_mfma_f32_16x16x32_bf16 v[88:91], v[210:213], v[194:197], v[88:91]
	ds_read_b128 v[222:225], v133 offset:3072
	v_mfma_f32_16x16x32_bf16 v[84:87], v[218:221], v[194:197], v[84:87]
	v_mfma_f32_16x16x32_bf16 v[72:75], v[210:213], v[202:205], v[72:75]
	v_mfma_f32_16x16x32_bf16 v[68:71], v[218:221], v[202:205], v[68:71]
	s_waitcnt lgkmcnt(1)
	v_mfma_f32_16x16x32_bf16 v[120:123], v[214:217], v[182:185], v[120:123]
	s_waitcnt lgkmcnt(0)
	v_mfma_f32_16x16x32_bf16 v[116:119], v[222:225], v[182:185], v[116:119]
	v_mfma_f32_16x16x32_bf16 v[104:107], v[214:217], v[190:193], v[104:107]
	v_mfma_f32_16x16x32_bf16 v[100:103], v[222:225], v[190:193], v[100:103]
	v_mfma_f32_16x16x32_bf16 v[88:91], v[214:217], v[198:201], v[88:91]
	v_mfma_f32_16x16x32_bf16 v[84:87], v[222:225], v[198:201], v[84:87]
	v_mfma_f32_16x16x32_bf16 v[72:75], v[214:217], v[206:209], v[72:75]
	v_mfma_f32_16x16x32_bf16 v[68:71], v[222:225], v[206:209], v[68:71]
	s_waitcnt vmcnt(4) lgkmcnt(0)
	s_barrier
; template <class Epi, class Sched>
; __device__ __forceinline__ void gemm_simple(PG8_LAS unsigned char* lds, const Gemm g, const Sched& S, const Epi& E, int wave_s) {
;     ...
;         for (; t < nt; t += 2) {
;             const bool last = (t == nt - 2);
;             PG8_TILE(0, cA + (size_t)(t + 1) * kstep, cB + (size_t)(t + 1) * kstep, true);
;             const char* a2 = last ? nA : cA + (size_t)(t + 2) * kstep; const char* b2 = last ? nB : cB + (size_t)(t + 2) * kstep;
;             PG8_TILE(1, a2, b2, (!last || has_next));
	ds_read_b128 v[178:181], v156 offset:16384
	ds_read_b128 v[186:189], v156 offset:18432
	ds_read_b128 v[194:197], v156 offset:20480
	s_add_u32 s24, s60, 0x80080
	s_addc_u32 s25, s61, 0
	s_mov_b32 m0, s46
	s_nop 0
	global_load_lds_dwordx4 v140, s[24:25]
	s_mov_b32 m0, s50
	s_nop 0
	global_load_lds_dwordx4 v153, s[24:25]
	s_waitcnt lgkmcnt(2)
	v_mfma_f32_16x16x32_bf16 v[64:67], v[146:149], v[178:181], v[64:67]
	v_mfma_f32_16x16x32_bf16 v[60:63], v[170:173], v[178:181], v[60:63]
	ds_read_b128 v[202:205], v156 offset:22528
	s_waitcnt lgkmcnt(2)
	v_mfma_f32_16x16x32_bf16 v[48:51], v[146:149], v[186:189], v[48:51]
	v_mfma_f32_16x16x32_bf16 v[44:47], v[170:173], v[186:189], v[44:47]
	ds_read_b128 v[182:185], v156 offset:17408
	s_waitcnt lgkmcnt(2)
	v_mfma_f32_16x16x32_bf16 v[32:35], v[146:149], v[194:197], v[32:35]
	v_mfma_f32_16x16x32_bf16 v[28:31], v[170:173], v[194:197], v[28:31]
	ds_read_b128 v[190:193], v156 offset:19456
	s_waitcnt lgkmcnt(2)
	v_mfma_f32_16x16x32_bf16 v[16:19], v[146:149], v[202:205], v[16:19]
	v_mfma_f32_16x16x32_bf16 v[12:15], v[170:173], v[202:205], v[12:15]
	ds_read_b128 v[198:201], v156 offset:21504
	s_waitcnt lgkmcnt(2)
	v_mfma_f32_16x16x32_bf16 v[64:67], v[158:161], v[182:185], v[64:67]
	v_mfma_f32_16x16x32_bf16 v[60:63], v[174:177], v[182:185], v[60:63]
	ds_read_b128 v[206:209], v156 offset:23552
	s_waitcnt lgkmcnt(2)
	v_mfma_f32_16x16x32_bf16 v[48:51], v[158:161], v[190:193], v[48:51]
	v_mfma_f32_16x16x32_bf16 v[44:47], v[174:177], v[190:193], v[44:47]
	s_waitcnt lgkmcnt(1)
	v_mfma_f32_16x16x32_bf16 v[32:35], v[158:161], v[198:201], v[32:35]
	v_mfma_f32_16x16x32_bf16 v[28:31], v[174:177], v[198:201], v[28:31]
	s_waitcnt lgkmcnt(0)
	v_mfma_f32_16x16x32_bf16 v[16:19], v[158:161], v[206:209], v[16:19]
	v_mfma_f32_16x16x32_bf16 v[12:15], v[174:177], v[206:209], v[12:15]
	s_add_u32 s24, s62, 0x80080
	s_addc_u32 s25, s63, 0
	s_mov_b32 m0, s47
	s_nop 0
	global_load_lds_dwordx4 v139, s[24:25]
	s_mov_b32 m0, s51
	s_nop 0
	global_load_lds_dwordx4 v152, s[24:25]
	v_mfma_f32_16x16x32_bf16 v[56:59], v[210:213], v[178:181], v[56:59]
	s_add_u32 s24, s62, 0x100
	s_addc_u32 s25, s63, 0
	s_add_u32 s60, s60, 0x100
	v_mfma_f32_16x16x32_bf16 v[52:55], v[218:221], v[178:181], v[52:55]
	s_addc_u32 s61, s61, 0
	v_mfma_f32_16x16x32_bf16 v[40:43], v[210:213], v[186:189], v[40:43]
	v_mfma_f32_16x16x32_bf16 v[36:39], v[218:221], v[186:189], v[36:39]
	v_mfma_f32_16x16x32_bf16 v[24:27], v[210:213], v[194:197], v[24:27]
	v_mfma_f32_16x16x32_bf16 v[20:23], v[218:221], v[194:197], v[20:23]
	v_mfma_f32_16x16x32_bf16 v[4:7], v[210:213], v[202:205], v[4:7]
	v_mfma_f32_16x16x32_bf16 v[8:11], v[218:221], v[202:205], v[8:11]
	v_mfma_f32_16x16x32_bf16 v[56:59], v[214:217], v[182:185], v[56:59]
	v_mfma_f32_16x16x32_bf16 v[52:55], v[222:225], v[182:185], v[52:55]
	v_mfma_f32_16x16x32_bf16 v[40:43], v[214:217], v[190:193], v[40:43]
	v_mfma_f32_16x16x32_bf16 v[36:39], v[222:225], v[190:193], v[36:39]
	v_mfma_f32_16x16x32_bf16 v[24:27], v[214:217], v[198:201], v[24:27]
	v_mfma_f32_16x16x32_bf16 v[20:23], v[222:225], v[198:201], v[20:23]
	v_mfma_f32_16x16x32_bf16 v[4:7], v[214:217], v[206:209], v[4:7]
	v_mfma_f32_16x16x32_bf16 v[8:11], v[222:225], v[206:209], v[8:11]
	s_waitcnt vmcnt(2) lgkmcnt(0)
	s_barrier
	ds_read_b128 v[146:149], v134
	ds_read_b128 v[178:181], v156 offset:32768
	ds_read_b128 v[170:173], v134 offset:2048
	ds_read_b128 v[186:189], v156 offset:34816
	ds_read_b128 v[194:197], v156 offset:36864
	s_cmp_eq_u32 s59, s22
	s_cselect_b32 s25, s13, s25
	s_cselect_b32 s24, s56, s24
	s_cselect_b32 s61, s5, s61
	s_cselect_b32 s60, s57, s60
	s_mov_b32 m0, s29
	s_nop 0
	global_load_lds_dwordx4 v140, s[60:61]
	s_mov_b32 m0, s35
	s_nop 0
	global_load_lds_dwordx4 v153, s[60:61]
	s_waitcnt lgkmcnt(3)
	v_mfma_f32_16x16x32_bf16 v[128:131], v[146:149], v[178:181], v[128:131]
	s_waitcnt lgkmcnt(2)
	v_mfma_f32_16x16x32_bf16 v[124:127], v[170:173], v[178:181], v[124:127]
	ds_read_b128 v[202:205], v156 offset:38912
	s_waitcnt lgkmcnt(2)
	v_mfma_f32_16x16x32_bf16 v[112:115], v[146:149], v[186:189], v[112:115]
	v_mfma_f32_16x16x32_bf16 v[108:111], v[170:173], v[186:189], v[108:111]
	ds_read_b128 v[158:161], v134 offset:1024
	ds_read_b128 v[182:185], v156 offset:33792
	s_waitcnt lgkmcnt(3)
	v_mfma_f32_16x16x32_bf16 v[96:99], v[146:149], v[194:197], v[96:99]
	ds_read_b128 v[174:177], v134 offset:3072
	v_mfma_f32_16x16x32_bf16 v[92:95], v[170:173], v[194:197], v[92:95]
	ds_read_b128 v[190:193], v156 offset:35840
	s_waitcnt lgkmcnt(4)
	v_mfma_f32_16x16x32_bf16 v[80:83], v[146:149], v[202:205], v[80:83]
	v_mfma_f32_16x16x32_bf16 v[76:79], v[170:173], v[202:205], v[76:79]
	ds_read_b128 v[198:201], v156 offset:37888
	s_waitcnt lgkmcnt(3)
	v_mfma_f32_16x16x32_bf16 v[128:131], v[158:161], v[182:185], v[128:131]
	s_waitcnt lgkmcnt(2)
	v_mfma_f32_16x16x32_bf16 v[124:127], v[174:177], v[182:185], v[124:127]
	ds_read_b128 v[206:209], v156 offset:39936
	s_waitcnt lgkmcnt(2)
	v_mfma_f32_16x16x32_bf16 v[112:115], v[158:161], v[190:193], v[112:115]
	v_mfma_f32_16x16x32_bf16 v[108:111], v[174:177], v[190:193], v[108:111]
	ds_read_b128 v[210:213], v135
	s_waitcnt lgkmcnt(2)
	v_mfma_f32_16x16x32_bf16 v[96:99], v[158:161], v[198:201], v[96:99]
	ds_read_b128 v[218:221], v135 offset:2048
	v_mfma_f32_16x16x32_bf16 v[92:95], v[174:177], v[198:201], v[92:95]
	s_waitcnt lgkmcnt(2)
	v_mfma_f32_16x16x32_bf16 v[80:83], v[158:161], v[206:209], v[80:83]
	v_mfma_f32_16x16x32_bf16 v[76:79], v[174:177], v[206:209], v[76:79]
	s_mov_b32 m0, s19
	s_nop 0
	global_load_lds_dwordx4 v139, s[24:25]
	s_mov_b32 m0, s36
	s_nop 0
	global_load_lds_dwordx4 v152, s[24:25]
	s_waitcnt lgkmcnt(1)
	v_mfma_f32_16x16x32_bf16 v[120:123], v[210:213], v[178:181], v[120:123]
	s_waitcnt lgkmcnt(0)
	v_mfma_f32_16x16x32_bf16 v[116:119], v[218:221], v[178:181], v[116:119]
	v_mfma_f32_16x16x32_bf16 v[104:107], v[210:213], v[186:189], v[104:107]
	v_mfma_f32_16x16x32_bf16 v[100:103], v[218:221], v[186:189], v[100:103]
	ds_read_b128 v[214:217], v135 offset:1024
	v_mfma_f32_16x16x32_bf16 v[88:91], v[210:213], v[194:197], v[88:91]
	ds_read_b128 v[222:225], v135 offset:3072
	v_mfma_f32_16x16x32_bf16 v[84:87], v[218:221], v[194:197], v[84:87]
	v_mfma_f32_16x16x32_bf16 v[72:75], v[210:213], v[202:205], v[72:75]
	v_mfma_f32_16x16x32_bf16 v[68:71], v[218:221], v[202:205], v[68:71]
	s_waitcnt lgkmcnt(1)
	v_mfma_f32_16x16x32_bf16 v[120:123], v[214:217], v[182:185], v[120:123]
	s_waitcnt lgkmcnt(0)
	v_mfma_f32_16x16x32_bf16 v[116:119], v[222:225], v[182:185], v[116:119]
	v_mfma_f32_16x16x32_bf16 v[104:107], v[214:217], v[190:193], v[104:107]
	v_mfma_f32_16x16x32_bf16 v[100:103], v[222:225], v[190:193], v[100:103]
	v_mfma_f32_16x16x32_bf16 v[88:91], v[214:217], v[198:201], v[88:91]
	v_mfma_f32_16x16x32_bf16 v[84:87], v[222:225], v[198:201], v[84:87]
	v_mfma_f32_16x16x32_bf16 v[72:75], v[214:217], v[206:209], v[72:75]
	v_mfma_f32_16x16x32_bf16 v[68:71], v[222:225], v[206:209], v[68:71]
	s_waitcnt vmcnt(4) lgkmcnt(0)
	s_barrier
; #define LAS __attribute__((address_space(3)))
;     __device__ __forceinline__ void prepare(LAS unsigned char* lds, const Unit& u, int tid, int par) const { if (RS) rstd_table(ssq, lds, u, tid, par); }
;     __device__ __forceinline__ void prepare(LAS unsigned char* lds, const Unit& u, int tid, int par) const { rstd_table(ssq, lds, u, tid, par); }
;     __device__ __forceinline__ void prepare(LAS unsigned char* lds, const Unit& u, int tid, int par) const { if (MODE == 1) rstd_table(ssq, lds, u, tid, par); }
;     __device__ __forceinline__ void prepare(LAS unsigned char* lds, const Unit& u, int tid, int par) const { rstd_table(ssq, lds, u, tid, par); }
; template <class Epi, class Sched>
; __device__ __forceinline__ void gemm_simple(PG8_LAS unsigned char* lds, const Gemm g, const Sched& S, const Epi& E, int wave_s) {
;     ...
;         for (; t < nt; t += 2) {
;             const bool last = (t == nt - 2);
;             PG8_TILE(0, cA + (size_t)(t + 1) * kstep, cB + (size_t)(t + 1) * kstep, true);
;             const char* a2 = last ? nA : cA + (size_t)(t + 2) * kstep; const char* b2 = last ? nB : cB + (size_t)(t + 2) * kstep;
;             PG8_TILE(1, a2, b2, (!last || has_next));
;         }
;         if (has_next) E.prepare(lds, nxt, tid, (ui + 1) & 1);
; __device__ __forceinline__ void rstd_table(const float* ssq, LAS unsigned char* lds, const Unit& u, int tid, int par) {
;     if (tid < 256) { const f32x4* p = (const f32x4*)(ssq + (size_t)(u.pm * 256 + tid) * 32); f32x4 a = p[0];
; #pragma unroll
;         for (int i = 1; i < 8; ++i) a += p[i];
;         ((LAS float*)(lds + 131072 + par * 1024))[tid] = 1.0f / sqrtf(((a[0] + a[1]) + (a[2] + a[3])) * (1.0f / DM) + 1e-6f); }
	ds_read_b128 v[178:181], v156 offset:49152
	ds_read_b128 v[186:189], v156 offset:51200
	ds_read_b128 v[194:197], v156 offset:53248
	s_add_u32 s60, s60, 0x80000
	s_addc_u32 s61, s61, 0
	s_mov_b32 m0, s37
	s_nop 0
	global_load_lds_dwordx4 v140, s[60:61]
	s_mov_b32 m0, s38
	s_nop 0
	global_load_lds_dwordx4 v153, s[60:61]
	s_waitcnt lgkmcnt(2)
	v_mfma_f32_16x16x32_bf16 v[64:67], v[146:149], v[178:181], v[64:67]
	v_mfma_f32_16x16x32_bf16 v[60:63], v[170:173], v[178:181], v[60:63]
	ds_read_b128 v[202:205], v156 offset:55296
	s_waitcnt lgkmcnt(2)
	v_mfma_f32_16x16x32_bf16 v[48:51], v[146:149], v[186:189], v[48:51]
	v_mfma_f32_16x16x32_bf16 v[44:47], v[170:173], v[186:189], v[44:47]
	ds_read_b128 v[182:185], v156 offset:50176
	s_waitcnt lgkmcnt(2)
	v_mfma_f32_16x16x32_bf16 v[32:35], v[146:149], v[194:197], v[32:35]
	v_mfma_f32_16x16x32_bf16 v[28:31], v[170:173], v[194:197], v[28:31]
	ds_read_b128 v[190:193], v156 offset:52224
	s_waitcnt lgkmcnt(2)
	v_mfma_f32_16x16x32_bf16 v[16:19], v[146:149], v[202:205], v[16:19]
	v_mfma_f32_16x16x32_bf16 v[12:15], v[170:173], v[202:205], v[12:15]
	ds_read_b128 v[198:201], v156 offset:54272
	s_waitcnt lgkmcnt(2)
	v_mfma_f32_16x16x32_bf16 v[64:67], v[158:161], v[182:185], v[64:67]
	v_mfma_f32_16x16x32_bf16 v[60:63], v[174:177], v[182:185], v[60:63]
	ds_read_b128 v[206:209], v156 offset:56320
	s_waitcnt lgkmcnt(2)
	v_mfma_f32_16x16x32_bf16 v[48:51], v[158:161], v[190:193], v[48:51]
	v_mfma_f32_16x16x32_bf16 v[44:47], v[174:177], v[190:193], v[44:47]
	s_waitcnt lgkmcnt(1)
	v_mfma_f32_16x16x32_bf16 v[32:35], v[158:161], v[198:201], v[32:35]
	v_mfma_f32_16x16x32_bf16 v[28:31], v[174:177], v[198:201], v[28:31]
	s_waitcnt lgkmcnt(0)
	v_mfma_f32_16x16x32_bf16 v[16:19], v[158:161], v[206:209], v[16:19]
	v_mfma_f32_16x16x32_bf16 v[12:15], v[174:177], v[206:209], v[12:15]
	s_add_u32 s24, s24, 0x80000
	s_addc_u32 s25, s25, 0
	s_mov_b32 m0, s39
	s_nop 0
	global_load_lds_dwordx4 v139, s[24:25]
	s_mov_b32 m0, s40
	s_nop 0
	global_load_lds_dwordx4 v152, s[24:25]
	v_mfma_f32_16x16x32_bf16 v[56:59], v[210:213], v[178:181], v[56:59]
	s_add_i32 s58, s58, 2
	s_add_u32 s22, s22, 0xffffff00
	s_addc_u32 s23, s23, -1
	v_mfma_f32_16x16x32_bf16 v[52:55], v[218:221], v[178:181], v[52:55]
	s_add_u32 s20, s20, 0x100
	s_addc_u32 s21, s21, 0
	s_add_u32 s10, s10, 0x100
	v_mfma_f32_16x16x32_bf16 v[40:43], v[210:213], v[186:189], v[40:43]
	s_addc_u32 s11, s11, 0
	s_cmp_lt_u32 s58, 30
	v_mfma_f32_16x16x32_bf16 v[36:39], v[218:221], v[186:189], v[36:39]
	v_mfma_f32_16x16x32_bf16 v[24:27], v[210:213], v[194:197], v[24:27]
	v_mfma_f32_16x16x32_bf16 v[20:23], v[218:221], v[194:197], v[20:23]
	v_mfma_f32_16x16x32_bf16 v[4:7], v[210:213], v[202:205], v[4:7]
	v_mfma_f32_16x16x32_bf16 v[8:11], v[218:221], v[202:205], v[8:11]
	s_cbranch_scc1 .Lrt_221
	v_mfma_f32_16x16x32_bf16 v[56:59], v[214:217], v[182:185], v[56:59]
	v_mfma_f32_16x16x32_bf16 v[52:55], v[222:225], v[182:185], v[52:55]
	v_mfma_f32_16x16x32_bf16 v[40:43], v[214:217], v[190:193], v[40:43]
	v_mfma_f32_16x16x32_bf16 v[36:39], v[222:225], v[190:193], v[36:39]
	v_mfma_f32_16x16x32_bf16 v[24:27], v[214:217], v[198:201], v[24:27]
	v_mfma_f32_16x16x32_bf16 v[20:23], v[222:225], v[198:201], v[20:23]
	v_mfma_f32_16x16x32_bf16 v[4:7], v[214:217], v[206:209], v[4:7]
	v_mfma_f32_16x16x32_bf16 v[8:11], v[222:225], v[206:209], v[8:11]
	s_nor_b64 s[10:11], s[6:7], s[8:9]
	s_and_saveexec_b64 s[20:21], s[10:11]
	s_cbranch_execz .LBB0_211
	v_lshl_add_u32 v132, s12, 8, v138
	v_ashrrev_i32_e32 v133, 31, v132
	v_readlane_b32 s10, v255, 2
	v_lshlrev_b64 v[132:133], 7, v[132:133]
	v_readlane_b32 s11, v255, 3
	s_lshl_b32 s5, s53, 10
	s_and_b32 s5, s5, 0x400
	v_lshl_add_u64 v[136:137], s[10:11], 0, v[132:133]
	global_load_dwordx4 v[132:135], v[136:137], off offset:48
	global_load_dwordx4 v[146:149], v[136:137], off offset:32
	global_load_dwordx4 v[158:161], v[136:137], off
	global_load_dwordx4 v[170:173], v[136:137], off offset:16
	s_waitcnt vmcnt(0)
	v_pk_add_f32 v[142:143], v[160:161], v[172:173]
	v_pk_add_f32 v[144:145], v[158:159], v[170:171]
	v_pk_add_f32 v[142:143], v[142:143], v[148:149]
	v_pk_add_f32 v[144:145], v[144:145], v[146:147]
	v_pk_add_f32 v[142:143], v[142:143], v[134:135]
	v_pk_add_f32 v[144:145], v[144:145], v[132:133]
	global_load_dwordx4 v[132:135], v[136:137], off offset:112
	global_load_dwordx4 v[146:149], v[136:137], off offset:96
	global_load_dwordx4 v[158:161], v[136:137], off offset:80
	global_load_dwordx4 v[170:173], v[136:137], off offset:64
	s_waitcnt vmcnt(0)
	v_pk_add_f32 v[136:137], v[142:143], v[172:173]
	v_pk_add_f32 v[142:143], v[144:145], v[170:171]
	v_pk_add_f32 v[136:137], v[136:137], v[160:161]
	v_pk_add_f32 v[142:143], v[142:143], v[158:159]
	v_pk_add_f32 v[136:137], v[136:137], v[148:149]
	v_pk_add_f32 v[142:143], v[142:143], v[146:147]
	v_pk_add_f32 v[134:135], v[136:137], v[134:135]
	v_pk_add_f32 v[132:133], v[142:143], v[132:133]
	s_nop 0
	v_pk_mov_b32 v[136:137], v[132:133], v[134:135] op_sel:[1,0]
	v_mov_b32_e32 v133, v135
	v_pk_add_f32 v[132:133], v[136:137], v[132:133]
	s_nop 0
	v_add_f32_e32 v132, v132, v133
	v_fmamk_f32 v132, v132, 0x3a000000, v164
	v_cmp_gt_f32_e32 vcc, s69, v132
	v_mul_f32_e32 v133, 0x4f800000, v132
	s_nop 0
	v_cndmask_b32_e32 v132, v132, v133, vcc
	v_sqrt_f32_e32 v133, v132
	s_nop 0
	v_add_u32_e32 v134, -1, v133
	v_fma_f32 v135, -v134, v133, v132
	v_cmp_ge_f32_e64 s[10:11], 0, v135
	v_add_u32_e32 v135, 1, v133
	s_nop 0
	v_cndmask_b32_e64 v134, v133, v134, s[10:11]
	v_fma_f32 v133, -v135, v133, v132
	v_cmp_lt_f32_e64 s[10:11], 0, v133
	s_nop 1
	v_cndmask_b32_e64 v133, v134, v135, s[10:11]
	v_mul_f32_e32 v134, 0x37800000, v133
	v_cndmask_b32_e32 v133, v133, v134, vcc
	v_cmp_class_f32_e32 vcc, v132, v165
	s_nop 1
	v_cndmask_b32_e32 v132, v133, v132, vcc
	v_div_scale_f32 v133, s[10:11], v132, v132, 1.0
	v_rcp_f32_e32 v134, v133
	s_nop 0
	v_fma_f32 v135, -v133, v134, 1.0
	v_fmac_f32_e32 v134, v135, v134
	v_div_scale_f32 v135, vcc, 1.0, v132, 1.0
	v_mul_f32_e32 v136, v135, v134
	v_fma_f32 v137, -v133, v136, v135
	v_fmac_f32_e32 v136, v137, v134
	v_fma_f32 v133, -v133, v136, v135
	v_div_fmas_f32 v133, v133, v134, v136
	v_div_fixup_f32 v132, v133, v132, 1.0
	v_add_u32_e32 v133, s5, v154
	ds_write_b32 v133, v132
	s_branch .LBB0_211

; template <class Epi, class Sched>
; __device__ __forceinline__ void gemm_simple(PG8_LAS unsigned char* lds, const Gemm g, const Sched& S, const Epi& E, int wave_s) {
;     ...
;         const bool has_next = S.next(ui + 1, nxt);
;         const char* nA = has_next ? (const char*)g.A + (size_t)nxt.pm * tstep : cA; const char* nB = has_next ? (const char*)g.Bt + (size_t)nxt.pn * tstep : cB;
;         int t = 0;
;         if (ui > 0) {
;             if constexpr (Epi::NST >= 16) PG8_TILE_W(0, cA + kstep, cB + kstep, "18", "20"); else PG8_TILE_W(0, cA + kstep, cB + kstep, "10", "12");
;             PG8_TILE_W(1, cA + 2 * kstep, cB + 2 * kstep, "2", "4");
;             t = 2;
;         }
;         for (; t < nt; t += 2) {
;             const bool last = (t == nt - 2);
;             PG8_TILE(0, cA + (size_t)(t + 1) * kstep, cB + (size_t)(t + 1) * kstep, true);
;             const char* a2 = last ? nA : cA + (size_t)(t + 2) * kstep; const char* b2 = last ? nB : cB + (size_t)(t + 2) * kstep;
;             PG8_TILE(1, a2, b2, (!last || has_next));
.LBB0_274:
	s_ashr_i32 s15, s14, 31
	s_lshl_b64 s[16:17], s[14:15], 20
	s_add_u32 s16, s94, s16
	s_addc_u32 s17, s95, s17
	s_and_b64 s[18:19], exec, s[8:9]
	s_cselect_b32 s15, s25, s17
	s_cselect_b32 s35, s24, s16
	s_ashr_i32 s13, s12, 31
	s_lshl_b64 s[18:19], s[12:13], 20
	s_add_u32 s18, s36, s18
	s_addc_u32 s19, s37, s19
	s_and_b64 s[28:29], exec, s[8:9]
	s_cselect_b32 s13, s11, s19
	s_cselect_b32 s60, s10, s18
	s_add_i32 s61, s26, -2
	s_lshl_b32 s62, s26, 7
	s_mov_b64 s[26:27], 0xf00
	s_branch .Lrt_top_275
.Lrt_275:
	v_mfma_f32_16x16x32_bf16 v[56:59], v[208:211], v[176:179], v[56:59]
	v_mfma_f32_16x16x32_bf16 v[52:55], v[216:219], v[176:179], v[52:55]
	v_mfma_f32_16x16x32_bf16 v[40:43], v[208:211], v[184:187], v[40:43]
	v_mfma_f32_16x16x32_bf16 v[36:39], v[216:219], v[184:187], v[36:39]
	v_mfma_f32_16x16x32_bf16 v[24:27], v[208:211], v[192:195], v[24:27]
	v_mfma_f32_16x16x32_bf16 v[20:23], v[216:219], v[192:195], v[20:23]
	v_mfma_f32_16x16x32_bf16 v[8:11], v[208:211], v[200:203], v[8:11]
	v_mfma_f32_16x16x32_bf16 v[4:7], v[216:219], v[200:203], v[4:7]
.Lrt_top_275:
.LBB0_275:
	s_waitcnt vmcnt(2) lgkmcnt(0)
	s_barrier
	ds_read_b128 v[136:139], v132
	ds_read_b128 v[156:159], v174
	ds_read_b128 v[146:149], v132 offset:2048
	ds_read_b128 v[180:183], v174 offset:2048
	ds_read_b128 v[188:191], v174 offset:4096
	s_add_u32 s63, s10, s62
	s_addc_u32 s64, s11, 0
	s_add_u32 s28, s63, 0x80
	s_addc_u32 s29, s64, 0
	s_mov_b32 m0, s49
	s_nop 0
	global_load_lds_dwordx4 v163, s[28:29]
	s_mov_b32 m0, s53
	s_nop 0
	global_load_lds_dwordx4 v171, s[28:29]
	s_waitcnt lgkmcnt(3)
	v_mfma_f32_16x16x32_bf16 v[128:131], v[136:139], v[156:159], v[128:131]
	s_waitcnt lgkmcnt(2)
	v_mfma_f32_16x16x32_bf16 v[124:127], v[146:149], v[156:159], v[124:127]
	ds_read_b128 v[196:199], v174 offset:6144
	s_waitcnt lgkmcnt(2)
	v_mfma_f32_16x16x32_bf16 v[112:115], v[136:139], v[180:183], v[112:115]
	v_mfma_f32_16x16x32_bf16 v[108:111], v[146:149], v[180:183], v[108:111]
	ds_read_b128 v[142:145], v132 offset:1024
	ds_read_b128 v[176:179], v174 offset:1024
	s_waitcnt lgkmcnt(3)
	v_mfma_f32_16x16x32_bf16 v[96:99], v[136:139], v[188:191], v[96:99]
	ds_read_b128 v[152:155], v132 offset:3072
	v_mfma_f32_16x16x32_bf16 v[92:95], v[146:149], v[188:191], v[92:95]
	ds_read_b128 v[184:187], v174 offset:3072
	s_waitcnt lgkmcnt(4)
	v_mfma_f32_16x16x32_bf16 v[80:83], v[136:139], v[196:199], v[80:83]
	v_mfma_f32_16x16x32_bf16 v[76:79], v[146:149], v[196:199], v[76:79]
	ds_read_b128 v[192:195], v174 offset:5120
	s_waitcnt lgkmcnt(3)
	v_mfma_f32_16x16x32_bf16 v[128:131], v[142:145], v[176:179], v[128:131]
	s_waitcnt lgkmcnt(2)
	v_mfma_f32_16x16x32_bf16 v[124:127], v[152:155], v[176:179], v[124:127]
	ds_read_b128 v[200:203], v174 offset:7168
	s_waitcnt lgkmcnt(2)
	v_mfma_f32_16x16x32_bf16 v[112:115], v[142:145], v[184:187], v[112:115]
	v_mfma_f32_16x16x32_bf16 v[108:111], v[152:155], v[184:187], v[108:111]
	ds_read_b128 v[204:207], v133
	s_waitcnt lgkmcnt(2)
	v_mfma_f32_16x16x32_bf16 v[96:99], v[142:145], v[192:195], v[96:99]
	ds_read_b128 v[212:215], v133 offset:2048
	v_mfma_f32_16x16x32_bf16 v[92:95], v[152:155], v[192:195], v[92:95]
	s_waitcnt lgkmcnt(2)
	v_mfma_f32_16x16x32_bf16 v[80:83], v[142:145], v[200:203], v[80:83]
	v_mfma_f32_16x16x32_bf16 v[76:79], v[152:155], v[200:203], v[76:79]
	s_add_u32 s65, s24, s62
	s_addc_u32 s66, s25, 0
	s_add_u32 s28, s65, 0x80
	s_addc_u32 s29, s66, 0
	s_mov_b32 m0, s50
	s_nop 0
	global_load_lds_dwordx4 v162, s[28:29]
	s_mov_b32 m0, s54
	s_nop 0
	global_load_lds_dwordx4 v170, s[28:29]
	s_waitcnt lgkmcnt(1)
	v_mfma_f32_16x16x32_bf16 v[120:123], v[204:207], v[156:159], v[120:123]
	s_waitcnt lgkmcnt(0)
	v_mfma_f32_16x16x32_bf16 v[116:119], v[212:215], v[156:159], v[116:119]
	v_mfma_f32_16x16x32_bf16 v[104:107], v[204:207], v[180:183], v[104:107]
	v_mfma_f32_16x16x32_bf16 v[100:103], v[212:215], v[180:183], v[100:103]
	ds_read_b128 v[208:211], v133 offset:1024
	v_mfma_f32_16x16x32_bf16 v[88:91], v[204:207], v[188:191], v[88:91]
	ds_read_b128 v[216:219], v133 offset:3072
	v_mfma_f32_16x16x32_bf16 v[84:87], v[212:215], v[188:191], v[84:87]
	v_mfma_f32_16x16x32_bf16 v[72:75], v[204:207], v[196:199], v[72:75]
	v_mfma_f32_16x16x32_bf16 v[68:71], v[212:215], v[196:199], v[68:71]
	s_waitcnt lgkmcnt(1)
	v_mfma_f32_16x16x32_bf16 v[120:123], v[208:211], v[176:179], v[120:123]
	s_waitcnt lgkmcnt(0)
	v_mfma_f32_16x16x32_bf16 v[116:119], v[216:219], v[176:179], v[116:119]
	v_mfma_f32_16x16x32_bf16 v[104:107], v[208:211], v[184:187], v[104:107]
	v_mfma_f32_16x16x32_bf16 v[100:103], v[216:219], v[184:187], v[100:103]
	v_mfma_f32_16x16x32_bf16 v[88:91], v[208:211], v[192:195], v[88:91]
	v_mfma_f32_16x16x32_bf16 v[84:87], v[216:219], v[192:195], v[84:87]
	v_mfma_f32_16x16x32_bf16 v[72:75], v[208:211], v[200:203], v[72:75]
	v_mfma_f32_16x16x32_bf16 v[68:71], v[216:219], v[200:203], v[68:71]
	s_waitcnt vmcnt(4) lgkmcnt(0)
	s_barrier
; template <class Epi, class Sched>
; __device__ __forceinline__ void gemm_simple(PG8_LAS unsigned char* lds, const Gemm g, const Sched& S, const Epi& E, int wave_s) {
;     ...
;         for (; t < nt; t += 2) {
;             const bool last = (t == nt - 2);
;             PG8_TILE(0, cA + (size_t)(t + 1) * kstep, cB + (size_t)(t + 1) * kstep, true);
;             const char* a2 = last ? nA : cA + (size_t)(t + 2) * kstep; const char* b2 = last ? nB : cB + (size_t)(t + 2) * kstep;
;             PG8_TILE(1, a2, b2, (!last || has_next));
	ds_read_b128 v[156:159], v174 offset:16384
	ds_read_b128 v[180:183], v174 offset:18432
	ds_read_b128 v[188:191], v174 offset:20480
	s_add_u32 s28, s63, 0x80080
	s_addc_u32 s29, s64, 0
	s_mov_b32 m0, s51
	s_nop 0
	global_load_lds_dwordx4 v163, s[28:29]
	s_mov_b32 m0, s55
	s_nop 0
	global_load_lds_dwordx4 v171, s[28:29]
	s_waitcnt lgkmcnt(2)
	v_mfma_f32_16x16x32_bf16 v[64:67], v[136:139], v[156:159], v[64:67]
	v_mfma_f32_16x16x32_bf16 v[60:63], v[146:149], v[156:159], v[60:63]
	ds_read_b128 v[196:199], v174 offset:22528
	s_waitcnt lgkmcnt(2)
	v_mfma_f32_16x16x32_bf16 v[48:51], v[136:139], v[180:183], v[48:51]
	v_mfma_f32_16x16x32_bf16 v[44:47], v[146:149], v[180:183], v[44:47]
	ds_read_b128 v[176:179], v174 offset:17408
	s_waitcnt lgkmcnt(2)
	v_mfma_f32_16x16x32_bf16 v[32:35], v[136:139], v[188:191], v[32:35]
	v_mfma_f32_16x16x32_bf16 v[28:31], v[146:149], v[188:191], v[28:31]
	ds_read_b128 v[184:187], v174 offset:19456
	s_waitcnt lgkmcnt(2)
	v_mfma_f32_16x16x32_bf16 v[16:19], v[136:139], v[196:199], v[16:19]
	v_mfma_f32_16x16x32_bf16 v[12:15], v[146:149], v[196:199], v[12:15]
	ds_read_b128 v[192:195], v174 offset:21504
	s_waitcnt lgkmcnt(2)
	v_mfma_f32_16x16x32_bf16 v[64:67], v[142:145], v[176:179], v[64:67]
	v_mfma_f32_16x16x32_bf16 v[60:63], v[152:155], v[176:179], v[60:63]
	ds_read_b128 v[200:203], v174 offset:23552
	s_waitcnt lgkmcnt(2)
	v_mfma_f32_16x16x32_bf16 v[48:51], v[142:145], v[184:187], v[48:51]
	v_mfma_f32_16x16x32_bf16 v[44:47], v[152:155], v[184:187], v[44:47]
	s_waitcnt lgkmcnt(1)
	v_mfma_f32_16x16x32_bf16 v[32:35], v[142:145], v[192:195], v[32:35]
	v_mfma_f32_16x16x32_bf16 v[28:31], v[152:155], v[192:195], v[28:31]
	s_waitcnt lgkmcnt(0)
	v_mfma_f32_16x16x32_bf16 v[16:19], v[142:145], v[200:203], v[16:19]
	v_mfma_f32_16x16x32_bf16 v[12:15], v[152:155], v[200:203], v[12:15]
	s_add_u32 s28, s65, 0x80080
	s_addc_u32 s29, s66, 0
	s_mov_b32 m0, s52
	s_nop 0
	global_load_lds_dwordx4 v162, s[28:29]
	s_mov_b32 m0, s56
	s_nop 0
	global_load_lds_dwordx4 v170, s[28:29]
	v_mfma_f32_16x16x32_bf16 v[56:59], v[204:207], v[156:159], v[56:59]
	s_add_u32 s28, s65, 0x100
	s_addc_u32 s29, s66, 0
	s_add_u32 s63, s63, 0x100
	v_mfma_f32_16x16x32_bf16 v[52:55], v[212:215], v[156:159], v[52:55]
	s_addc_u32 s64, s64, 0
	v_mfma_f32_16x16x32_bf16 v[40:43], v[204:207], v[180:183], v[40:43]
	v_mfma_f32_16x16x32_bf16 v[36:39], v[212:215], v[180:183], v[36:39]
	v_mfma_f32_16x16x32_bf16 v[24:27], v[204:207], v[188:191], v[24:27]
	v_mfma_f32_16x16x32_bf16 v[20:23], v[212:215], v[188:191], v[20:23]
	v_mfma_f32_16x16x32_bf16 v[8:11], v[204:207], v[196:199], v[8:11]
	v_mfma_f32_16x16x32_bf16 v[4:7], v[212:215], v[196:199], v[4:7]
	v_mfma_f32_16x16x32_bf16 v[56:59], v[208:211], v[176:179], v[56:59]
	v_mfma_f32_16x16x32_bf16 v[52:55], v[216:219], v[176:179], v[52:55]
	v_mfma_f32_16x16x32_bf16 v[40:43], v[208:211], v[184:187], v[40:43]
	v_mfma_f32_16x16x32_bf16 v[36:39], v[216:219], v[184:187], v[36:39]
	v_mfma_f32_16x16x32_bf16 v[24:27], v[208:211], v[192:195], v[24:27]
	v_mfma_f32_16x16x32_bf16 v[20:23], v[216:219], v[192:195], v[20:23]
	v_mfma_f32_16x16x32_bf16 v[8:11], v[208:211], v[200:203], v[8:11]
	v_mfma_f32_16x16x32_bf16 v[4:7], v[216:219], v[200:203], v[4:7]
	s_waitcnt vmcnt(2) lgkmcnt(0)
	s_barrier
	ds_read_b128 v[136:139], v134
	ds_read_b128 v[156:159], v174 offset:32768
	ds_read_b128 v[146:149], v134 offset:2048
	ds_read_b128 v[180:183], v174 offset:34816
	ds_read_b128 v[188:191], v174 offset:36864
	s_cmp_eq_u32 s62, s26
	s_cselect_b32 s29, s15, s29
	s_cselect_b32 s28, s35, s28
	s_cselect_b32 s65, s13, s64
	s_cselect_b32 s64, s60, s63
	s_mov_b32 m0, s38
	s_nop 0
	global_load_lds_dwordx4 v163, s[64:65]
	s_mov_b32 m0, s39
	s_nop 0
	global_load_lds_dwordx4 v171, s[64:65]
	s_waitcnt lgkmcnt(3)
	v_mfma_f32_16x16x32_bf16 v[128:131], v[136:139], v[156:159], v[128:131]
	s_waitcnt lgkmcnt(2)
	v_mfma_f32_16x16x32_bf16 v[124:127], v[146:149], v[156:159], v[124:127]
	ds_read_b128 v[196:199], v174 offset:38912
	s_waitcnt lgkmcnt(2)
	v_mfma_f32_16x16x32_bf16 v[112:115], v[136:139], v[180:183], v[112:115]
	v_mfma_f32_16x16x32_bf16 v[108:111], v[146:149], v[180:183], v[108:111]
	ds_read_b128 v[142:145], v134 offset:1024
	ds_read_b128 v[176:179], v174 offset:33792
	s_waitcnt lgkmcnt(3)
	v_mfma_f32_16x16x32_bf16 v[96:99], v[136:139], v[188:191], v[96:99]
	ds_read_b128 v[152:155], v134 offset:3072
	v_mfma_f32_16x16x32_bf16 v[92:95], v[146:149], v[188:191], v[92:95]
	ds_read_b128 v[184:187], v174 offset:35840
	s_waitcnt lgkmcnt(4)
	v_mfma_f32_16x16x32_bf16 v[80:83], v[136:139], v[196:199], v[80:83]
	v_mfma_f32_16x16x32_bf16 v[76:79], v[146:149], v[196:199], v[76:79]
	ds_read_b128 v[192:195], v174 offset:37888
	s_waitcnt lgkmcnt(3)
	v_mfma_f32_16x16x32_bf16 v[128:131], v[142:145], v[176:179], v[128:131]
	s_waitcnt lgkmcnt(2)
	v_mfma_f32_16x16x32_bf16 v[124:127], v[152:155], v[176:179], v[124:127]
	ds_read_b128 v[200:203], v174 offset:39936
	s_waitcnt lgkmcnt(2)
	v_mfma_f32_16x16x32_bf16 v[112:115], v[142:145], v[184:187], v[112:115]
	v_mfma_f32_16x16x32_bf16 v[108:111], v[152:155], v[184:187], v[108:111]
	ds_read_b128 v[204:207], v135
	s_waitcnt lgkmcnt(2)
	v_mfma_f32_16x16x32_bf16 v[96:99], v[142:145], v[192:195], v[96:99]
	ds_read_b128 v[212:215], v135 offset:2048
	v_mfma_f32_16x16x32_bf16 v[92:95], v[152:155], v[192:195], v[92:95]
	s_waitcnt lgkmcnt(2)
	v_mfma_f32_16x16x32_bf16 v[80:83], v[142:145], v[200:203], v[80:83]
	v_mfma_f32_16x16x32_bf16 v[76:79], v[152:155], v[200:203], v[76:79]
	s_mov_b32 m0, s23
	s_nop 0
	global_load_lds_dwordx4 v162, s[28:29]
	s_mov_b32 m0, s40
	s_nop 0
	global_load_lds_dwordx4 v170, s[28:29]
	s_waitcnt lgkmcnt(1)
	v_mfma_f32_16x16x32_bf16 v[120:123], v[204:207], v[156:159], v[120:123]
	s_waitcnt lgkmcnt(0)
	v_mfma_f32_16x16x32_bf16 v[116:119], v[212:215], v[156:159], v[116:119]
	v_mfma_f32_16x16x32_bf16 v[104:107], v[204:207], v[180:183], v[104:107]
	v_mfma_f32_16x16x32_bf16 v[100:103], v[212:215], v[180:183], v[100:103]
	ds_read_b128 v[208:211], v135 offset:1024
	v_mfma_f32_16x16x32_bf16 v[88:91], v[204:207], v[188:191], v[88:91]
	ds_read_b128 v[216:219], v135 offset:3072
	v_mfma_f32_16x16x32_bf16 v[84:87], v[212:215], v[188:191], v[84:87]
	v_mfma_f32_16x16x32_bf16 v[72:75], v[204:207], v[196:199], v[72:75]
	v_mfma_f32_16x16x32_bf16 v[68:71], v[212:215], v[196:199], v[68:71]
	s_waitcnt lgkmcnt(1)
	v_mfma_f32_16x16x32_bf16 v[120:123], v[208:211], v[176:179], v[120:123]
	s_waitcnt lgkmcnt(0)
	v_mfma_f32_16x16x32_bf16 v[116:119], v[216:219], v[176:179], v[116:119]
	v_mfma_f32_16x16x32_bf16 v[104:107], v[208:211], v[184:187], v[104:107]
	v_mfma_f32_16x16x32_bf16 v[100:103], v[216:219], v[184:187], v[100:103]
	v_mfma_f32_16x16x32_bf16 v[88:91], v[208:211], v[192:195], v[88:91]
	v_mfma_f32_16x16x32_bf16 v[84:87], v[216:219], v[192:195], v[84:87]
	v_mfma_f32_16x16x32_bf16 v[72:75], v[208:211], v[200:203], v[72:75]
	v_mfma_f32_16x16x32_bf16 v[68:71], v[216:219], v[200:203], v[68:71]
	s_waitcnt vmcnt(4) lgkmcnt(0)
	s_barrier
; #define LAS __attribute__((address_space(3)))
; __device__ __forceinline__ void rstd_table(const float* ssq, LAS unsigned char* lds, const Unit& u, int tid, int par) {
;     if (tid < 256) { const f32x4* p = (const f32x4*)(ssq + (size_t)(u.pm * 256 + tid) * 32); f32x4 a = p[0];
; #pragma unroll
;         for (int i = 1; i < 8; ++i) a += p[i];
;         ((LAS float*)(lds + 131072 + par * 1024))[tid] = 1.0f / sqrtf(((a[0] + a[1]) + (a[2] + a[3])) * (1.0f / DM) + 1e-6f); }
	ds_read_b128 v[156:159], v174 offset:49152
	ds_read_b128 v[180:183], v174 offset:51200
	ds_read_b128 v[188:191], v174 offset:53248
	s_add_u32 s64, s64, 0x80000
	s_addc_u32 s65, s65, 0
	s_mov_b32 m0, s41
	s_nop 0
	global_load_lds_dwordx4 v163, s[64:65]
	s_mov_b32 m0, s42
	s_nop 0
	global_load_lds_dwordx4 v171, s[64:65]
	s_waitcnt lgkmcnt(2)
	v_mfma_f32_16x16x32_bf16 v[64:67], v[136:139], v[156:159], v[64:67]
	v_mfma_f32_16x16x32_bf16 v[60:63], v[146:149], v[156:159], v[60:63]
	ds_read_b128 v[196:199], v174 offset:55296
	s_waitcnt lgkmcnt(2)
	v_mfma_f32_16x16x32_bf16 v[48:51], v[136:139], v[180:183], v[48:51]
	v_mfma_f32_16x16x32_bf16 v[44:47], v[146:149], v[180:183], v[44:47]
	ds_read_b128 v[176:179], v174 offset:50176
	s_waitcnt lgkmcnt(2)
	v_mfma_f32_16x16x32_bf16 v[32:35], v[136:139], v[188:191], v[32:35]
	v_mfma_f32_16x16x32_bf16 v[28:31], v[146:149], v[188:191], v[28:31]
	ds_read_b128 v[184:187], v174 offset:52224
	s_waitcnt lgkmcnt(2)
	v_mfma_f32_16x16x32_bf16 v[16:19], v[136:139], v[196:199], v[16:19]
	v_mfma_f32_16x16x32_bf16 v[12:15], v[146:149], v[196:199], v[12:15]
	ds_read_b128 v[192:195], v174 offset:54272
	s_waitcnt lgkmcnt(2)
	v_mfma_f32_16x16x32_bf16 v[64:67], v[142:145], v[176:179], v[64:67]
	v_mfma_f32_16x16x32_bf16 v[60:63], v[152:155], v[176:179], v[60:63]
	ds_read_b128 v[200:203], v174 offset:56320
	s_waitcnt lgkmcnt(2)
	v_mfma_f32_16x16x32_bf16 v[48:51], v[142:145], v[184:187], v[48:51]
	v_mfma_f32_16x16x32_bf16 v[44:47], v[152:155], v[184:187], v[44:47]
	s_waitcnt lgkmcnt(1)
	v_mfma_f32_16x16x32_bf16 v[32:35], v[142:145], v[192:195], v[32:35]
	v_mfma_f32_16x16x32_bf16 v[28:31], v[152:155], v[192:195], v[28:31]
	s_waitcnt lgkmcnt(0)
	v_mfma_f32_16x16x32_bf16 v[16:19], v[142:145], v[200:203], v[16:19]
	v_mfma_f32_16x16x32_bf16 v[12:15], v[152:155], v[200:203], v[12:15]
	s_add_u32 s28, s28, 0x80000
	s_addc_u32 s29, s29, 0
	s_mov_b32 m0, s43
	s_nop 0
	global_load_lds_dwordx4 v162, s[28:29]
	s_mov_b32 m0, s44
	s_nop 0
	global_load_lds_dwordx4 v170, s[28:29]
	v_mfma_f32_16x16x32_bf16 v[56:59], v[204:207], v[156:159], v[56:59]
	s_add_i32 s61, s61, 2
	s_add_u32 s26, s26, 0xffffff00
	s_addc_u32 s27, s27, -1
	v_mfma_f32_16x16x32_bf16 v[52:55], v[212:215], v[156:159], v[52:55]
	s_add_u32 s24, s24, 0x100
	s_addc_u32 s25, s25, 0
	s_add_u32 s10, s10, 0x100
	v_mfma_f32_16x16x32_bf16 v[40:43], v[204:207], v[180:183], v[40:43]
	s_addc_u32 s11, s11, 0
	s_cmp_lt_u32 s61, 30
	v_mfma_f32_16x16x32_bf16 v[36:39], v[212:215], v[180:183], v[36:39]
	v_mfma_f32_16x16x32_bf16 v[24:27], v[204:207], v[188:191], v[24:27]
	v_mfma_f32_16x16x32_bf16 v[20:23], v[212:215], v[188:191], v[20:23]
	v_mfma_f32_16x16x32_bf16 v[8:11], v[204:207], v[196:199], v[8:11]
	v_mfma_f32_16x16x32_bf16 v[4:7], v[212:215], v[196:199], v[4:7]
	s_cbranch_scc1 .Lrt_275
	v_mfma_f32_16x16x32_bf16 v[56:59], v[208:211], v[176:179], v[56:59]
	v_mfma_f32_16x16x32_bf16 v[52:55], v[216:219], v[176:179], v[52:55]
	v_mfma_f32_16x16x32_bf16 v[40:43], v[208:211], v[184:187], v[40:43]
	v_mfma_f32_16x16x32_bf16 v[36:39], v[216:219], v[184:187], v[36:39]
	v_mfma_f32_16x16x32_bf16 v[24:27], v[208:211], v[192:195], v[24:27]
	v_mfma_f32_16x16x32_bf16 v[20:23], v[216:219], v[192:195], v[20:23]
	v_mfma_f32_16x16x32_bf16 v[8:11], v[208:211], v[200:203], v[8:11]
	v_mfma_f32_16x16x32_bf16 v[4:7], v[216:219], v[200:203], v[4:7]
	s_nor_b64 s[10:11], s[6:7], s[8:9]
	s_and_saveexec_b64 s[24:25], s[10:11]
	s_cbranch_execz .LBB0_278
	v_lshl_add_u32 v132, s14, 8, v140
	v_ashrrev_i32_e32 v133, 31, v132
	v_readlane_b32 s10, v255, 2
	v_lshlrev_b64 v[132:133], 7, v[132:133]
	v_readlane_b32 s11, v255, 3
	s_nop 1
	v_lshl_add_u64 v[152:153], s[10:11], 0, v[132:133]
	global_load_dwordx4 v[132:135], v[152:153], off offset:48
	global_load_dwordx4 v[136:139], v[152:153], off offset:32
	global_load_dwordx4 v[142:145], v[152:153], off
	global_load_dwordx4 v[146:149], v[152:153], off offset:16
	s_waitcnt vmcnt(0)
	v_pk_add_f32 v[144:145], v[144:145], v[148:149]
	v_pk_add_f32 v[142:143], v[142:143], v[146:147]
	v_pk_add_f32 v[138:139], v[144:145], v[138:139]
	v_pk_add_f32 v[136:137], v[142:143], v[136:137]
	v_pk_add_f32 v[154:155], v[138:139], v[134:135]
	v_pk_add_f32 v[156:157], v[136:137], v[132:133]
	global_load_dwordx4 v[132:135], v[152:153], off offset:112
	global_load_dwordx4 v[136:139], v[152:153], off offset:96
	global_load_dwordx4 v[142:145], v[152:153], off offset:80
	global_load_dwordx4 v[146:149], v[152:153], off offset:64
	s_waitcnt vmcnt(0)
	v_pk_add_f32 v[148:149], v[154:155], v[148:149]
	v_pk_add_f32 v[146:147], v[156:157], v[146:147]
	v_pk_add_f32 v[144:145], v[148:149], v[144:145]
	v_pk_add_f32 v[142:143], v[146:147], v[142:143]
	v_pk_add_f32 v[138:139], v[144:145], v[138:139]
	v_pk_add_f32 v[136:137], v[142:143], v[136:137]
	v_pk_add_f32 v[134:135], v[138:139], v[134:135]
	v_pk_add_f32 v[132:133], v[136:137], v[132:133]
	s_nop 0
	v_pk_mov_b32 v[136:137], v[132:133], v[134:135] op_sel:[1,0]
	v_mov_b32_e32 v133, v135
	v_pk_add_f32 v[132:133], v[136:137], v[132:133]
	s_nop 0
	v_add_f32_e32 v132, v132, v133
	v_fmamk_f32 v132, v132, 0x3a000000, v164
	v_cmp_gt_f32_e32 vcc, s69, v132
	v_mul_f32_e32 v133, 0x4f800000, v132
	s_nop 0
	v_cndmask_b32_e32 v132, v132, v133, vcc
	v_sqrt_f32_e32 v133, v132
	s_nop 0
	v_add_u32_e32 v134, -1, v133
	v_fma_f32 v135, -v134, v133, v132
	v_cmp_ge_f32_e64 s[10:11], 0, v135
	v_add_u32_e32 v135, 1, v133
	s_nop 0
	v_cndmask_b32_e64 v134, v133, v134, s[10:11]
	v_fma_f32 v133, -v135, v133, v132
	v_cmp_lt_f32_e64 s[10:11], 0, v133
	s_nop 1
	v_cndmask_b32_e64 v133, v134, v135, s[10:11]
	v_mul_f32_e32 v134, 0x37800000, v133
	v_cndmask_b32_e32 v133, v133, v134, vcc
	v_cmp_class_f32_e32 vcc, v132, v165
	s_nop 1
	v_cndmask_b32_e32 v132, v133, v132, vcc
	v_div_scale_f32 v133, s[10:11], v132, v132, 1.0
	v_rcp_f32_e32 v134, v133
	s_lshl_b32 s10, s59, 10
	s_and_b32 s10, s10, 0x400
	v_fma_f32 v135, -v133, v134, 1.0
	v_fmac_f32_e32 v134, v135, v134
	v_div_scale_f32 v135, vcc, 1.0, v132, 1.0
	v_mul_f32_e32 v136, v135, v134
	v_fma_f32 v137, -v133, v136, v135
	v_fmac_f32_e32 v136, v137, v134
	v_fma_f32 v133, -v133, v136, v135
	v_div_fmas_f32 v133, v133, v134, v136
	v_div_fixup_f32 v132, v133, v132, 1.0
	v_add_u32_e32 v133, s10, v172
	ds_write_b32 v133, v132

; template <class Epi, class Sched>
; __device__ __forceinline__ void gemm_simple(PG8_LAS unsigned char* lds, const Gemm g, const Sched& S, const Epi& E, int wave_s) {
;     ...
;         const char* nA = has_next ? (const char*)g.A + (size_t)nxt.pm * tstep : cA; const char* nB = has_next ? (const char*)g.Bt + (size_t)nxt.pn * tstep : cB;
;         int t = 0;
;         if (ui > 0) {
;             if constexpr (Epi::NST >= 16) PG8_TILE_W(0, cA + kstep, cB + kstep, "18", "20"); else PG8_TILE_W(0, cA + kstep, cB + kstep, "10", "12");
;             PG8_TILE_W(1, cA + 2 * kstep, cB + 2 * kstep, "2", "4");
;             t = 2;
;         }
;         for (; t < nt; t += 2) {
;             const bool last = (t == nt - 2);
;             PG8_TILE(0, cA + (size_t)(t + 1) * kstep, cB + (size_t)(t + 1) * kstep, true);
;             const char* a2 = last ? nA : cA + (size_t)(t + 2) * kstep; const char* b2 = last ? nB : cB + (size_t)(t + 2) * kstep;
;             PG8_TILE(1, a2, b2, (!last || has_next));
.LBB0_306:
	s_ashr_i32 s13, s12, 31
	s_lshl_b64 s[14:15], s[12:13], 20
	s_add_u32 s14, s94, s14
	s_addc_u32 s15, s95, s15
	s_and_b64 s[16:17], exec, s[8:9]
	s_cselect_b32 s13, s21, s15
	s_cselect_b32 s56, s20, s14
	s_ashr_i32 s5, s4, 31
	s_lshl_b64 s[16:17], s[4:5], 20
	s_add_u32 s16, s68, s16
	s_addc_u32 s17, s70, s17
	s_and_b64 s[24:25], exec, s[8:9]
	s_cselect_b32 s5, s11, s17
	s_cselect_b32 s57, s10, s16
	s_add_i32 s58, s22, -2
	s_lshl_b32 s59, s22, 7
	s_mov_b64 s[22:23], 0xf00
	s_branch .Lrt_top_307
.Lrt_307:
	v_mfma_f32_16x16x32_bf16 v[64:67], v[214:217], v[182:185], v[64:67]
	v_mfma_f32_16x16x32_bf16 v[60:63], v[222:225], v[182:185], v[60:63]
	v_mfma_f32_16x16x32_bf16 v[48:51], v[214:217], v[190:193], v[48:51]
	v_mfma_f32_16x16x32_bf16 v[44:47], v[222:225], v[190:193], v[44:47]
	v_mfma_f32_16x16x32_bf16 v[32:35], v[214:217], v[198:201], v[32:35]
	v_mfma_f32_16x16x32_bf16 v[28:31], v[222:225], v[198:201], v[28:31]
	v_mfma_f32_16x16x32_bf16 v[12:15], v[214:217], v[206:209], v[12:15]
	v_mfma_f32_16x16x32_bf16 v[16:19], v[222:225], v[206:209], v[16:19]
.Lrt_top_307:
.LBB0_307:
	s_waitcnt vmcnt(2) lgkmcnt(0)
	s_barrier
	ds_read_b128 v[136:139], v132
	ds_read_b128 v[178:181], v177
	ds_read_b128 v[156:159], v132 offset:2048
	ds_read_b128 v[186:189], v177 offset:2048
	ds_read_b128 v[194:197], v177 offset:4096
	s_add_u32 s60, s10, s59
	s_addc_u32 s61, s11, 0
	s_add_u32 s24, s60, 0x80
	s_addc_u32 s25, s61, 0
	s_mov_b32 m0, s43
	s_nop 0
	global_load_lds_dwordx4 v172, s[24:25]
	s_mov_b32 m0, s49
	s_nop 0
	global_load_lds_dwordx4 v174, s[24:25]
	s_waitcnt lgkmcnt(3)
	v_mfma_f32_16x16x32_bf16 v[120:123], v[136:139], v[178:181], v[120:123]
	s_waitcnt lgkmcnt(2)
	v_mfma_f32_16x16x32_bf16 v[116:119], v[156:159], v[178:181], v[116:119]
	ds_read_b128 v[202:205], v177 offset:6144
	s_waitcnt lgkmcnt(2)
	v_mfma_f32_16x16x32_bf16 v[104:107], v[136:139], v[186:189], v[104:107]
	v_mfma_f32_16x16x32_bf16 v[100:103], v[156:159], v[186:189], v[100:103]
	ds_read_b128 v[152:155], v132 offset:1024
	ds_read_b128 v[182:185], v177 offset:1024
	s_waitcnt lgkmcnt(3)
	v_mfma_f32_16x16x32_bf16 v[88:91], v[136:139], v[194:197], v[88:91]
	ds_read_b128 v[160:163], v132 offset:3072
	v_mfma_f32_16x16x32_bf16 v[84:87], v[156:159], v[194:197], v[84:87]
	ds_read_b128 v[190:193], v177 offset:3072
	s_waitcnt lgkmcnt(4)
	v_mfma_f32_16x16x32_bf16 v[72:75], v[136:139], v[202:205], v[72:75]
	v_mfma_f32_16x16x32_bf16 v[68:71], v[156:159], v[202:205], v[68:71]
	ds_read_b128 v[198:201], v177 offset:5120
	s_waitcnt lgkmcnt(3)
	v_mfma_f32_16x16x32_bf16 v[120:123], v[152:155], v[182:185], v[120:123]
	s_waitcnt lgkmcnt(2)
	v_mfma_f32_16x16x32_bf16 v[116:119], v[160:163], v[182:185], v[116:119]
	ds_read_b128 v[206:209], v177 offset:7168
	s_waitcnt lgkmcnt(2)
	v_mfma_f32_16x16x32_bf16 v[104:107], v[152:155], v[190:193], v[104:107]
	v_mfma_f32_16x16x32_bf16 v[100:103], v[160:163], v[190:193], v[100:103]
	ds_read_b128 v[210:213], v133
	s_waitcnt lgkmcnt(2)
	v_mfma_f32_16x16x32_bf16 v[88:91], v[152:155], v[198:201], v[88:91]
	ds_read_b128 v[218:221], v133 offset:2048
	v_mfma_f32_16x16x32_bf16 v[84:87], v[160:163], v[198:201], v[84:87]
	s_waitcnt lgkmcnt(2)
	v_mfma_f32_16x16x32_bf16 v[72:75], v[152:155], v[206:209], v[72:75]
	v_mfma_f32_16x16x32_bf16 v[68:71], v[160:163], v[206:209], v[68:71]
	s_add_u32 s62, s20, s59
	s_addc_u32 s63, s21, 0
	s_add_u32 s24, s62, 0x80
	s_addc_u32 s25, s63, 0
	s_mov_b32 m0, s44
	s_nop 0
	global_load_lds_dwordx4 v171, s[24:25]
	s_mov_b32 m0, s50
	s_nop 0
	global_load_lds_dwordx4 v173, s[24:25]
	s_waitcnt lgkmcnt(1)
	v_mfma_f32_16x16x32_bf16 v[128:131], v[210:213], v[178:181], v[128:131]
	s_waitcnt lgkmcnt(0)
	v_mfma_f32_16x16x32_bf16 v[124:127], v[218:221], v[178:181], v[124:127]
	v_mfma_f32_16x16x32_bf16 v[112:115], v[210:213], v[186:189], v[112:115]
	v_mfma_f32_16x16x32_bf16 v[108:111], v[218:221], v[186:189], v[108:111]
	ds_read_b128 v[214:217], v133 offset:1024
	v_mfma_f32_16x16x32_bf16 v[96:99], v[210:213], v[194:197], v[96:99]
	ds_read_b128 v[222:225], v133 offset:3072
	v_mfma_f32_16x16x32_bf16 v[92:95], v[218:221], v[194:197], v[92:95]
	v_mfma_f32_16x16x32_bf16 v[80:83], v[210:213], v[202:205], v[80:83]
	v_mfma_f32_16x16x32_bf16 v[76:79], v[218:221], v[202:205], v[76:79]
	s_waitcnt lgkmcnt(1)
	v_mfma_f32_16x16x32_bf16 v[128:131], v[214:217], v[182:185], v[128:131]
	s_waitcnt lgkmcnt(0)
	v_mfma_f32_16x16x32_bf16 v[124:127], v[222:225], v[182:185], v[124:127]
	v_mfma_f32_16x16x32_bf16 v[112:115], v[214:217], v[190:193], v[112:115]
	v_mfma_f32_16x16x32_bf16 v[108:111], v[222:225], v[190:193], v[108:111]
	v_mfma_f32_16x16x32_bf16 v[96:99], v[214:217], v[198:201], v[96:99]
	v_mfma_f32_16x16x32_bf16 v[92:95], v[222:225], v[198:201], v[92:95]
	v_mfma_f32_16x16x32_bf16 v[80:83], v[214:217], v[206:209], v[80:83]
	v_mfma_f32_16x16x32_bf16 v[76:79], v[222:225], v[206:209], v[76:79]
	s_waitcnt vmcnt(4) lgkmcnt(0)
	s_barrier
; template <class Epi, class Sched>
; __device__ __forceinline__ void gemm_simple(PG8_LAS unsigned char* lds, const Gemm g, const Sched& S, const Epi& E, int wave_s) {
;     ...
;             PG8_TILE(0, cA + (size_t)(t + 1) * kstep, cB + (size_t)(t + 1) * kstep, true);
;             const char* a2 = last ? nA : cA + (size_t)(t + 2) * kstep; const char* b2 = last ? nB : cB + (size_t)(t + 2) * kstep;
;             PG8_TILE(1, a2, b2, (!last || has_next));
	ds_read_b128 v[178:181], v177 offset:16384
	ds_read_b128 v[186:189], v177 offset:18432
	ds_read_b128 v[194:197], v177 offset:20480
	s_add_u32 s24, s60, 0x80080
	s_addc_u32 s25, s61, 0
	s_mov_b32 m0, s45
	s_nop 0
	global_load_lds_dwordx4 v172, s[24:25]
	s_mov_b32 m0, s51
	s_nop 0
	global_load_lds_dwordx4 v174, s[24:25]
	s_waitcnt lgkmcnt(2)
	v_mfma_f32_16x16x32_bf16 v[56:59], v[136:139], v[178:181], v[56:59]
	v_mfma_f32_16x16x32_bf16 v[52:55], v[156:159], v[178:181], v[52:55]
	ds_read_b128 v[202:205], v177 offset:22528
	s_waitcnt lgkmcnt(2)
	v_mfma_f32_16x16x32_bf16 v[40:43], v[136:139], v[186:189], v[40:43]
	v_mfma_f32_16x16x32_bf16 v[36:39], v[156:159], v[186:189], v[36:39]
	ds_read_b128 v[182:185], v177 offset:17408
	s_waitcnt lgkmcnt(2)
	v_mfma_f32_16x16x32_bf16 v[24:27], v[136:139], v[194:197], v[24:27]
	v_mfma_f32_16x16x32_bf16 v[20:23], v[156:159], v[194:197], v[20:23]
	ds_read_b128 v[190:193], v177 offset:19456
	s_waitcnt lgkmcnt(2)
	v_mfma_f32_16x16x32_bf16 v[8:11], v[136:139], v[202:205], v[8:11]
	v_mfma_f32_16x16x32_bf16 v[4:7], v[156:159], v[202:205], v[4:7]
	ds_read_b128 v[198:201], v177 offset:21504
	s_waitcnt lgkmcnt(2)
	v_mfma_f32_16x16x32_bf16 v[56:59], v[152:155], v[182:185], v[56:59]
	v_mfma_f32_16x16x32_bf16 v[52:55], v[160:163], v[182:185], v[52:55]
	ds_read_b128 v[206:209], v177 offset:23552
	s_waitcnt lgkmcnt(2)
	v_mfma_f32_16x16x32_bf16 v[40:43], v[152:155], v[190:193], v[40:43]
	v_mfma_f32_16x16x32_bf16 v[36:39], v[160:163], v[190:193], v[36:39]
	s_waitcnt lgkmcnt(1)
	v_mfma_f32_16x16x32_bf16 v[24:27], v[152:155], v[198:201], v[24:27]
	v_mfma_f32_16x16x32_bf16 v[20:23], v[160:163], v[198:201], v[20:23]
	s_waitcnt lgkmcnt(0)
	v_mfma_f32_16x16x32_bf16 v[8:11], v[152:155], v[206:209], v[8:11]
	v_mfma_f32_16x16x32_bf16 v[4:7], v[160:163], v[206:209], v[4:7]
	s_add_u32 s24, s62, 0x80080
	s_addc_u32 s25, s63, 0
	s_mov_b32 m0, s46
	s_nop 0
	global_load_lds_dwordx4 v171, s[24:25]
	s_mov_b32 m0, s52
	s_nop 0
	global_load_lds_dwordx4 v173, s[24:25]
	v_mfma_f32_16x16x32_bf16 v[64:67], v[210:213], v[178:181], v[64:67]
	s_add_u32 s24, s62, 0x100
	s_addc_u32 s25, s63, 0
	s_add_u32 s60, s60, 0x100
	v_mfma_f32_16x16x32_bf16 v[60:63], v[218:221], v[178:181], v[60:63]
	s_addc_u32 s61, s61, 0
	v_mfma_f32_16x16x32_bf16 v[48:51], v[210:213], v[186:189], v[48:51]
	v_mfma_f32_16x16x32_bf16 v[44:47], v[218:221], v[186:189], v[44:47]
	v_mfma_f32_16x16x32_bf16 v[32:35], v[210:213], v[194:197], v[32:35]
	v_mfma_f32_16x16x32_bf16 v[28:31], v[218:221], v[194:197], v[28:31]
	v_mfma_f32_16x16x32_bf16 v[12:15], v[210:213], v[202:205], v[12:15]
	v_mfma_f32_16x16x32_bf16 v[16:19], v[218:221], v[202:205], v[16:19]
	v_mfma_f32_16x16x32_bf16 v[64:67], v[214:217], v[182:185], v[64:67]
	v_mfma_f32_16x16x32_bf16 v[60:63], v[222:225], v[182:185], v[60:63]
	v_mfma_f32_16x16x32_bf16 v[48:51], v[214:217], v[190:193], v[48:51]
	v_mfma_f32_16x16x32_bf16 v[44:47], v[222:225], v[190:193], v[44:47]
	v_mfma_f32_16x16x32_bf16 v[32:35], v[214:217], v[198:201], v[32:35]
	v_mfma_f32_16x16x32_bf16 v[28:31], v[222:225], v[198:201], v[28:31]
	v_mfma_f32_16x16x32_bf16 v[12:15], v[214:217], v[206:209], v[12:15]
	v_mfma_f32_16x16x32_bf16 v[16:19], v[222:225], v[206:209], v[16:19]
	s_waitcnt vmcnt(2) lgkmcnt(0)
	s_barrier
	ds_read_b128 v[136:139], v134
	ds_read_b128 v[178:181], v177 offset:32768
	ds_read_b128 v[156:159], v134 offset:2048
	ds_read_b128 v[186:189], v177 offset:34816
	ds_read_b128 v[194:197], v177 offset:36864
	s_cmp_eq_u32 s59, s22
	s_cselect_b32 s25, s13, s25
	s_cselect_b32 s24, s56, s24
	s_cselect_b32 s61, s5, s61
	s_cselect_b32 s60, s57, s60
	s_mov_b32 m0, s27
	s_nop 0
	global_load_lds_dwordx4 v172, s[60:61]
	s_mov_b32 m0, s28
	s_nop 0
	global_load_lds_dwordx4 v174, s[60:61]
	s_waitcnt lgkmcnt(3)
	v_mfma_f32_16x16x32_bf16 v[120:123], v[136:139], v[178:181], v[120:123]
	s_waitcnt lgkmcnt(2)
	v_mfma_f32_16x16x32_bf16 v[116:119], v[156:159], v[178:181], v[116:119]
	ds_read_b128 v[202:205], v177 offset:38912
	s_waitcnt lgkmcnt(2)
	v_mfma_f32_16x16x32_bf16 v[104:107], v[136:139], v[186:189], v[104:107]
	v_mfma_f32_16x16x32_bf16 v[100:103], v[156:159], v[186:189], v[100:103]
	ds_read_b128 v[152:155], v134 offset:1024
	ds_read_b128 v[182:185], v177 offset:33792
	s_waitcnt lgkmcnt(3)
	v_mfma_f32_16x16x32_bf16 v[88:91], v[136:139], v[194:197], v[88:91]
	ds_read_b128 v[160:163], v134 offset:3072
	v_mfma_f32_16x16x32_bf16 v[84:87], v[156:159], v[194:197], v[84:87]
	ds_read_b128 v[190:193], v177 offset:35840
	s_waitcnt lgkmcnt(4)
	v_mfma_f32_16x16x32_bf16 v[72:75], v[136:139], v[202:205], v[72:75]
	v_mfma_f32_16x16x32_bf16 v[68:71], v[156:159], v[202:205], v[68:71]
	ds_read_b128 v[198:201], v177 offset:37888
	s_waitcnt lgkmcnt(3)
	v_mfma_f32_16x16x32_bf16 v[120:123], v[152:155], v[182:185], v[120:123]
	s_waitcnt lgkmcnt(2)
	v_mfma_f32_16x16x32_bf16 v[116:119], v[160:163], v[182:185], v[116:119]
	ds_read_b128 v[206:209], v177 offset:39936
	s_waitcnt lgkmcnt(2)
	v_mfma_f32_16x16x32_bf16 v[104:107], v[152:155], v[190:193], v[104:107]
	v_mfma_f32_16x16x32_bf16 v[100:103], v[160:163], v[190:193], v[100:103]
	ds_read_b128 v[210:213], v135
	s_waitcnt lgkmcnt(2)
	v_mfma_f32_16x16x32_bf16 v[88:91], v[152:155], v[198:201], v[88:91]
	ds_read_b128 v[218:221], v135 offset:2048
	v_mfma_f32_16x16x32_bf16 v[84:87], v[160:163], v[198:201], v[84:87]
	s_waitcnt lgkmcnt(2)
	v_mfma_f32_16x16x32_bf16 v[72:75], v[152:155], v[206:209], v[72:75]
	v_mfma_f32_16x16x32_bf16 v[68:71], v[160:163], v[206:209], v[68:71]
	s_mov_b32 m0, s19
	s_nop 0
	global_load_lds_dwordx4 v171, s[24:25]
	s_mov_b32 m0, s29
	s_nop 0
	global_load_lds_dwordx4 v173, s[24:25]
	s_waitcnt lgkmcnt(1)
	v_mfma_f32_16x16x32_bf16 v[128:131], v[210:213], v[178:181], v[128:131]
	s_waitcnt lgkmcnt(0)
	v_mfma_f32_16x16x32_bf16 v[124:127], v[218:221], v[178:181], v[124:127]
	v_mfma_f32_16x16x32_bf16 v[112:115], v[210:213], v[186:189], v[112:115]
	v_mfma_f32_16x16x32_bf16 v[108:111], v[218:221], v[186:189], v[108:111]
	ds_read_b128 v[214:217], v135 offset:1024
	v_mfma_f32_16x16x32_bf16 v[96:99], v[210:213], v[194:197], v[96:99]
	ds_read_b128 v[222:225], v135 offset:3072
	v_mfma_f32_16x16x32_bf16 v[92:95], v[218:221], v[194:197], v[92:95]
	v_mfma_f32_16x16x32_bf16 v[80:83], v[210:213], v[202:205], v[80:83]
	v_mfma_f32_16x16x32_bf16 v[76:79], v[218:221], v[202:205], v[76:79]
	s_waitcnt lgkmcnt(1)
	v_mfma_f32_16x16x32_bf16 v[128:131], v[214:217], v[182:185], v[128:131]
	s_waitcnt lgkmcnt(0)
	v_mfma_f32_16x16x32_bf16 v[124:127], v[222:225], v[182:185], v[124:127]
	v_mfma_f32_16x16x32_bf16 v[112:115], v[214:217], v[190:193], v[112:115]
	v_mfma_f32_16x16x32_bf16 v[108:111], v[222:225], v[190:193], v[108:111]
	v_mfma_f32_16x16x32_bf16 v[96:99], v[214:217], v[198:201], v[96:99]
	v_mfma_f32_16x16x32_bf16 v[92:95], v[222:225], v[198:201], v[92:95]
	v_mfma_f32_16x16x32_bf16 v[80:83], v[214:217], v[206:209], v[80:83]
	v_mfma_f32_16x16x32_bf16 v[76:79], v[222:225], v[206:209], v[76:79]
	s_waitcnt vmcnt(4) lgkmcnt(0)
	s_barrier
; #define LAS __attribute__((address_space(3)))
; __device__ __forceinline__ void rstd_table(const float* ssq, LAS unsigned char* lds, const Unit& u, int tid, int par) {
;     if (tid < 256) { const f32x4* p = (const f32x4*)(ssq + (size_t)(u.pm * 256 + tid) * 32); f32x4 a = p[0];
; #pragma unroll
;         for (int i = 1; i < 8; ++i) a += p[i];
;         ((LAS float*)(lds + 131072 + par * 1024))[tid] = 1.0f / sqrtf(((a[0] + a[1]) + (a[2] + a[3])) * (1.0f / DM) + 1e-6f); }
	ds_read_b128 v[178:181], v177 offset:49152
	ds_read_b128 v[186:189], v177 offset:51200
	ds_read_b128 v[194:197], v177 offset:53248
	s_add_u32 s60, s60, 0x80000
	s_addc_u32 s61, s61, 0
	s_mov_b32 m0, s36
	s_nop 0
	global_load_lds_dwordx4 v172, s[60:61]
	s_mov_b32 m0, s37
	s_nop 0
	global_load_lds_dwordx4 v174, s[60:61]
	s_waitcnt lgkmcnt(2)
	v_mfma_f32_16x16x32_bf16 v[56:59], v[136:139], v[178:181], v[56:59]
	v_mfma_f32_16x16x32_bf16 v[52:55], v[156:159], v[178:181], v[52:55]
	ds_read_b128 v[202:205], v177 offset:55296
	s_waitcnt lgkmcnt(2)
	v_mfma_f32_16x16x32_bf16 v[40:43], v[136:139], v[186:189], v[40:43]
	v_mfma_f32_16x16x32_bf16 v[36:39], v[156:159], v[186:189], v[36:39]
	ds_read_b128 v[182:185], v177 offset:50176
	s_waitcnt lgkmcnt(2)
	v_mfma_f32_16x16x32_bf16 v[24:27], v[136:139], v[194:197], v[24:27]
	v_mfma_f32_16x16x32_bf16 v[20:23], v[156:159], v[194:197], v[20:23]
	ds_read_b128 v[190:193], v177 offset:52224
	s_waitcnt lgkmcnt(2)
	v_mfma_f32_16x16x32_bf16 v[8:11], v[136:139], v[202:205], v[8:11]
	v_mfma_f32_16x16x32_bf16 v[4:7], v[156:159], v[202:205], v[4:7]
	ds_read_b128 v[198:201], v177 offset:54272
	s_waitcnt lgkmcnt(2)
	v_mfma_f32_16x16x32_bf16 v[56:59], v[152:155], v[182:185], v[56:59]
	v_mfma_f32_16x16x32_bf16 v[52:55], v[160:163], v[182:185], v[52:55]
	ds_read_b128 v[206:209], v177 offset:56320
	s_waitcnt lgkmcnt(2)
	v_mfma_f32_16x16x32_bf16 v[40:43], v[152:155], v[190:193], v[40:43]
	v_mfma_f32_16x16x32_bf16 v[36:39], v[160:163], v[190:193], v[36:39]
	s_waitcnt lgkmcnt(1)
	v_mfma_f32_16x16x32_bf16 v[24:27], v[152:155], v[198:201], v[24:27]
	v_mfma_f32_16x16x32_bf16 v[20:23], v[160:163], v[198:201], v[20:23]
	s_waitcnt lgkmcnt(0)
	v_mfma_f32_16x16x32_bf16 v[8:11], v[152:155], v[206:209], v[8:11]
	v_mfma_f32_16x16x32_bf16 v[4:7], v[160:163], v[206:209], v[4:7]
	s_add_u32 s24, s24, 0x80000
	s_addc_u32 s25, s25, 0
	s_mov_b32 m0, s38
	s_nop 0
	global_load_lds_dwordx4 v171, s[24:25]
	s_mov_b32 m0, s39
	s_nop 0
	global_load_lds_dwordx4 v173, s[24:25]
	v_mfma_f32_16x16x32_bf16 v[64:67], v[210:213], v[178:181], v[64:67]
	s_add_i32 s58, s58, 2
	s_add_u32 s22, s22, 0xffffff00
	s_addc_u32 s23, s23, -1
	v_mfma_f32_16x16x32_bf16 v[60:63], v[218:221], v[178:181], v[60:63]
	s_add_u32 s20, s20, 0x100
	s_addc_u32 s21, s21, 0
	s_add_u32 s10, s10, 0x100
	v_mfma_f32_16x16x32_bf16 v[48:51], v[210:213], v[186:189], v[48:51]
	s_addc_u32 s11, s11, 0
	s_cmp_lt_u32 s58, 30
	v_mfma_f32_16x16x32_bf16 v[44:47], v[218:221], v[186:189], v[44:47]
	v_mfma_f32_16x16x32_bf16 v[32:35], v[210:213], v[194:197], v[32:35]
	v_mfma_f32_16x16x32_bf16 v[28:31], v[218:221], v[194:197], v[28:31]
	v_mfma_f32_16x16x32_bf16 v[12:15], v[210:213], v[202:205], v[12:15]
	v_mfma_f32_16x16x32_bf16 v[16:19], v[218:221], v[202:205], v[16:19]
	s_cbranch_scc1 .Lrt_307
	v_mfma_f32_16x16x32_bf16 v[64:67], v[214:217], v[182:185], v[64:67]
	v_mfma_f32_16x16x32_bf16 v[60:63], v[222:225], v[182:185], v[60:63]
	v_mfma_f32_16x16x32_bf16 v[48:51], v[214:217], v[190:193], v[48:51]
	v_mfma_f32_16x16x32_bf16 v[44:47], v[222:225], v[190:193], v[44:47]
	v_mfma_f32_16x16x32_bf16 v[32:35], v[214:217], v[198:201], v[32:35]
	v_mfma_f32_16x16x32_bf16 v[28:31], v[222:225], v[198:201], v[28:31]
	v_mfma_f32_16x16x32_bf16 v[12:15], v[214:217], v[206:209], v[12:15]
	v_mfma_f32_16x16x32_bf16 v[16:19], v[222:225], v[206:209], v[16:19]
	s_nor_b64 s[10:11], s[6:7], s[8:9]
	s_and_saveexec_b64 s[20:21], s[10:11]
	s_cbranch_execz .LBB0_310
	v_lshl_add_u32 v132, s12, 8, v170
	v_ashrrev_i32_e32 v133, 31, v132
	v_readlane_b32 s10, v255, 2
	v_lshlrev_b64 v[132:133], 7, v[132:133]
	v_readlane_b32 s11, v255, 3
	s_lshl_b32 s5, s54, 10
	s_and_b32 s5, s5, 0x400
	v_lshl_add_u64 v[142:143], s[10:11], 0, v[132:133]
	global_load_dwordx4 v[132:135], v[142:143], off offset:48
	global_load_dwordx4 v[136:139], v[142:143], off offset:32
	global_load_dwordx4 v[152:155], v[142:143], off
	global_load_dwordx4 v[156:159], v[142:143], off offset:16
	s_waitcnt vmcnt(0)
	v_pk_add_f32 v[144:145], v[154:155], v[158:159]
	v_pk_add_f32 v[146:147], v[152:153], v[156:157]
	v_pk_add_f32 v[138:139], v[144:145], v[138:139]
	v_pk_add_f32 v[136:137], v[146:147], v[136:137]
	v_pk_add_f32 v[144:145], v[138:139], v[134:135]
	v_pk_add_f32 v[146:147], v[136:137], v[132:133]
	global_load_dwordx4 v[132:135], v[142:143], off offset:112
	global_load_dwordx4 v[136:139], v[142:143], off offset:96
	global_load_dwordx4 v[152:155], v[142:143], off offset:80
	global_load_dwordx4 v[156:159], v[142:143], off offset:64
	s_waitcnt vmcnt(0)
	v_pk_add_f32 v[142:143], v[144:145], v[158:159]
	v_pk_add_f32 v[144:145], v[146:147], v[156:157]
	v_pk_add_f32 v[142:143], v[142:143], v[154:155]
	v_pk_add_f32 v[144:145], v[144:145], v[152:153]
	v_pk_add_f32 v[138:139], v[142:143], v[138:139]
	v_pk_add_f32 v[136:137], v[144:145], v[136:137]
	v_pk_add_f32 v[134:135], v[138:139], v[134:135]
	v_pk_add_f32 v[132:133], v[136:137], v[132:133]
	s_nop 0
	v_pk_mov_b32 v[136:137], v[132:133], v[134:135] op_sel:[1,0]
	v_mov_b32_e32 v133, v135
	v_pk_add_f32 v[132:133], v[136:137], v[132:133]
	s_nop 0
	v_add_f32_e32 v132, v132, v133
	v_fmamk_f32 v132, v132, 0x3a000000, v164
	v_cmp_gt_f32_e32 vcc, s69, v132
	v_mul_f32_e32 v133, 0x4f800000, v132
	s_nop 0
	v_cndmask_b32_e32 v132, v132, v133, vcc
	v_sqrt_f32_e32 v133, v132
	s_nop 0
	v_add_u32_e32 v134, -1, v133
	v_fma_f32 v135, -v134, v133, v132
	v_cmp_ge_f32_e64 s[10:11], 0, v135
	v_add_u32_e32 v135, 1, v133
	s_nop 0
	v_cndmask_b32_e64 v134, v133, v134, s[10:11]
	v_fma_f32 v133, -v135, v133, v132
	v_cmp_lt_f32_e64 s[10:11], 0, v133
	s_nop 1
	v_cndmask_b32_e64 v133, v134, v135, s[10:11]
	v_mul_f32_e32 v134, 0x37800000, v133
	v_cndmask_b32_e32 v133, v133, v134, vcc
	v_cmp_class_f32_e32 vcc, v132, v165
	s_nop 1
	v_cndmask_b32_e32 v132, v133, v132, vcc
	v_div_scale_f32 v133, s[10:11], v132, v132, 1.0
	v_rcp_f32_e32 v134, v133
	s_nop 0
	v_fma_f32 v135, -v133, v134, 1.0
	v_fmac_f32_e32 v134, v135, v134
	v_div_scale_f32 v135, vcc, 1.0, v132, 1.0
	v_mul_f32_e32 v136, v135, v134
	v_fma_f32 v137, -v133, v136, v135
	v_fmac_f32_e32 v136, v137, v134
	v_fma_f32 v133, -v133, v136, v135
	v_div_fmas_f32 v133, v133, v134, v136
	v_div_fixup_f32 v132, v133, v132, 1.0
	v_add_u32_e32 v133, s5, v175
	ds_write_b32 v133, v132
